# scan: per-chunk normalised state (decay folded into staged vectors, cw tables by idle wave 4), removes per-step decay multiply
# speedup vs baseline: 1.0082x; 1.0082x over previous
; __device__ __forceinline__ unsigned cvt_pk_bf16(float lo, float hi) { const f32x2 v = {lo, hi}; const bf16x2_t b = __builtin_convertvector(v, bf16x2_t); return __builtin_bit_cast(unsigned, b); }
; __device__ __forceinline__ float bf_lo(unsigned w) { return __uint_as_float(w << 16); }
; __device__ __forceinline__ float bf_hi(unsigned w) { return __uint_as_float(w & 0xffff0000u); }
; __device__ __forceinline__ int v_st(int k, int c) { const int kk = (k & ~0xC) | ((k & 4) << 1) | ((k & 8) >> 1); return ((kk >> 3) * 4 + (c >> 5)) * 512 + ((kk & 7) * 32 + (c & 31)) * 2; }
; __device__ __forceinline__ int v_rd_base(int lane) { return ((lane & 3) << 3) | (((lane >> 2) & 3) << 6) | (((lane >> 4) & 1) << 5) | (((lane >> 5) & 1) << 8); }
; __device__ __forceinline__ void attn_unit(const bf16_t* Q, const bf16_t* KV, const bf16_t* KR, bf16_t* O, int b, int h, int qb, char* lds, const int tid) {
;     ...
;     const int tq = qb * 256 + wid * 32 + r32;
;     const bf16_t* Qw = Q + ((size_t)b * SEQ + tq) * 3072 + h * 192 + hi * 8;
; #pragma unroll
;     for (int d0 = 0; d0 < 12; ++d0) qr[d0] = *reinterpret_cast<const bf16x8*>(Qw + d0 * 16);
; #pragma unroll
;     for (int ax = 0; ax < 2; ++ax) {
;         const float pos = (float)(ax ? (tq & 63) : (tq >> 6));
;         u32x4 w1 = __builtin_bit_cast(u32x4, qr[8 + 2 * ax]), w2 = __builtin_bit_cast(u32x4, qr[9 + 2 * ax]);
; #pragma unroll
;         for (int e2 = 0; e2 < 4; ++e2) {
;             float o1[2], o2[2];
; #pragma unroll
;             for (int hh = 0; hh < 2; ++hh) {
;                 const int i = hi * 8 + e2 * 2 + hh;
;                 const float ang = pos * exp2f(-(float)i * (13.287712379549449f / 16.0f));
;                 const float cs = __cosf(ang), sn = __sinf(ang);
;                 const float x1 = hh ? bf_hi(w1[e2]) : bf_lo(w1[e2]), x2 = hh ? bf_hi(w2[e2]) : bf_lo(w2[e2]);
;                 o1[hh] = x1 * cs - x2 * sn; o2[hh] = x2 * cs + x1 * sn;
;             }
;             w1[e2] = cvt_pk_bf16(o1[0], o1[1]); w2[e2] = cvt_pk_bf16(o2[0], o2[1]);
;         }
;         qr[8 + 2 * ax] = __builtin_bit_cast(bf16x8, w1); qr[9 + 2 * ax] = __builtin_bit_cast(bf16x8, w2);
;     }
;     const int sr = tid >> 4, sc = (tid & 15) * 8, vst0 = v_st(sr, sc), vst1 = v_st(32 + sr, sc);
;     const int krr = tid >> 3, krc = (tid & 7) * 8;
;     const int vb0 = (int)(uintptr_t)V_lds + v_rd_base(lane);
.LBB0_51:
	s_add_u32 s8, s42, 0x7300000
	s_addc_u32 s9, s43, 0
	s_add_u32 s10, s42, 0x13100000
	s_addc_u32 s11, s43, 0
	s_add_u32 s19, s42, 0x20b00000
	s_addc_u32 s20, s43, 0
	v_bfe_u32 v5, v166, 5, 1
	v_and_b32_e32 v0, 0x3fffffc0, v166
	s_add_i32 s0, 0, 0x18000
	v_lshl_add_u32 v167, v0, 2, s0
	v_ashrrev_i32_e32 v0, 1, v166
	v_lshlrev_b32_e32 v2, 3, v5
	v_and_b32_e32 v170, 0xffffffe0, v0
	v_or_b32_e32 v0, 6, v2
	v_cvt_f32_ubyte0_e32 v0, v0
	v_mul_f32_e32 v4, 0xbf549a78, v0
	s_mov_b32 s0, 0xc2fc0000
	v_cmp_gt_f32_e32 vcc, s0, v4
	v_mov_b32_e32 v6, 0x42800000
	v_not_b32_e32 v7, 63
	v_cndmask_b32_e32 v4, 0, v6, vcc
	v_fmac_f32_e32 v4, 0xbf549a78, v0
	v_exp_f32_e32 v0, v4
	v_cndmask_b32_e32 v4, 0, v7, vcc
	v_ashrrev_i32_e32 v172, 4, v166
	v_lshlrev_b32_e32 v8, 3, v166
	v_ldexp_f32 v169, v0, v4
	v_cvt_f32_ubyte0_e32 v0, v2
	v_mul_f32_e32 v4, 0xbf549a78, v0
	v_cmp_gt_f32_e32 vcc, s0, v4
	v_and_b32_e32 v9, 3, v172
	v_add_u32_e32 v11, 32, v172
	v_cndmask_b32_e32 v4, 0, v6, vcc
	v_fmac_f32_e32 v4, 0xbf549a78, v0
	v_exp_f32_e32 v0, v4
	v_cndmask_b32_e32 v4, 0, v7, vcc
	v_lshlrev_b32_e32 v12, 1, v11
	v_ashrrev_i32_e32 v173, 31, v172
	v_ldexp_f32 v188, v0, v4
	v_or_b32_e32 v0, 1, v2
	v_cvt_f32_ubyte0_e32 v0, v0
	v_mul_f32_e32 v4, 0xbf549a78, v0
	v_cmp_gt_f32_e32 vcc, s0, v4
	v_ashrrev_i32_e32 v174, 3, v166
	v_and_b32_e32 v168, 31, v166
	v_cndmask_b32_e32 v4, 0, v6, vcc
	v_fmac_f32_e32 v4, 0xbf549a78, v0
	v_exp_f32_e32 v0, v4
	v_cndmask_b32_e32 v4, 0, v7, vcc
	v_lshlrev_b32_e32 v219, 4, v5
	v_lshlrev_b32_e32 v220, 8, v168
	v_ldexp_f32 v189, v0, v4
	v_or_b32_e32 v0, 2, v2
	v_cvt_f32_ubyte0_e32 v0, v0
	v_mul_f32_e32 v4, 0xbf549a78, v0
	v_cmp_gt_f32_e32 vcc, s0, v4
	v_lshlrev_b32_e32 v13, 1, v166
	v_and_b32_e32 v3, 63, v166
	v_cndmask_b32_e32 v4, 0, v6, vcc
	v_fmac_f32_e32 v4, 0xbf549a78, v0
	v_exp_f32_e32 v0, v4
	v_cndmask_b32_e32 v4, 0, v7, vcc
	v_ashrrev_i32_e32 v175, 31, v174
	v_cmp_gt_u32_e64 s[6:7], 32, v3
	v_ldexp_f32 v190, v0, v4
	v_or_b32_e32 v0, 3, v2
	v_cvt_f32_ubyte0_e32 v0, v0
	v_mul_f32_e32 v4, 0xbf549a78, v0
	v_cmp_gt_f32_e32 vcc, s0, v4
	v_lshl_add_u32 v229, v168, 2, v167
	v_ashrrev_i32_e32 v171, 31, v170
	v_cndmask_b32_e32 v4, 0, v6, vcc
	v_fmac_f32_e32 v4, 0xbf549a78, v0
	v_exp_f32_e32 v0, v4
	v_cndmask_b32_e32 v4, 0, v7, vcc
	v_lshlrev_b32_e32 v180, 14, v5
	v_mov_b32_e32 v181, v1
	v_ldexp_f32 v191, v0, v4
	v_or_b32_e32 v0, 4, v2
	v_cvt_f32_ubyte0_e32 v0, v0
	v_mul_f32_e32 v4, 0xbf549a78, v0
	v_cmp_gt_f32_e32 vcc, s0, v4
	v_lshlrev_b32_e32 v182, 1, v2
	s_nop 0
	v_cndmask_b32_e32 v4, 0, v6, vcc
	v_fmac_f32_e32 v4, 0xbf549a78, v0
	v_exp_f32_e32 v0, v4
	v_cndmask_b32_e32 v4, 0, v7, vcc
	v_ldexp_f32 v192, v0, v4
	v_or_b32_e32 v0, 5, v2
	v_cvt_f32_ubyte0_e32 v0, v0
	v_mul_f32_e32 v4, 0xbf549a78, v0
	v_cmp_gt_f32_e32 vcc, s0, v4
	s_nop 1
	v_cndmask_b32_e32 v4, 0, v6, vcc
	v_fmac_f32_e32 v4, 0xbf549a78, v0
	v_exp_f32_e32 v0, v4
	v_cndmask_b32_e32 v4, 0, v7, vcc
	v_ldexp_f32 v193, v0, v4
	v_or_b32_e32 v0, 7, v2
	v_cvt_f32_ubyte0_e32 v0, v0
	v_mul_f32_e32 v4, 0xbf549a78, v0
	v_cmp_gt_f32_e32 vcc, s0, v4
	s_mov_b64 s[0:1], 0x4020
	v_lshl_add_u64 v[176:177], v[172:173], 0, s[0:1]
	v_cndmask_b32_e32 v4, 0, v6, vcc
	v_fmac_f32_e32 v4, 0xbf549a78, v0
	v_exp_f32_e32 v0, v4
	v_cndmask_b32_e32 v4, 0, v7, vcc
	v_lshlrev_b32_e32 v6, 1, v172
	v_bfe_u32 v7, v8, 5, 2
	v_ldexp_f32 v194, v0, v4
	v_and_b32_e32 v0, 0xfffff0, v172
	v_and_or_b32 v0, v6, 8, v0
	v_and_b32_e32 v4, 0x78, v8
	v_lshrrev_b32_e32 v6, 1, v172
	v_lshrrev_b32_e32 v0, 1, v0
	v_or_b32_e32 v0, v0, v7
	v_and_or_b32 v6, v6, 4, v9
	v_lshlrev_b32_e32 v9, 1, v4
	v_lshlrev_b32_e32 v0, 9, v0
	v_lshlrev_b32_e32 v6, 6, v6
	v_and_b32_e32 v10, 48, v9
	v_or3_b32 v195, v0, v6, v10
	v_and_b32_e32 v0, 0xfffff0, v11
	v_and_or_b32 v0, v12, 8, v0
	v_lshrrev_b32_e32 v0, 1, v0
	v_or_b32_e32 v0, v0, v7
	v_lshlrev_b32_e32 v0, 9, v0
	v_or3_b32 v196, v0, v6, v10
	v_lshlrev_b32_e32 v10, 4, v166
	v_and_b32_e32 v0, 0x70, v10
	v_lshl_add_u64 v[6:7], s[42:43], 0, v[0:1]
	s_mov_b64 s[0:1], 0x12e00000
	v_lshl_add_u64 v[178:179], v[6:7], 0, s[0:1]
	v_lshlrev_b32_e32 v6, 8, v172
	v_and_b32_e32 v7, 0x70, v166
	v_bitop3_b32 v197, v9, v6, v7 bitop3:0xde
	v_lshlrev_b32_e32 v6, 8, v11
	v_bitop3_b32 v198, v9, v6, v7 bitop3:0xde
	v_lshlrev_b32_e32 v7, 4, v174
	s_movk_i32 s0, 0x70
	v_lshlrev_b32_e32 v6, 8, v174
	v_bitop3_b32 v7, v10, v7, s0 bitop3:0x28
	s_add_i32 s0, 0, 0x10000
	v_add3_u32 v199, s0, v7, v6
	s_movk_i32 s0, 0x80
	v_or_b32_e32 v6, 32, v219
	v_bitop3_b32 v225, v219, v0, s0 bitop3:0x36
	s_movk_i32 s0, 0xa0
	v_bitop3_b32 v222, v6, v220, v0 bitop3:0xde
	v_or_b32_e32 v6, 64, v219
	v_bitop3_b32 v226, v219, v0, s0 bitop3:0x36
	s_movk_i32 s0, 0xc0
	v_bitop3_b32 v223, v6, v220, v0 bitop3:0xde
	v_or_b32_e32 v6, 0x60, v219
	v_bitop3_b32 v227, v219, v0, s0 bitop3:0x36
	s_movk_i32 s0, 0xe0
	v_bitop3_b32 v221, v219, v220, v0 bitop3:0xde
	v_bitop3_b32 v224, v6, v220, v0 bitop3:0xde
	v_bitop3_b32 v228, v219, v0, s0 bitop3:0x36
	v_and_b32_e32 v0, 0x118, v8
	s_cmp_lg_u32 0, -1
	v_and_b32_e32 v12, 0xc0, v10
	v_and_or_b32 v0, v13, 32, v0
	s_cselect_b32 s0, 0, 0
	v_add3_u32 v230, v12, s0, v0
	v_lshlrev_b32_e32 v184, 1, v4
	s_branch .LBB0_53

;     __device__ __forceinline__ const float* in(int i) const { return *(const float* const __attribute__((address_space(4)))*)(p + 8 * i); }
;     __device__ __forceinline__ unsigned char* ws() const { return *(unsigned char* const __attribute__((address_space(4)))*)(p + 296); }
; __device__ __forceinline__ void scan_phase(const KP& P, LAS unsigned char* lds, const int tid, const int bx, const int G) {
;     ...
;         const f32x4 kkc = *(const f32x4*)(P.in(21) + ch), kac = *(const f32x4*)(P.in(22) + ch), rkc = *(const f32x4*)(P.in(23) + ch);
;         float* BONd = (float*)(P.ws() + WS_BON) + (size_t)d * T * 32;
;         const int v = tid >> 3, kc = tid & 7;
;         f32x2 S[4];
; #pragma unroll
;         for (int i = 0; i < 4; ++i) S[i] = (f32x2){0.f, 0.f};
;         u32x2 lr, lk, lv, le, la;
.LBB0_186:
	s_bfe_u32 s2, s30, 0x50001
	s_and_b32 s3, s30, 1
	v_lshl_or_b32 v60, s2, 6, v53
	s_mul_i32 s0, s3, 0x2200000
	v_lshlrev_b32_e32 v0, 2, v60
	s_lshl_b32 s34, s0, 1
	s_waitcnt lgkmcnt(0)
	global_load_dwordx4 v[2:5], v0, s[16:17]
	global_load_dwordx4 v[6:9], v0, s[18:19]
	s_load_dwordx2 s[0:1], s[40:41], 0xb8
	s_mul_i32 s4, s3, 0x4400
	s_lshl_b32 s5, s4, 12
	s_add_u32 s12, s14, s34
	s_addc_u32 s13, s15, 0
	s_waitcnt lgkmcnt(0)
	global_load_dwordx4 v[10:13], v0, s[0:1]
	s_lshl_b32 s0, s4, 7
	s_ashr_i32 s33, s30, 6
	s_add_u32 s20, s14, s5
	s_addc_u32 s21, s15, 0
	s_add_u32 s36, s12, 0x8800000
	s_addc_u32 s37, s13, 0
	s_add_u32 s0, s24, s0
	s_addc_u32 s1, s25, 0
	s_cmp_eq_u32 s3, 0
	s_cselect_b64 s[12:13], -1, 0
	s_lshl_b32 s31, s33, 8
	s_addk_i32 s31, 0x4000
	v_cndmask_b32_e64 v0, v54, v52, s[12:13]
	v_add_u32_e32 v40, s31, v0
	v_ashrrev_i32_e32 v41, 31, v40
	v_lshlrev_b64 v[14:15], 12, v[40:41]
	v_lshl_or_b32 v14, v60, 1, v14
	v_lshl_add_u64 v[16:17], s[22:23], 0, v[14:15]
	v_readfirstlane_b32 s47, v166
	s_cmp_lg_u32 s47, 0x100
	s_cbranch_scc1 .Lscan_cw0_skip
	s_mov_b32 s46, 0
	s_mov_b32 s47, 0
	s_branch .Lscan_cw_entry
.Lscan_cw0_ret:
.Lscan_cw0_skip:
	s_waitcnt vmcnt(63) expcnt(7) lgkmcnt(15)
	s_barrier
	global_load_dwordx2 v[22:23], v[16:17], off
	v_lshl_add_u64 v[16:17], s[26:27], 0, v[14:15]
	global_load_dwordx2 v[24:25], v[16:17], off
	v_lshl_add_u64 v[16:17], s[28:29], 0, v[14:15]
	global_load_dwordx2 v[26:27], v[16:17], off
	v_lshl_add_u64 v[16:17], s[20:21], 0, v[14:15]
	v_lshl_add_u64 v[14:15], s[36:37], 0, v[14:15]
	global_load_dwordx2 v[28:29], v[16:17], off
	global_load_dwordx2 v[30:31], v[14:15], off
	s_mov_b32 s3, s82
	s_waitcnt vmcnt(0)
	v_lshlrev_b32_e32 v14, 16, v24
	v_and_b32_e32 v15, 0xffff0000, v24
	v_lshlrev_b32_e32 v16, 16, v25
	v_and_b32_e32 v17, 0xffff0000, v25
	v_pk_mul_f32 v[36:37], v[4:5], v[16:17]
	v_pk_mul_f32 v[34:35], v[2:3], v[14:15]
	s_waitcnt vmcnt(0)
	v_cvt_f32_f16_e32 v32, v30
	v_cvt_f32_f16_sdwa v33, v30 dst_sel:DWORD dst_unused:UNUSED_PAD src0_sel:WORD_1
	v_cvt_f32_f16_e32 v38, v31
	v_cvt_f32_f16_sdwa v39, v31 dst_sel:DWORD dst_unused:UNUSED_PAD src0_sel:WORD_1
	v_mul_f32_e32 v0, v35, v35
	v_pk_add_f32 v[20:21], v[32:33], -1.0 op_sel_hi:[1,0]
	v_mul_f32_e32 v46, v37, v37
	v_pk_add_f32 v[18:19], v[38:39], -1.0 op_sel_hi:[1,0]
	v_pk_fma_f32 v[42:43], v[6:7], v[20:21], 1.0 op_sel_hi:[1,1,0]
	v_pk_fma_f32 v[18:19], v[8:9], v[18:19], 1.0 op_sel_hi:[1,1,0]
	v_fmac_f32_e32 v0, v34, v34
	v_pk_mul_f32 v[20:21], v[18:19], v[16:17]
	v_pk_mul_f32 v[18:19], v[42:43], v[14:15]
	v_lshlrev_b32_e32 v14, 16, v22
	v_and_b32_e32 v15, 0xffff0000, v22
	v_lshlrev_b32_e32 v16, 16, v23
	v_and_b32_e32 v17, 0xffff0000, v23
	v_pk_mul_f32 v[42:43], v[18:19], v[14:15]
	v_pk_mul_f32 v[44:45], v[20:21], v[16:17]
	v_pk_mul_f32 v[42:43], v[10:11], v[42:43]
	v_pk_mul_f32 v[44:45], v[12:13], v[44:45]
	v_fmac_f32_e32 v46, v36, v36
	v_add_f32_e32 v42, v42, v43
	v_add_f32_e32 v43, v44, v45
	v_add_f32_e32 v0, v0, v46
	v_add_f32_e32 v42, v42, v43
	s_nop 0
	v_add_f32_dpp v0, v0, v0 quad_perm:[1,0,3,2] row_mask:0xf bank_mask:0xf bound_ctrl:1
	v_add_f32_dpp v42, v42, v42 quad_perm:[1,0,3,2] row_mask:0xf bank_mask:0xf bound_ctrl:1
	s_nop 0
	v_add_f32_dpp v0, v0, v0 quad_perm:[2,3,0,1] row_mask:0xf bank_mask:0xf bound_ctrl:1
	v_add_f32_dpp v42, v42, v42 quad_perm:[2,3,0,1] row_mask:0xf bank_mask:0xf bound_ctrl:1
	s_nop 0
	v_add_f32_dpp v0, v0, v0 row_half_mirror row_mask:0xf bank_mask:0xf bound_ctrl:1
	v_add_f32_dpp v45, v42, v42 row_half_mirror row_mask:0xf bank_mask:0xf bound_ctrl:1
	v_mov_b64_e32 v[42:43], s[2:3]
	v_mov_b32_dpp v44, v0 row_mirror row_mask:0xf bank_mask:0xf bound_ctrl:1
	v_mov_b32_dpp v46, v45 row_mirror row_mask:0xf bank_mask:0xf bound_ctrl:1
	s_and_saveexec_b64 s[4:5], s[8:9]
	s_xor_b64 s[4:5], exec, s[4:5]
	v_mov_b64_e32 v[42:43], s[2:3]
	s_andn2_saveexec_b64 s[4:5], s[4:5]
	s_cbranch_execz .LBB0_190
	v_lshlrev_b64 v[40:41], 7, v[40:41]
	v_lshl_add_u64 v[40:41], s[0:1], 0, v[40:41]
	s_lshl_b32 s2, s2, 2
	s_mov_b32 s3, s82
	v_lshl_add_u64 v[40:41], v[40:41], 0, s[2:3]
	v_add_f32_e32 v43, v45, v46
	global_store_dword v[40:41], v43, off
; #define SC_LOAD(c) do { const size_t off_ = (size_t)scan_row((c), tk, d, b) * D + ch; lr = *(const u32x2*)(R + off_); lk = *(const u32x2*)(Kb + off_); lv = *(const u32x2*)(Vb + off_); \
;             le = *(const u32x2*)(Ed + off_); la = *(const u32x2*)(Ad + off_); } while (0)
; __device__ __forceinline__ void scan_phase(const KP& P, LAS unsigned char* lds, const int tid, const int bx, const int G) {
;     ...
;         __syncthreads();
;         SC_LOAD(0); SC_WRITE(0, 0);
;         __syncthreads();
; #pragma unroll 1
;     ...
;             if (c + 1 < NCH) SC_WRITE((c + 1) & 1, c + 1);
.LBB0_190:
	s_or_b64 exec, exec, s[4:5]
	v_add_f32_e32 v0, v0, v44
	v_max_f32_e32 v0, 0x179abe15, v0
	v_cvt_f32_f16_e32 v43, v28
	v_rsq_f32_e32 v0, v0
	v_cvt_f32_f16_sdwa v45, v28 dst_sel:DWORD dst_unused:UNUSED_PAD src0_sel:WORD_1
	v_cvt_f32_f16_e32 v46, v29
	v_cvt_f32_f16_sdwa v47, v29 dst_sel:DWORD dst_unused:UNUSED_PAD src0_sel:WORD_1
	v_pk_mul_f32 v[36:37], v[36:37], v[0:1] op_sel_hi:[1,0] neg_lo:[0,1] neg_hi:[0,1]
	v_pk_mul_f32 v[34:35], v[34:35], v[0:1] op_sel_hi:[1,0] neg_lo:[0,1] neg_hi:[0,1]
	v_mul_f32_e32 v0, 0xbfb8aa3b, v43
	v_exp_f32_e32 v44, v0
	v_mul_f32_e32 v0, 0xbfb8aa3b, v45
	v_exp_f32_e32 v45, v0
	v_mul_f32_e32 v0, 0xbfb8aa3b, v46
	v_exp_f32_e32 v46, v0
	v_mul_f32_e32 v0, 0xbfb8aa3b, v47
	v_exp_f32_e32 v47, v0
	s_add_u32 s2, s42, s34
	s_addc_u32 s3, s43, 0
	v_pk_mul_f32 v[40:41], v[38:39], v[36:37] neg_lo:[0,1] neg_hi:[0,1]
	v_pk_mul_f32 v[38:39], v[32:33], v[34:35] neg_lo:[0,1] neg_hi:[0,1]
	ds_read_b128 v[66:69], v57 offset:8192
	ds_read_b128 v[70:73], v57 offset:16384
	ds_read_b128 v[74:77], v57 offset:24576
	s_waitcnt lgkmcnt(0)
	v_pk_mul_f32 v[18:19], v[18:19], v[70:71]
	v_pk_mul_f32 v[20:21], v[20:21], v[72:73]
	v_pk_mul_f32 v[38:39], v[38:39], v[70:71]
	v_pk_mul_f32 v[40:41], v[40:41], v[72:73]
	v_pk_mul_f32 v[34:35], v[34:35], v[74:75]
	v_pk_mul_f32 v[36:37], v[36:37], v[76:77]
	v_pk_mul_f32 v[14:15], v[14:15], v[66:67]
	v_pk_mul_f32 v[16:17], v[16:17], v[68:69]
	ds_write_b128 v55, v[66:69]
	ds_write_b128 v55, v[18:21] offset:256
	ds_write_b128 v55, v[34:37] offset:512
	ds_write_b128 v55, v[38:41] offset:768
	ds_write_b128 v55, v[14:17] offset:1024
	v_lshlrev_b32_e32 v14, 16, v26
	v_and_b32_e32 v15, 0xffff0000, v26
	v_lshlrev_b32_e32 v16, 16, v27
	v_and_b32_e32 v17, 0xffff0000, v27
	v_lshlrev_b32_e32 v0, 1, v60
	ds_write_b128 v55, v[14:17] offset:1280
	v_lshl_add_u64 v[14:15], s[2:3], 0, v[0:1]
	s_mov_b64 s[2:3], 0x18300000
	v_lshlrev_b32_e32 v0, 2, v42
	v_mov_b32_e32 v36, 0
	s_lshl_b32 s33, s33, 12
	v_lshl_add_u64 v[32:33], v[14:15], 0, s[2:3]
	v_lshl_add_u64 v[34:35], s[0:1], 0, v[0:1]
	s_mov_b32 s3, 0
	v_mov_b32_e32 v37, v36
	v_mov_b32_e32 v40, v36
	v_mov_b32_e32 v41, v36
	v_mov_b32_e32 v38, v36
	v_mov_b32_e32 v39, v36
	v_mov_b32_e32 v42, v36
	v_mov_b32_e32 v43, v36
	v_mov_b32_e32 v96, v36
	v_mov_b32_e32 v97, v36
	v_mov_b32_e32 v98, v36
	v_mov_b32_e32 v99, v36
	v_mov_b32_e32 v100, v36
	v_mov_b32_e32 v101, v36
	v_mov_b32_e32 v102, v36
	v_mov_b32_e32 v103, v36
	v_mov_b32_e32 v104, v36
	v_mov_b32_e32 v105, v36
	v_mov_b32_e32 v106, v36
	v_mov_b32_e32 v107, v36
	v_mov_b32_e32 v108, v36
	v_mov_b32_e32 v109, v36
	v_mov_b32_e32 v110, v36
	v_mov_b32_e32 v111, v36
	s_waitcnt lgkmcnt(0)
	s_barrier
	s_branch .LBB0_193
.LBB0_191:
	s_or_b64 exec, exec, s[0:1]
	v_add_f32_e32 v0, v0, v61
	v_max_f32_e32 v0, 0x179abe15, v0
	v_cvt_f32_f16_e32 v62, v28
	v_rsq_f32_e32 v0, v0
	v_cvt_f32_f16_sdwa v61, v28 dst_sel:DWORD dst_unused:UNUSED_PAD src0_sel:WORD_1
	v_cvt_f32_f16_e32 v64, v29
	v_cvt_f32_f16_sdwa v65, v29 dst_sel:DWORD dst_unused:UNUSED_PAD src0_sel:WORD_1
	v_pk_mul_f32 v[50:51], v[50:51], v[0:1] op_sel_hi:[1,0] neg_lo:[0,1] neg_hi:[0,1]
	v_pk_mul_f32 v[48:49], v[48:49], v[0:1] op_sel_hi:[1,0] neg_lo:[0,1] neg_hi:[0,1]
	v_mul_f32_e32 v0, 0xbfb8aa3b, v62
	v_exp_f32_e32 v62, v0
	v_mul_f32_e32 v0, 0xbfb8aa3b, v61
	v_exp_f32_e32 v63, v0
	v_mul_f32_e32 v0, 0xbfb8aa3b, v64
	v_exp_f32_e32 v64, v0
	v_mul_f32_e32 v0, 0xbfb8aa3b, v65
	v_exp_f32_e32 v65, v0
	s_bitcmp1_b32 s2, 0
	s_cselect_b32 s0, 0xc000, 0
	v_add_u32_e32 v0, s0, v55
	v_pk_mul_f32 v[46:47], v[46:47], v[50:51] neg_lo:[0,1] neg_hi:[0,1]
	v_pk_mul_f32 v[44:45], v[44:45], v[48:49] neg_lo:[0,1] neg_hi:[0,1]
	ds_read_b128 v[66:69], v57 offset:8192
	ds_read_b128 v[70:73], v57 offset:16384
	ds_read_b128 v[74:77], v57 offset:24576
	s_waitcnt lgkmcnt(0)
	v_pk_mul_f32 v[18:19], v[18:19], v[70:71]
	v_pk_mul_f32 v[20:21], v[20:21], v[72:73]
	v_pk_mul_f32 v[44:45], v[44:45], v[70:71]
	v_pk_mul_f32 v[46:47], v[46:47], v[72:73]
	v_pk_mul_f32 v[48:49], v[48:49], v[74:75]
	v_pk_mul_f32 v[50:51], v[50:51], v[76:77]
	v_pk_mul_f32 v[14:15], v[14:15], v[66:67]
	v_pk_mul_f32 v[16:17], v[16:17], v[68:69]
	ds_write_b128 v0, v[66:69]
	ds_write_b128 v0, v[18:21] offset:256
	ds_write_b128 v0, v[48:51] offset:512
	ds_write_b128 v0, v[44:47] offset:768
	ds_write_b128 v0, v[14:17] offset:1024
	v_lshlrev_b32_e32 v14, 16, v26
	v_and_b32_e32 v15, 0xffff0000, v26
	v_lshlrev_b32_e32 v16, 16, v27
	v_and_b32_e32 v17, 0xffff0000, v27
	ds_write_b128 v0, v[14:17] offset:1280

; __device__ __forceinline__ int scan_row(int chunk, int tk, int d, int b) {
;     ...
;     if (chunk < 8) return NL + b * CTXL + (d ? (CTXL - 1 - s) : s);
;     const int s2 = s - CTXL; return b * SEQ + (d ? (SEQ - 1 - s2) : s2);
.LBB0_195:
	v_readfirstlane_b32 s34, v166
	s_cmp_lt_u32 s34, 0x100
	s_cbranch_scc1 .Lscan_compute
	s_cmp_lg_u32 s34, 0x100
	s_cbranch_scc1 .LBB0_229
	s_cmp_ge_u32 s2, 0x88
	s_cbranch_scc1 .LBB0_229
	s_mov_b32 s46, s2
	s_mov_b32 s47, 1
.Lscan_cw_entry:
	s_lshl_b32 s35, s46, 5
	s_cmp_lt_u32 s46, 8
	s_cselect_b32 s38, s31, s33
	s_cselect_b32 s39, 0xff, s80
	s_cselect_b32 s32, 0, 0x100
	v_and_b32_e32 v45, 63, v166
	v_sub_u32_e32 v44, v60, v53
	v_add_u32_e32 v44, v44, v45
	v_lshlrev_b32_e32 v44, 1, v44
	v_lshlrev_b32_e32 v45, 2, v45
	v_add_u32_e32 v45, 0x1a000, v45
	s_cmp_lg_u64 s[12:13], 0
	s_cbranch_scc0 .Lscan_cw_rev
	s_sub_u32 s35, s35, s32
	s_mov_b32 s32, 0x1000
	s_branch .Lscan_cw_com
.Lscan_cw_rev:
	s_sub_u32 s35, s39, s35
	s_sub_u32 s35, s35, 31
	s_mov_b32 s32, 0xfffff000
	v_add_u32_e32 v44, 0x1f000, v44
.Lscan_cw_com:
	s_add_u32 s35, s38, s35
	s_lshl_b32 s35, s35, 12
	s_add_u32 s86, s20, s35
	s_addc_u32 s87, s21, 0
	global_load_ushort v62, v44, s[86:87]
	v_add_u32_e32 v44, s32, v44
	global_load_ushort v63, v44, s[86:87]
	v_add_u32_e32 v44, s32, v44
	global_load_ushort v64, v44, s[86:87]
	v_add_u32_e32 v44, s32, v44
	global_load_ushort v65, v44, s[86:87]
	v_add_u32_e32 v44, s32, v44
	global_load_ushort v66, v44, s[86:87]
	v_add_u32_e32 v44, s32, v44
	global_load_ushort v67, v44, s[86:87]
	v_add_u32_e32 v44, s32, v44
	global_load_ushort v68, v44, s[86:87]
	v_add_u32_e32 v44, s32, v44
	global_load_ushort v69, v44, s[86:87]
	v_add_u32_e32 v44, s32, v44
	global_load_ushort v70, v44, s[86:87]
	v_add_u32_e32 v44, s32, v44
	global_load_ushort v71, v44, s[86:87]
	v_add_u32_e32 v44, s32, v44
	global_load_ushort v72, v44, s[86:87]
	v_add_u32_e32 v44, s32, v44
	global_load_ushort v73, v44, s[86:87]
	v_add_u32_e32 v44, s32, v44
	global_load_ushort v74, v44, s[86:87]
	v_add_u32_e32 v44, s32, v44
	global_load_ushort v75, v44, s[86:87]
	v_add_u32_e32 v44, s32, v44
	global_load_ushort v76, v44, s[86:87]
	v_add_u32_e32 v44, s32, v44
	global_load_ushort v77, v44, s[86:87]
	v_add_u32_e32 v44, s32, v44
	global_load_ushort v78, v44, s[86:87]
	v_add_u32_e32 v44, s32, v44
	global_load_ushort v79, v44, s[86:87]
	v_add_u32_e32 v44, s32, v44
	global_load_ushort v80, v44, s[86:87]
	v_add_u32_e32 v44, s32, v44
	global_load_ushort v81, v44, s[86:87]
	v_add_u32_e32 v44, s32, v44
	global_load_ushort v82, v44, s[86:87]
	v_add_u32_e32 v44, s32, v44
	global_load_ushort v83, v44, s[86:87]
	v_add_u32_e32 v44, s32, v44
	global_load_ushort v84, v44, s[86:87]
	v_add_u32_e32 v44, s32, v44
	global_load_ushort v85, v44, s[86:87]
	v_add_u32_e32 v44, s32, v44
	global_load_ushort v86, v44, s[86:87]
	v_add_u32_e32 v44, s32, v44
	global_load_ushort v87, v44, s[86:87]
	v_add_u32_e32 v44, s32, v44
	global_load_ushort v88, v44, s[86:87]
	v_add_u32_e32 v44, s32, v44
	global_load_ushort v89, v44, s[86:87]
	v_add_u32_e32 v44, s32, v44
	global_load_ushort v90, v44, s[86:87]
	v_add_u32_e32 v44, s32, v44
	global_load_ushort v91, v44, s[86:87]
	v_add_u32_e32 v44, s32, v44
	global_load_ushort v92, v44, s[86:87]
	v_add_u32_e32 v44, s32, v44
	global_load_ushort v93, v44, s[86:87]
	v_add_u32_e32 v44, s32, v44
	v_mov_b32_e32 v46, 0
	s_waitcnt vmcnt(0)
	v_cvt_f32_f16_e32 v47, v62
	v_mul_f32_e32 v48, 0xbfb8aa3b, v46
	v_add_f32_e32 v46, v46, v47
	v_exp_f32_e32 v48, v48
	v_mul_f32_e32 v49, 0xbfb8aa3b, v46
	v_mul_f32_e32 v50, 0x3fb8aa3b, v46
	v_exp_f32_e32 v49, v49
	v_exp_f32_e32 v50, v50
	ds_write_b32 v45, v48 offset:16384
	s_nop 0
	ds_write_b32 v45, v49 offset:0
	ds_write_b32 v45, v50 offset:8192
	v_cvt_f32_f16_e32 v47, v63
	v_mul_f32_e32 v48, 0xbfb8aa3b, v46
	v_add_f32_e32 v46, v46, v47
	v_exp_f32_e32 v48, v48
	v_mul_f32_e32 v49, 0xbfb8aa3b, v46
	v_mul_f32_e32 v50, 0x3fb8aa3b, v46
	v_exp_f32_e32 v49, v49
	v_exp_f32_e32 v50, v50
	ds_write_b32 v45, v48 offset:16640
	s_nop 0
	ds_write_b32 v45, v49 offset:256
	ds_write_b32 v45, v50 offset:8448
	v_cvt_f32_f16_e32 v47, v64
	v_mul_f32_e32 v48, 0xbfb8aa3b, v46
	v_add_f32_e32 v46, v46, v47
	v_exp_f32_e32 v48, v48
	v_mul_f32_e32 v49, 0xbfb8aa3b, v46
	v_mul_f32_e32 v50, 0x3fb8aa3b, v46
	v_exp_f32_e32 v49, v49
	v_exp_f32_e32 v50, v50
	ds_write_b32 v45, v48 offset:16896
	s_nop 0
	ds_write_b32 v45, v49 offset:512
	ds_write_b32 v45, v50 offset:8704
	v_cvt_f32_f16_e32 v47, v65
	v_mul_f32_e32 v48, 0xbfb8aa3b, v46
	v_add_f32_e32 v46, v46, v47
	v_exp_f32_e32 v48, v48
	v_mul_f32_e32 v49, 0xbfb8aa3b, v46
	v_mul_f32_e32 v50, 0x3fb8aa3b, v46
	v_exp_f32_e32 v49, v49
	v_exp_f32_e32 v50, v50
	ds_write_b32 v45, v48 offset:17152
	s_nop 0
	ds_write_b32 v45, v49 offset:768
	ds_write_b32 v45, v50 offset:8960
	v_cvt_f32_f16_e32 v47, v66
	v_mul_f32_e32 v48, 0xbfb8aa3b, v46
	v_add_f32_e32 v46, v46, v47
	v_exp_f32_e32 v48, v48
	v_mul_f32_e32 v49, 0xbfb8aa3b, v46
	v_mul_f32_e32 v50, 0x3fb8aa3b, v46
	v_exp_f32_e32 v49, v49
	v_exp_f32_e32 v50, v50
	ds_write_b32 v45, v48 offset:17408
	s_nop 0
	ds_write_b32 v45, v49 offset:1024
	ds_write_b32 v45, v50 offset:9216
	v_cvt_f32_f16_e32 v47, v67
	v_mul_f32_e32 v48, 0xbfb8aa3b, v46
	v_add_f32_e32 v46, v46, v47
	v_exp_f32_e32 v48, v48
	v_mul_f32_e32 v49, 0xbfb8aa3b, v46
	v_mul_f32_e32 v50, 0x3fb8aa3b, v46
	v_exp_f32_e32 v49, v49
	v_exp_f32_e32 v50, v50
	ds_write_b32 v45, v48 offset:17664
	s_nop 0
	ds_write_b32 v45, v49 offset:1280
	ds_write_b32 v45, v50 offset:9472
	v_cvt_f32_f16_e32 v47, v68
	v_mul_f32_e32 v48, 0xbfb8aa3b, v46
	v_add_f32_e32 v46, v46, v47
	v_exp_f32_e32 v48, v48
	v_mul_f32_e32 v49, 0xbfb8aa3b, v46
	v_mul_f32_e32 v50, 0x3fb8aa3b, v46
	v_exp_f32_e32 v49, v49
	v_exp_f32_e32 v50, v50
	ds_write_b32 v45, v48 offset:17920
	s_nop 0
	ds_write_b32 v45, v49 offset:1536
	ds_write_b32 v45, v50 offset:9728
	v_cvt_f32_f16_e32 v47, v69
	v_mul_f32_e32 v48, 0xbfb8aa3b, v46
	v_add_f32_e32 v46, v46, v47
	v_exp_f32_e32 v48, v48
	v_mul_f32_e32 v49, 0xbfb8aa3b, v46
	v_mul_f32_e32 v50, 0x3fb8aa3b, v46
	v_exp_f32_e32 v49, v49
	v_exp_f32_e32 v50, v50
	ds_write_b32 v45, v48 offset:18176
	s_nop 0
	ds_write_b32 v45, v49 offset:1792
	ds_write_b32 v45, v50 offset:9984
	v_cvt_f32_f16_e32 v47, v70
	v_mul_f32_e32 v48, 0xbfb8aa3b, v46
	v_add_f32_e32 v46, v46, v47
	v_exp_f32_e32 v48, v48
	v_mul_f32_e32 v49, 0xbfb8aa3b, v46
	v_mul_f32_e32 v50, 0x3fb8aa3b, v46
	v_exp_f32_e32 v49, v49
	v_exp_f32_e32 v50, v50
	ds_write_b32 v45, v48 offset:18432
	s_nop 0
	ds_write_b32 v45, v49 offset:2048
	ds_write_b32 v45, v50 offset:10240
	v_cvt_f32_f16_e32 v47, v71
	v_mul_f32_e32 v48, 0xbfb8aa3b, v46
	v_add_f32_e32 v46, v46, v47
	v_exp_f32_e32 v48, v48
	v_mul_f32_e32 v49, 0xbfb8aa3b, v46
	v_mul_f32_e32 v50, 0x3fb8aa3b, v46
	v_exp_f32_e32 v49, v49
	v_exp_f32_e32 v50, v50
	ds_write_b32 v45, v48 offset:18688
	s_nop 0
	ds_write_b32 v45, v49 offset:2304
	ds_write_b32 v45, v50 offset:10496
	v_cvt_f32_f16_e32 v47, v72
	v_mul_f32_e32 v48, 0xbfb8aa3b, v46
	v_add_f32_e32 v46, v46, v47
	v_exp_f32_e32 v48, v48
	v_mul_f32_e32 v49, 0xbfb8aa3b, v46
	v_mul_f32_e32 v50, 0x3fb8aa3b, v46
	v_exp_f32_e32 v49, v49
	v_exp_f32_e32 v50, v50
	ds_write_b32 v45, v48 offset:18944
	s_nop 0
	ds_write_b32 v45, v49 offset:2560
	ds_write_b32 v45, v50 offset:10752
	v_cvt_f32_f16_e32 v47, v73
	v_mul_f32_e32 v48, 0xbfb8aa3b, v46
	v_add_f32_e32 v46, v46, v47
	v_exp_f32_e32 v48, v48
	v_mul_f32_e32 v49, 0xbfb8aa3b, v46
	v_mul_f32_e32 v50, 0x3fb8aa3b, v46
	v_exp_f32_e32 v49, v49
	v_exp_f32_e32 v50, v50
	ds_write_b32 v45, v48 offset:19200
	s_nop 0
	ds_write_b32 v45, v49 offset:2816
	ds_write_b32 v45, v50 offset:11008
	v_cvt_f32_f16_e32 v47, v74
	v_mul_f32_e32 v48, 0xbfb8aa3b, v46
	v_add_f32_e32 v46, v46, v47
	v_exp_f32_e32 v48, v48
	v_mul_f32_e32 v49, 0xbfb8aa3b, v46
	v_mul_f32_e32 v50, 0x3fb8aa3b, v46
	v_exp_f32_e32 v49, v49
	v_exp_f32_e32 v50, v50
	ds_write_b32 v45, v48 offset:19456
	s_nop 0
	ds_write_b32 v45, v49 offset:3072
	ds_write_b32 v45, v50 offset:11264
	v_cvt_f32_f16_e32 v47, v75
	v_mul_f32_e32 v48, 0xbfb8aa3b, v46
	v_add_f32_e32 v46, v46, v47
	v_exp_f32_e32 v48, v48
	v_mul_f32_e32 v49, 0xbfb8aa3b, v46
	v_mul_f32_e32 v50, 0x3fb8aa3b, v46
	v_exp_f32_e32 v49, v49
	v_exp_f32_e32 v50, v50
	ds_write_b32 v45, v48 offset:19712
	s_nop 0
	ds_write_b32 v45, v49 offset:3328
	ds_write_b32 v45, v50 offset:11520
	v_cvt_f32_f16_e32 v47, v76
	v_mul_f32_e32 v48, 0xbfb8aa3b, v46
	v_add_f32_e32 v46, v46, v47
	v_exp_f32_e32 v48, v48
	v_mul_f32_e32 v49, 0xbfb8aa3b, v46
	v_mul_f32_e32 v50, 0x3fb8aa3b, v46
	v_exp_f32_e32 v49, v49
	v_exp_f32_e32 v50, v50
	ds_write_b32 v45, v48 offset:19968
	s_nop 0
	ds_write_b32 v45, v49 offset:3584
	ds_write_b32 v45, v50 offset:11776
	v_cvt_f32_f16_e32 v47, v77
	v_mul_f32_e32 v48, 0xbfb8aa3b, v46
	v_add_f32_e32 v46, v46, v47
	v_exp_f32_e32 v48, v48
	v_mul_f32_e32 v49, 0xbfb8aa3b, v46
	v_mul_f32_e32 v50, 0x3fb8aa3b, v46
	v_exp_f32_e32 v49, v49
	v_exp_f32_e32 v50, v50
	ds_write_b32 v45, v48 offset:20224
	s_nop 0
	ds_write_b32 v45, v49 offset:3840
	ds_write_b32 v45, v50 offset:12032
	v_cvt_f32_f16_e32 v47, v78
	v_mul_f32_e32 v48, 0xbfb8aa3b, v46
	v_add_f32_e32 v46, v46, v47
	v_exp_f32_e32 v48, v48
	v_mul_f32_e32 v49, 0xbfb8aa3b, v46
	v_mul_f32_e32 v50, 0x3fb8aa3b, v46
	v_exp_f32_e32 v49, v49
	v_exp_f32_e32 v50, v50
	ds_write_b32 v45, v48 offset:20480
	s_nop 0
	ds_write_b32 v45, v49 offset:4096
	ds_write_b32 v45, v50 offset:12288
	v_cvt_f32_f16_e32 v47, v79
	v_mul_f32_e32 v48, 0xbfb8aa3b, v46
	v_add_f32_e32 v46, v46, v47
	v_exp_f32_e32 v48, v48
	v_mul_f32_e32 v49, 0xbfb8aa3b, v46
	v_mul_f32_e32 v50, 0x3fb8aa3b, v46
	v_exp_f32_e32 v49, v49
	v_exp_f32_e32 v50, v50
	ds_write_b32 v45, v48 offset:20736
	s_nop 0
	ds_write_b32 v45, v49 offset:4352
	ds_write_b32 v45, v50 offset:12544
	v_cvt_f32_f16_e32 v47, v80
	v_mul_f32_e32 v48, 0xbfb8aa3b, v46
	v_add_f32_e32 v46, v46, v47
	v_exp_f32_e32 v48, v48
	v_mul_f32_e32 v49, 0xbfb8aa3b, v46
	v_mul_f32_e32 v50, 0x3fb8aa3b, v46
	v_exp_f32_e32 v49, v49
	v_exp_f32_e32 v50, v50
	ds_write_b32 v45, v48 offset:20992
	s_nop 0
	ds_write_b32 v45, v49 offset:4608
	ds_write_b32 v45, v50 offset:12800
	v_cvt_f32_f16_e32 v47, v81
	v_mul_f32_e32 v48, 0xbfb8aa3b, v46
	v_add_f32_e32 v46, v46, v47
	v_exp_f32_e32 v48, v48
	v_mul_f32_e32 v49, 0xbfb8aa3b, v46
	v_mul_f32_e32 v50, 0x3fb8aa3b, v46
	v_exp_f32_e32 v49, v49
	v_exp_f32_e32 v50, v50
	ds_write_b32 v45, v48 offset:21248
	s_nop 0
	ds_write_b32 v45, v49 offset:4864
	ds_write_b32 v45, v50 offset:13056
	v_cvt_f32_f16_e32 v47, v82
	v_mul_f32_e32 v48, 0xbfb8aa3b, v46
	v_add_f32_e32 v46, v46, v47
	v_exp_f32_e32 v48, v48
	v_mul_f32_e32 v49, 0xbfb8aa3b, v46
	v_mul_f32_e32 v50, 0x3fb8aa3b, v46
	v_exp_f32_e32 v49, v49
	v_exp_f32_e32 v50, v50
	ds_write_b32 v45, v48 offset:21504
	s_nop 0
	ds_write_b32 v45, v49 offset:5120
	ds_write_b32 v45, v50 offset:13312
	v_cvt_f32_f16_e32 v47, v83
	v_mul_f32_e32 v48, 0xbfb8aa3b, v46
	v_add_f32_e32 v46, v46, v47
	v_exp_f32_e32 v48, v48
	v_mul_f32_e32 v49, 0xbfb8aa3b, v46
	v_mul_f32_e32 v50, 0x3fb8aa3b, v46
	v_exp_f32_e32 v49, v49
	v_exp_f32_e32 v50, v50
	ds_write_b32 v45, v48 offset:21760
	s_nop 0
	ds_write_b32 v45, v49 offset:5376
	ds_write_b32 v45, v50 offset:13568
	v_cvt_f32_f16_e32 v47, v84
	v_mul_f32_e32 v48, 0xbfb8aa3b, v46
	v_add_f32_e32 v46, v46, v47
	v_exp_f32_e32 v48, v48
	v_mul_f32_e32 v49, 0xbfb8aa3b, v46
	v_mul_f32_e32 v50, 0x3fb8aa3b, v46
	v_exp_f32_e32 v49, v49
	v_exp_f32_e32 v50, v50
	ds_write_b32 v45, v48 offset:22016
	s_nop 0
	ds_write_b32 v45, v49 offset:5632
	ds_write_b32 v45, v50 offset:13824
	v_cvt_f32_f16_e32 v47, v85
; #define LAS __attribute__((address_space(3)))
; __device__ __forceinline__ void scan_phase(const KP& P, LAS unsigned char* lds, const int tid, const int bx, const int G) {
;     ...
;             const LAS float* cb = buf + (c & 1) * 12288 + kc * 8;
; #pragma unroll 16
;             for (int s = 0; s < 32; ++s) {
;                 const LAS float* p = cb + s * 384;
;                 const f32x4 w0 = *(const LAS f32x4*)(p), w1 = *(const LAS f32x4*)(p + 4);
;                 const f32x4 k0 = *(const LAS f32x4*)(p + 64), k1 = *(const LAS f32x4*)(p + 68);
;                 const f32x4 a0 = *(const LAS f32x4*)(p + 128), a1 = *(const LAS f32x4*)(p + 132);
;                 const f32x4 b0 = *(const LAS f32x4*)(p + 192), b1 = *(const LAS f32x4*)(p + 196);
;                 const f32x4 r0 = *(const LAS f32x4*)(p + 256), r1 = *(const LAS f32x4*)(p + 260);
;                 const float vv = buf[(c & 1) * 12288 + s * 384 + 320 + v];
	v_mul_f32_e32 v48, 0xbfb8aa3b, v46
	v_add_f32_e32 v46, v46, v47
	v_exp_f32_e32 v48, v48
	v_mul_f32_e32 v49, 0xbfb8aa3b, v46
	v_mul_f32_e32 v50, 0x3fb8aa3b, v46
	v_exp_f32_e32 v49, v49
	v_exp_f32_e32 v50, v50
	ds_write_b32 v45, v48 offset:22272
	s_nop 0
	ds_write_b32 v45, v49 offset:5888
	ds_write_b32 v45, v50 offset:14080
	v_cvt_f32_f16_e32 v47, v86
	v_mul_f32_e32 v48, 0xbfb8aa3b, v46
	v_add_f32_e32 v46, v46, v47
	v_exp_f32_e32 v48, v48
	v_mul_f32_e32 v49, 0xbfb8aa3b, v46
	v_mul_f32_e32 v50, 0x3fb8aa3b, v46
	v_exp_f32_e32 v49, v49
	v_exp_f32_e32 v50, v50
	ds_write_b32 v45, v48 offset:22528
	s_nop 0
	ds_write_b32 v45, v49 offset:6144
	ds_write_b32 v45, v50 offset:14336
	v_cvt_f32_f16_e32 v47, v87
	v_mul_f32_e32 v48, 0xbfb8aa3b, v46
	v_add_f32_e32 v46, v46, v47
	v_exp_f32_e32 v48, v48
	v_mul_f32_e32 v49, 0xbfb8aa3b, v46
	v_mul_f32_e32 v50, 0x3fb8aa3b, v46
	v_exp_f32_e32 v49, v49
	v_exp_f32_e32 v50, v50
	ds_write_b32 v45, v48 offset:22784
	s_nop 0
	ds_write_b32 v45, v49 offset:6400
	ds_write_b32 v45, v50 offset:14592
	v_cvt_f32_f16_e32 v47, v88
	v_mul_f32_e32 v48, 0xbfb8aa3b, v46
	v_add_f32_e32 v46, v46, v47
	v_exp_f32_e32 v48, v48
	v_mul_f32_e32 v49, 0xbfb8aa3b, v46
	v_mul_f32_e32 v50, 0x3fb8aa3b, v46
	v_exp_f32_e32 v49, v49
	v_exp_f32_e32 v50, v50
	ds_write_b32 v45, v48 offset:23040
	s_nop 0
	ds_write_b32 v45, v49 offset:6656
	ds_write_b32 v45, v50 offset:14848
	v_cvt_f32_f16_e32 v47, v89
	v_mul_f32_e32 v48, 0xbfb8aa3b, v46
	v_add_f32_e32 v46, v46, v47
	v_exp_f32_e32 v48, v48
	v_mul_f32_e32 v49, 0xbfb8aa3b, v46
	v_mul_f32_e32 v50, 0x3fb8aa3b, v46
	v_exp_f32_e32 v49, v49
	v_exp_f32_e32 v50, v50
	ds_write_b32 v45, v48 offset:23296
	s_nop 0
	ds_write_b32 v45, v49 offset:6912
	ds_write_b32 v45, v50 offset:15104
	v_cvt_f32_f16_e32 v47, v90
	v_mul_f32_e32 v48, 0xbfb8aa3b, v46
	v_add_f32_e32 v46, v46, v47
	v_exp_f32_e32 v48, v48
	v_mul_f32_e32 v49, 0xbfb8aa3b, v46
	v_mul_f32_e32 v50, 0x3fb8aa3b, v46
	v_exp_f32_e32 v49, v49
	v_exp_f32_e32 v50, v50
	ds_write_b32 v45, v48 offset:23552
	s_nop 0
	ds_write_b32 v45, v49 offset:7168
	ds_write_b32 v45, v50 offset:15360
	v_cvt_f32_f16_e32 v47, v91
	v_mul_f32_e32 v48, 0xbfb8aa3b, v46
	v_add_f32_e32 v46, v46, v47
	v_exp_f32_e32 v48, v48
	v_mul_f32_e32 v49, 0xbfb8aa3b, v46
	v_mul_f32_e32 v50, 0x3fb8aa3b, v46
	v_exp_f32_e32 v49, v49
	v_exp_f32_e32 v50, v50
	ds_write_b32 v45, v48 offset:23808
	s_nop 0
	ds_write_b32 v45, v49 offset:7424
	ds_write_b32 v45, v50 offset:15616
	v_cvt_f32_f16_e32 v47, v92
	v_mul_f32_e32 v48, 0xbfb8aa3b, v46
	v_add_f32_e32 v46, v46, v47
	v_exp_f32_e32 v48, v48
	v_mul_f32_e32 v49, 0xbfb8aa3b, v46
	v_mul_f32_e32 v50, 0x3fb8aa3b, v46
	v_exp_f32_e32 v49, v49
	v_exp_f32_e32 v50, v50
	ds_write_b32 v45, v48 offset:24064
	s_nop 0
	ds_write_b32 v45, v49 offset:7680
	ds_write_b32 v45, v50 offset:15872
	v_cvt_f32_f16_e32 v47, v93
	v_mul_f32_e32 v48, 0xbfb8aa3b, v46
	v_add_f32_e32 v46, v46, v47
	v_exp_f32_e32 v48, v48
	v_mul_f32_e32 v49, 0xbfb8aa3b, v46
	v_mul_f32_e32 v50, 0x3fb8aa3b, v46
	v_exp_f32_e32 v49, v49
	v_exp_f32_e32 v50, v50
	ds_write_b32 v45, v48 offset:24320
	s_nop 0
	ds_write_b32 v45, v49 offset:7936
	ds_write_b32 v45, v50 offset:16128
	s_waitcnt lgkmcnt(0)
	s_cmp_eq_u32 s47, 0
	s_cbranch_scc1 .Lscan_cw0_ret
	s_branch .LBB0_229
.Lscan_compute:
	s_bitcmp1_b32 s3, 0
	s_cselect_b32 s0, 0xc000, 0
	v_lshlrev_b32_e32 v45, 1, v58
	v_or_b32_e32 v44, s0, v56
	v_add_u32_e32 v46, s0, v45
	v_add_u32_e32 v46, 0x500, v46
	v_add_u32_e32 v45, 0x18000, v45
	s_mov_b64 s[0:1], exec
	ds_read_b128 v[148:151], v44 offset:512
	ds_read_b128 v[152:155], v44 offset:528
	ds_read_b128 v[156:159], v44 offset:2048
	ds_read_b128 v[160:163], v44 offset:2064
	ds_read_b128 v[120:123], v44 offset:256
	ds_read_b128 v[124:127], v44 offset:272
	ds_read_b128 v[128:131], v44 offset:768
	ds_read_b128 v[132:135], v44 offset:784
	ds_read_b128 v[136:139], v44 offset:1024
	ds_read_b128 v[140:143], v44 offset:1040
	ds_read_b64 v[144:145], v46 offset:0
	ds_read_b128 v[112:115], v44 offset:47616
	ds_read_b128 v[116:119], v44 offset:47632
	s_waitcnt lgkmcnt(11)
	v_pk_mul_f32 v[188:189], v[96:97], v[148:149] op_sel:[0,0] op_sel_hi:[1,0]
	v_pk_mul_f32 v[190:191], v[98:99], v[148:149] op_sel:[0,1] op_sel_hi:[1,1]
	v_pk_fma_f32 v[188:189], v[100:101], v[150:151], v[188:189] op_sel:[0,0,0] op_sel_hi:[1,0,1]
	v_pk_fma_f32 v[190:191], v[102:103], v[150:151], v[190:191] op_sel:[0,1,0] op_sel_hi:[1,1,1]
	v_pk_fma_f32 v[188:189], v[104:105], v[152:153], v[188:189] op_sel:[0,0,0] op_sel_hi:[1,0,1]
	v_pk_fma_f32 v[190:191], v[106:107], v[152:153], v[190:191] op_sel:[0,1,0] op_sel_hi:[1,1,1]
	v_pk_fma_f32 v[188:189], v[108:109], v[154:155], v[188:189] op_sel:[0,0,0] op_sel_hi:[1,0,1]
	v_pk_fma_f32 v[190:191], v[110:111], v[154:155], v[190:191] op_sel:[0,1,0] op_sel_hi:[1,1,1]
	v_pk_add_f32 v[194:195], v[188:189], v[190:191]
	ds_read_b128 v[70:73], v44 offset:1792
	ds_read_b128 v[74:77], v44 offset:1808
	ds_read_b128 v[78:81], v44 offset:2304
	ds_read_b128 v[82:85], v44 offset:2320
	ds_read_b128 v[86:89], v44 offset:2560
	ds_read_b128 v[90:93], v44 offset:2576
	ds_read_b64 v[146:147], v46 offset:1536
	ds_read_b128 v[148:151], v44 offset:3584
	ds_read_b128 v[152:155], v44 offset:3600
	s_waitcnt lgkmcnt(9)
; #define LAS __attribute__((address_space(3)))
; __device__ __forceinline__ float red8(float x) { x += dpp_mov<0xB1>(x); x += dpp_mov<0x4E>(x); x += dpp_mov<0x141>(x); return x; }
; __device__ __forceinline__ void scan_phase(const KP& P, LAS unsigned char* lds, const int tid, const int bx, const int G) {
;     ...
;             for (int s = 0; s < 32; ++s) {
;                 const LAS float* p = cb + s * 384;
;                 const f32x4 w0 = *(const LAS f32x4*)(p), w1 = *(const LAS f32x4*)(p + 4);
;                 const f32x4 k0 = *(const LAS f32x4*)(p + 64), k1 = *(const LAS f32x4*)(p + 68);
;                 const f32x4 a0 = *(const LAS f32x4*)(p + 128), a1 = *(const LAS f32x4*)(p + 132);
;                 const f32x4 b0 = *(const LAS f32x4*)(p + 192), b1 = *(const LAS f32x4*)(p + 196);
;                 const f32x4 r0 = *(const LAS f32x4*)(p + 256), r1 = *(const LAS f32x4*)(p + 260);
;                 const float vv = buf[(c & 1) * 12288 + s * 384 + 320 + v];
;                 f32x2 sa2 = S[0] * (f32x2){a0.x, a0.y};
;                 sa2 += S[1] * (f32x2){a0.z, a0.w}; sa2 += S[2] * (f32x2){a1.x, a1.y}; sa2 += S[3] * (f32x2){a1.z, a1.w};
;                 const float sa = red8(sa2.x + sa2.y);
;                 const f32x2 sav = {sa, sa}, vv2 = {vv, vv};
;                 S[0] = S[0] * (f32x2){w0.x, w0.y} + sav * (f32x2){b0.x, b0.y} + vv2 * (f32x2){k0.x, k0.y};
;                 S[1] = S[1] * (f32x2){w0.z, w0.w} + sav * (f32x2){b0.z, b0.w} + vv2 * (f32x2){k0.z, k0.w};
;                 S[2] = S[2] * (f32x2){w1.x, w1.y} + sav * (f32x2){b1.x, b1.y} + vv2 * (f32x2){k1.x, k1.y};
;                 S[3] = S[3] * (f32x2){w1.z, w1.w} + sav * (f32x2){b1.z, b1.w} + vv2 * (f32x2){k1.z, k1.w};
;                 f32x2 y2 = S[0] * (f32x2){r0.x, r0.y};
;                 y2 += S[1] * (f32x2){r0.z, r0.w}; y2 += S[2] * (f32x2){r1.x, r1.y}; y2 += S[3] * (f32x2){r1.z, r1.w};
;                 const float y = red8(y2.x + y2.y);
;                 if (kc == 0) ybuf[s * 64 + v] = y;
	v_add_f32_dpp v194, v194, v194 quad_perm:[1,0,3,2] row_mask:0xf bank_mask:0xf bound_ctrl:1
	v_add_f32_dpp v195, v195, v195 quad_perm:[1,0,3,2] row_mask:0xf bank_mask:0xf bound_ctrl:1
	v_pk_fma_f32 v[96:97], v[144:145], v[120:121], v[96:97] op_sel:[0,0,0] op_sel_hi:[1,0,1]
	v_pk_fma_f32 v[98:99], v[144:145], v[120:121], v[98:99] op_sel:[0,1,0] op_sel_hi:[1,1,1]
	v_pk_fma_f32 v[100:101], v[144:145], v[122:123], v[100:101] op_sel:[0,0,0] op_sel_hi:[1,0,1]
	v_add_f32_dpp v194, v194, v194 quad_perm:[2,3,0,1] row_mask:0xf bank_mask:0xf bound_ctrl:1
	v_add_f32_dpp v195, v195, v195 quad_perm:[2,3,0,1] row_mask:0xf bank_mask:0xf bound_ctrl:1
	v_pk_fma_f32 v[102:103], v[144:145], v[122:123], v[102:103] op_sel:[0,1,0] op_sel_hi:[1,1,1]
	v_pk_fma_f32 v[104:105], v[144:145], v[124:125], v[104:105] op_sel:[0,0,0] op_sel_hi:[1,0,1]
	v_pk_fma_f32 v[106:107], v[144:145], v[124:125], v[106:107] op_sel:[0,1,0] op_sel_hi:[1,1,1]
	v_add_f32_dpp v194, v194, v194 row_half_mirror row_mask:0xf bank_mask:0xf bound_ctrl:1
	v_add_f32_dpp v195, v195, v195 row_half_mirror row_mask:0xf bank_mask:0xf bound_ctrl:1
	v_pk_fma_f32 v[108:109], v[144:145], v[126:127], v[108:109] op_sel:[0,0,0] op_sel_hi:[1,0,1]
	v_pk_fma_f32 v[110:111], v[144:145], v[126:127], v[110:111] op_sel:[0,1,0] op_sel_hi:[1,1,1]
	s_nop 0
	v_pk_fma_f32 v[96:97], v[194:195], v[128:129], v[96:97] op_sel:[0,0,0] op_sel_hi:[1,0,1]
	v_pk_fma_f32 v[98:99], v[194:195], v[128:129], v[98:99] op_sel:[0,1,0] op_sel_hi:[1,1,1]
	v_pk_fma_f32 v[100:101], v[194:195], v[130:131], v[100:101] op_sel:[0,0,0] op_sel_hi:[1,0,1]
	v_pk_fma_f32 v[102:103], v[194:195], v[130:131], v[102:103] op_sel:[0,1,0] op_sel_hi:[1,1,1]
	v_pk_fma_f32 v[104:105], v[194:195], v[132:133], v[104:105] op_sel:[0,0,0] op_sel_hi:[1,0,1]
	v_pk_fma_f32 v[106:107], v[194:195], v[132:133], v[106:107] op_sel:[0,1,0] op_sel_hi:[1,1,1]
	v_pk_fma_f32 v[108:109], v[194:195], v[134:135], v[108:109] op_sel:[0,0,0] op_sel_hi:[1,0,1]
	v_pk_fma_f32 v[110:111], v[194:195], v[134:135], v[110:111] op_sel:[0,1,0] op_sel_hi:[1,1,1]
	v_pk_mul_f32 v[184:185], v[96:97], v[136:137] op_sel:[0,0] op_sel_hi:[1,0]
	v_pk_mul_f32 v[188:189], v[96:97], v[156:157] op_sel:[0,0] op_sel_hi:[1,0]
	v_pk_mul_f32 v[186:187], v[98:99], v[136:137] op_sel:[0,1] op_sel_hi:[1,1]
	v_pk_mul_f32 v[190:191], v[98:99], v[156:157] op_sel:[0,1] op_sel_hi:[1,1]
	v_pk_fma_f32 v[184:185], v[100:101], v[138:139], v[184:185] op_sel:[0,0,0] op_sel_hi:[1,0,1]
	v_pk_fma_f32 v[188:189], v[100:101], v[158:159], v[188:189] op_sel:[0,0,0] op_sel_hi:[1,0,1]
	v_pk_fma_f32 v[186:187], v[102:103], v[138:139], v[186:187] op_sel:[0,1,0] op_sel_hi:[1,1,1]
	v_pk_fma_f32 v[190:191], v[102:103], v[158:159], v[190:191] op_sel:[0,1,0] op_sel_hi:[1,1,1]
	v_pk_fma_f32 v[184:185], v[104:105], v[140:141], v[184:185] op_sel:[0,0,0] op_sel_hi:[1,0,1]
	v_pk_fma_f32 v[188:189], v[104:105], v[160:161], v[188:189] op_sel:[0,0,0] op_sel_hi:[1,0,1]
	v_pk_fma_f32 v[186:187], v[106:107], v[140:141], v[186:187] op_sel:[0,1,0] op_sel_hi:[1,1,1]
	v_pk_fma_f32 v[190:191], v[106:107], v[160:161], v[190:191] op_sel:[0,1,0] op_sel_hi:[1,1,1]
	v_pk_fma_f32 v[184:185], v[108:109], v[142:143], v[184:185] op_sel:[0,0,0] op_sel_hi:[1,0,1]
	v_pk_fma_f32 v[188:189], v[108:109], v[162:163], v[188:189] op_sel:[0,0,0] op_sel_hi:[1,0,1]
	v_pk_fma_f32 v[186:187], v[110:111], v[142:143], v[186:187] op_sel:[0,1,0] op_sel_hi:[1,1,1]
	v_pk_fma_f32 v[190:191], v[110:111], v[162:163], v[190:191] op_sel:[0,1,0] op_sel_hi:[1,1,1]
	v_pk_add_f32 v[192:193], v[184:185], v[186:187]
	v_pk_add_f32 v[194:195], v[188:189], v[190:191]
	ds_read_b128 v[120:123], v44 offset:3328
	ds_read_b128 v[124:127], v44 offset:3344
	ds_read_b128 v[128:131], v44 offset:3840
	ds_read_b128 v[132:135], v44 offset:3856
	ds_read_b128 v[136:139], v44 offset:4096
	ds_read_b128 v[140:143], v44 offset:4112
	ds_read_b64 v[144:145], v46 offset:3072
	ds_read_b128 v[156:159], v44 offset:5120
	ds_read_b128 v[160:163], v44 offset:5136
	s_waitcnt lgkmcnt(9)
	v_add_f32_dpp v192, v192, v192 quad_perm:[1,0,3,2] row_mask:0xf bank_mask:0xf bound_ctrl:1
	v_add_f32_dpp v193, v193, v193 quad_perm:[1,0,3,2] row_mask:0xf bank_mask:0xf bound_ctrl:1
	v_add_f32_dpp v194, v194, v194 quad_perm:[1,0,3,2] row_mask:0xf bank_mask:0xf bound_ctrl:1
	v_add_f32_dpp v195, v195, v195 quad_perm:[1,0,3,2] row_mask:0xf bank_mask:0xf bound_ctrl:1
	v_pk_fma_f32 v[96:97], v[146:147], v[70:71], v[96:97] op_sel:[0,0,0] op_sel_hi:[1,0,1]
	v_pk_fma_f32 v[98:99], v[146:147], v[70:71], v[98:99] op_sel:[0,1,0] op_sel_hi:[1,1,1]
	v_pk_fma_f32 v[100:101], v[146:147], v[72:73], v[100:101] op_sel:[0,0,0] op_sel_hi:[1,0,1]
	v_add_f32_dpp v192, v192, v192 quad_perm:[2,3,0,1] row_mask:0xf bank_mask:0xf bound_ctrl:1
	v_add_f32_dpp v193, v193, v193 quad_perm:[2,3,0,1] row_mask:0xf bank_mask:0xf bound_ctrl:1
	v_add_f32_dpp v194, v194, v194 quad_perm:[2,3,0,1] row_mask:0xf bank_mask:0xf bound_ctrl:1
	v_add_f32_dpp v195, v195, v195 quad_perm:[2,3,0,1] row_mask:0xf bank_mask:0xf bound_ctrl:1
	v_pk_fma_f32 v[102:103], v[146:147], v[72:73], v[102:103] op_sel:[0,1,0] op_sel_hi:[1,1,1]
	v_pk_fma_f32 v[104:105], v[146:147], v[74:75], v[104:105] op_sel:[0,0,0] op_sel_hi:[1,0,1]
	v_pk_fma_f32 v[106:107], v[146:147], v[74:75], v[106:107] op_sel:[0,1,0] op_sel_hi:[1,1,1]
	v_add_f32_dpp v192, v192, v192 row_half_mirror row_mask:0xf bank_mask:0xf bound_ctrl:1
	v_add_f32_dpp v193, v193, v193 row_half_mirror row_mask:0xf bank_mask:0xf bound_ctrl:1
	v_add_f32_dpp v194, v194, v194 row_half_mirror row_mask:0xf bank_mask:0xf bound_ctrl:1
	v_add_f32_dpp v195, v195, v195 row_half_mirror row_mask:0xf bank_mask:0xf bound_ctrl:1
; #define LAS __attribute__((address_space(3)))
; __device__ __forceinline__ float red8(float x) { x += dpp_mov<0xB1>(x); x += dpp_mov<0x4E>(x); x += dpp_mov<0x141>(x); return x; }
; __device__ __forceinline__ void scan_phase(const KP& P, LAS unsigned char* lds, const int tid, const int bx, const int G) {
;     ...
;             for (int s = 0; s < 32; ++s) {
;                 const LAS float* p = cb + s * 384;
;                 const f32x4 w0 = *(const LAS f32x4*)(p), w1 = *(const LAS f32x4*)(p + 4);
;                 const f32x4 k0 = *(const LAS f32x4*)(p + 64), k1 = *(const LAS f32x4*)(p + 68);
;                 const f32x4 a0 = *(const LAS f32x4*)(p + 128), a1 = *(const LAS f32x4*)(p + 132);
;                 const f32x4 b0 = *(const LAS f32x4*)(p + 192), b1 = *(const LAS f32x4*)(p + 196);
;                 const f32x4 r0 = *(const LAS f32x4*)(p + 256), r1 = *(const LAS f32x4*)(p + 260);
;                 const float vv = buf[(c & 1) * 12288 + s * 384 + 320 + v];
;                 f32x2 sa2 = S[0] * (f32x2){a0.x, a0.y};
;                 sa2 += S[1] * (f32x2){a0.z, a0.w}; sa2 += S[2] * (f32x2){a1.x, a1.y}; sa2 += S[3] * (f32x2){a1.z, a1.w};
;                 const float sa = red8(sa2.x + sa2.y);
;                 const f32x2 sav = {sa, sa}, vv2 = {vv, vv};
;                 S[0] = S[0] * (f32x2){w0.x, w0.y} + sav * (f32x2){b0.x, b0.y} + vv2 * (f32x2){k0.x, k0.y};
;                 S[1] = S[1] * (f32x2){w0.z, w0.w} + sav * (f32x2){b0.z, b0.w} + vv2 * (f32x2){k0.z, k0.w};
;                 S[2] = S[2] * (f32x2){w1.x, w1.y} + sav * (f32x2){b1.x, b1.y} + vv2 * (f32x2){k1.x, k1.y};
;                 S[3] = S[3] * (f32x2){w1.z, w1.w} + sav * (f32x2){b1.z, b1.w} + vv2 * (f32x2){k1.z, k1.w};
;                 f32x2 y2 = S[0] * (f32x2){r0.x, r0.y};
;                 y2 += S[1] * (f32x2){r0.z, r0.w}; y2 += S[2] * (f32x2){r1.x, r1.y}; y2 += S[3] * (f32x2){r1.z, r1.w};
;                 const float y = red8(y2.x + y2.y);
;                 if (kc == 0) ybuf[s * 64 + v] = y;
	v_pk_fma_f32 v[108:109], v[146:147], v[76:77], v[108:109] op_sel:[0,0,0] op_sel_hi:[1,0,1]
	s_mov_b64 exec, s[10:11]
	ds_write_b64 v45, v[192:193] offset:0
	s_mov_b64 exec, s[0:1]
	v_pk_fma_f32 v[110:111], v[146:147], v[76:77], v[110:111] op_sel:[0,1,0] op_sel_hi:[1,1,1]
	s_nop 0
	v_pk_fma_f32 v[96:97], v[194:195], v[78:79], v[96:97] op_sel:[0,0,0] op_sel_hi:[1,0,1]
	v_pk_fma_f32 v[98:99], v[194:195], v[78:79], v[98:99] op_sel:[0,1,0] op_sel_hi:[1,1,1]
	v_pk_fma_f32 v[100:101], v[194:195], v[80:81], v[100:101] op_sel:[0,0,0] op_sel_hi:[1,0,1]
	v_pk_fma_f32 v[102:103], v[194:195], v[80:81], v[102:103] op_sel:[0,1,0] op_sel_hi:[1,1,1]
	v_pk_fma_f32 v[104:105], v[194:195], v[82:83], v[104:105] op_sel:[0,0,0] op_sel_hi:[1,0,1]
	v_pk_fma_f32 v[106:107], v[194:195], v[82:83], v[106:107] op_sel:[0,1,0] op_sel_hi:[1,1,1]
	v_pk_fma_f32 v[108:109], v[194:195], v[84:85], v[108:109] op_sel:[0,0,0] op_sel_hi:[1,0,1]
	v_pk_fma_f32 v[110:111], v[194:195], v[84:85], v[110:111] op_sel:[0,1,0] op_sel_hi:[1,1,1]
	v_pk_mul_f32 v[184:185], v[96:97], v[86:87] op_sel:[0,0] op_sel_hi:[1,0]
	v_pk_mul_f32 v[188:189], v[96:97], v[148:149] op_sel:[0,0] op_sel_hi:[1,0]
	v_pk_mul_f32 v[186:187], v[98:99], v[86:87] op_sel:[0,1] op_sel_hi:[1,1]
	v_pk_mul_f32 v[190:191], v[98:99], v[148:149] op_sel:[0,1] op_sel_hi:[1,1]
	v_pk_fma_f32 v[184:185], v[100:101], v[88:89], v[184:185] op_sel:[0,0,0] op_sel_hi:[1,0,1]
	v_pk_fma_f32 v[188:189], v[100:101], v[150:151], v[188:189] op_sel:[0,0,0] op_sel_hi:[1,0,1]
	v_pk_fma_f32 v[186:187], v[102:103], v[88:89], v[186:187] op_sel:[0,1,0] op_sel_hi:[1,1,1]
	v_pk_fma_f32 v[190:191], v[102:103], v[150:151], v[190:191] op_sel:[0,1,0] op_sel_hi:[1,1,1]
	v_pk_fma_f32 v[184:185], v[104:105], v[90:91], v[184:185] op_sel:[0,0,0] op_sel_hi:[1,0,1]
	v_pk_fma_f32 v[188:189], v[104:105], v[152:153], v[188:189] op_sel:[0,0,0] op_sel_hi:[1,0,1]
	v_pk_fma_f32 v[186:187], v[106:107], v[90:91], v[186:187] op_sel:[0,1,0] op_sel_hi:[1,1,1]
	v_pk_fma_f32 v[190:191], v[106:107], v[152:153], v[190:191] op_sel:[0,1,0] op_sel_hi:[1,1,1]
	v_pk_fma_f32 v[184:185], v[108:109], v[92:93], v[184:185] op_sel:[0,0,0] op_sel_hi:[1,0,1]
	v_pk_fma_f32 v[188:189], v[108:109], v[154:155], v[188:189] op_sel:[0,0,0] op_sel_hi:[1,0,1]
	v_pk_fma_f32 v[186:187], v[110:111], v[92:93], v[186:187] op_sel:[0,1,0] op_sel_hi:[1,1,1]
	v_pk_fma_f32 v[190:191], v[110:111], v[154:155], v[190:191] op_sel:[0,1,0] op_sel_hi:[1,1,1]
	v_pk_add_f32 v[192:193], v[184:185], v[186:187]
	v_pk_add_f32 v[194:195], v[188:189], v[190:191]
	ds_read_b128 v[70:73], v44 offset:4864
	ds_read_b128 v[74:77], v44 offset:4880
	ds_read_b128 v[78:81], v44 offset:5376
	ds_read_b128 v[82:85], v44 offset:5392
	ds_read_b128 v[86:89], v44 offset:5632
	ds_read_b128 v[90:93], v44 offset:5648
	ds_read_b64 v[146:147], v46 offset:4608
	ds_read_b128 v[148:151], v44 offset:6656
	ds_read_b128 v[152:155], v44 offset:6672
	s_waitcnt lgkmcnt(10)
	v_add_f32_dpp v192, v192, v192 quad_perm:[1,0,3,2] row_mask:0xf bank_mask:0xf bound_ctrl:1
	v_add_f32_dpp v193, v193, v193 quad_perm:[1,0,3,2] row_mask:0xf bank_mask:0xf bound_ctrl:1
	v_add_f32_dpp v194, v194, v194 quad_perm:[1,0,3,2] row_mask:0xf bank_mask:0xf bound_ctrl:1
	v_add_f32_dpp v195, v195, v195 quad_perm:[1,0,3,2] row_mask:0xf bank_mask:0xf bound_ctrl:1
	v_pk_fma_f32 v[96:97], v[144:145], v[120:121], v[96:97] op_sel:[0,0,0] op_sel_hi:[1,0,1]
	v_pk_fma_f32 v[98:99], v[144:145], v[120:121], v[98:99] op_sel:[0,1,0] op_sel_hi:[1,1,1]
	v_pk_fma_f32 v[100:101], v[144:145], v[122:123], v[100:101] op_sel:[0,0,0] op_sel_hi:[1,0,1]
	v_add_f32_dpp v192, v192, v192 quad_perm:[2,3,0,1] row_mask:0xf bank_mask:0xf bound_ctrl:1
	v_add_f32_dpp v193, v193, v193 quad_perm:[2,3,0,1] row_mask:0xf bank_mask:0xf bound_ctrl:1
	v_add_f32_dpp v194, v194, v194 quad_perm:[2,3,0,1] row_mask:0xf bank_mask:0xf bound_ctrl:1
	v_add_f32_dpp v195, v195, v195 quad_perm:[2,3,0,1] row_mask:0xf bank_mask:0xf bound_ctrl:1
	v_pk_fma_f32 v[102:103], v[144:145], v[122:123], v[102:103] op_sel:[0,1,0] op_sel_hi:[1,1,1]
	v_pk_fma_f32 v[104:105], v[144:145], v[124:125], v[104:105] op_sel:[0,0,0] op_sel_hi:[1,0,1]
	v_pk_fma_f32 v[106:107], v[144:145], v[124:125], v[106:107] op_sel:[0,1,0] op_sel_hi:[1,1,1]
	v_add_f32_dpp v192, v192, v192 row_half_mirror row_mask:0xf bank_mask:0xf bound_ctrl:1
	v_add_f32_dpp v193, v193, v193 row_half_mirror row_mask:0xf bank_mask:0xf bound_ctrl:1
	v_add_f32_dpp v194, v194, v194 row_half_mirror row_mask:0xf bank_mask:0xf bound_ctrl:1
	v_add_f32_dpp v195, v195, v195 row_half_mirror row_mask:0xf bank_mask:0xf bound_ctrl:1
	v_pk_fma_f32 v[108:109], v[144:145], v[126:127], v[108:109] op_sel:[0,0,0] op_sel_hi:[1,0,1]
	s_mov_b64 exec, s[10:11]
	ds_write_b64 v45, v[192:193] offset:256
	s_mov_b64 exec, s[0:1]
	v_pk_fma_f32 v[110:111], v[144:145], v[126:127], v[110:111] op_sel:[0,1,0] op_sel_hi:[1,1,1]
	s_nop 0
	v_pk_fma_f32 v[96:97], v[194:195], v[128:129], v[96:97] op_sel:[0,0,0] op_sel_hi:[1,0,1]
	v_pk_fma_f32 v[98:99], v[194:195], v[128:129], v[98:99] op_sel:[0,1,0] op_sel_hi:[1,1,1]
	v_pk_fma_f32 v[100:101], v[194:195], v[130:131], v[100:101] op_sel:[0,0,0] op_sel_hi:[1,0,1]
	v_pk_fma_f32 v[102:103], v[194:195], v[130:131], v[102:103] op_sel:[0,1,0] op_sel_hi:[1,1,1]
	v_pk_fma_f32 v[104:105], v[194:195], v[132:133], v[104:105] op_sel:[0,0,0] op_sel_hi:[1,0,1]
	v_pk_fma_f32 v[106:107], v[194:195], v[132:133], v[106:107] op_sel:[0,1,0] op_sel_hi:[1,1,1]
	v_pk_fma_f32 v[108:109], v[194:195], v[134:135], v[108:109] op_sel:[0,0,0] op_sel_hi:[1,0,1]
	v_pk_fma_f32 v[110:111], v[194:195], v[134:135], v[110:111] op_sel:[0,1,0] op_sel_hi:[1,1,1]
	v_pk_mul_f32 v[184:185], v[96:97], v[136:137] op_sel:[0,0] op_sel_hi:[1,0]
; #define LAS __attribute__((address_space(3)))
; __device__ __forceinline__ float red8(float x) { x += dpp_mov<0xB1>(x); x += dpp_mov<0x4E>(x); x += dpp_mov<0x141>(x); return x; }
; __device__ __forceinline__ void scan_phase(const KP& P, LAS unsigned char* lds, const int tid, const int bx, const int G) {
;     ...
;             for (int s = 0; s < 32; ++s) {
;                 const LAS float* p = cb + s * 384;
;                 const f32x4 w0 = *(const LAS f32x4*)(p), w1 = *(const LAS f32x4*)(p + 4);
;                 const f32x4 k0 = *(const LAS f32x4*)(p + 64), k1 = *(const LAS f32x4*)(p + 68);
;                 const f32x4 a0 = *(const LAS f32x4*)(p + 128), a1 = *(const LAS f32x4*)(p + 132);
;                 const f32x4 b0 = *(const LAS f32x4*)(p + 192), b1 = *(const LAS f32x4*)(p + 196);
;                 const f32x4 r0 = *(const LAS f32x4*)(p + 256), r1 = *(const LAS f32x4*)(p + 260);
;                 const float vv = buf[(c & 1) * 12288 + s * 384 + 320 + v];
;                 f32x2 sa2 = S[0] * (f32x2){a0.x, a0.y};
;                 sa2 += S[1] * (f32x2){a0.z, a0.w}; sa2 += S[2] * (f32x2){a1.x, a1.y}; sa2 += S[3] * (f32x2){a1.z, a1.w};
;                 const float sa = red8(sa2.x + sa2.y);
;                 const f32x2 sav = {sa, sa}, vv2 = {vv, vv};
;                 S[0] = S[0] * (f32x2){w0.x, w0.y} + sav * (f32x2){b0.x, b0.y} + vv2 * (f32x2){k0.x, k0.y};
;                 S[1] = S[1] * (f32x2){w0.z, w0.w} + sav * (f32x2){b0.z, b0.w} + vv2 * (f32x2){k0.z, k0.w};
;                 S[2] = S[2] * (f32x2){w1.x, w1.y} + sav * (f32x2){b1.x, b1.y} + vv2 * (f32x2){k1.x, k1.y};
;                 S[3] = S[3] * (f32x2){w1.z, w1.w} + sav * (f32x2){b1.z, b1.w} + vv2 * (f32x2){k1.z, k1.w};
;                 f32x2 y2 = S[0] * (f32x2){r0.x, r0.y};
;                 y2 += S[1] * (f32x2){r0.z, r0.w}; y2 += S[2] * (f32x2){r1.x, r1.y}; y2 += S[3] * (f32x2){r1.z, r1.w};
;                 const float y = red8(y2.x + y2.y);
;                 if (kc == 0) ybuf[s * 64 + v] = y;
	v_pk_mul_f32 v[188:189], v[96:97], v[156:157] op_sel:[0,0] op_sel_hi:[1,0]
	v_pk_mul_f32 v[186:187], v[98:99], v[136:137] op_sel:[0,1] op_sel_hi:[1,1]
	v_pk_mul_f32 v[190:191], v[98:99], v[156:157] op_sel:[0,1] op_sel_hi:[1,1]
	v_pk_fma_f32 v[184:185], v[100:101], v[138:139], v[184:185] op_sel:[0,0,0] op_sel_hi:[1,0,1]
	v_pk_fma_f32 v[188:189], v[100:101], v[158:159], v[188:189] op_sel:[0,0,0] op_sel_hi:[1,0,1]
	v_pk_fma_f32 v[186:187], v[102:103], v[138:139], v[186:187] op_sel:[0,1,0] op_sel_hi:[1,1,1]
	v_pk_fma_f32 v[190:191], v[102:103], v[158:159], v[190:191] op_sel:[0,1,0] op_sel_hi:[1,1,1]
	v_pk_fma_f32 v[184:185], v[104:105], v[140:141], v[184:185] op_sel:[0,0,0] op_sel_hi:[1,0,1]
	v_pk_fma_f32 v[188:189], v[104:105], v[160:161], v[188:189] op_sel:[0,0,0] op_sel_hi:[1,0,1]
	v_pk_fma_f32 v[186:187], v[106:107], v[140:141], v[186:187] op_sel:[0,1,0] op_sel_hi:[1,1,1]
	v_pk_fma_f32 v[190:191], v[106:107], v[160:161], v[190:191] op_sel:[0,1,0] op_sel_hi:[1,1,1]
	v_pk_fma_f32 v[184:185], v[108:109], v[142:143], v[184:185] op_sel:[0,0,0] op_sel_hi:[1,0,1]
	v_pk_fma_f32 v[188:189], v[108:109], v[162:163], v[188:189] op_sel:[0,0,0] op_sel_hi:[1,0,1]
	v_pk_fma_f32 v[186:187], v[110:111], v[142:143], v[186:187] op_sel:[0,1,0] op_sel_hi:[1,1,1]
	v_pk_fma_f32 v[190:191], v[110:111], v[162:163], v[190:191] op_sel:[0,1,0] op_sel_hi:[1,1,1]
	v_pk_add_f32 v[192:193], v[184:185], v[186:187]
	v_pk_add_f32 v[194:195], v[188:189], v[190:191]
	ds_read_b128 v[120:123], v44 offset:6400
	ds_read_b128 v[124:127], v44 offset:6416
	ds_read_b128 v[128:131], v44 offset:6912
	ds_read_b128 v[132:135], v44 offset:6928
	ds_read_b128 v[136:139], v44 offset:7168
	ds_read_b128 v[140:143], v44 offset:7184
	ds_read_b64 v[144:145], v46 offset:6144
	ds_read_b128 v[156:159], v44 offset:8192
	ds_read_b128 v[160:163], v44 offset:8208
	s_waitcnt lgkmcnt(10)
	v_add_f32_dpp v192, v192, v192 quad_perm:[1,0,3,2] row_mask:0xf bank_mask:0xf bound_ctrl:1
	v_add_f32_dpp v193, v193, v193 quad_perm:[1,0,3,2] row_mask:0xf bank_mask:0xf bound_ctrl:1
	v_add_f32_dpp v194, v194, v194 quad_perm:[1,0,3,2] row_mask:0xf bank_mask:0xf bound_ctrl:1
	v_add_f32_dpp v195, v195, v195 quad_perm:[1,0,3,2] row_mask:0xf bank_mask:0xf bound_ctrl:1
	v_pk_fma_f32 v[96:97], v[146:147], v[70:71], v[96:97] op_sel:[0,0,0] op_sel_hi:[1,0,1]
	v_pk_fma_f32 v[98:99], v[146:147], v[70:71], v[98:99] op_sel:[0,1,0] op_sel_hi:[1,1,1]
	v_pk_fma_f32 v[100:101], v[146:147], v[72:73], v[100:101] op_sel:[0,0,0] op_sel_hi:[1,0,1]
	v_add_f32_dpp v192, v192, v192 quad_perm:[2,3,0,1] row_mask:0xf bank_mask:0xf bound_ctrl:1
	v_add_f32_dpp v193, v193, v193 quad_perm:[2,3,0,1] row_mask:0xf bank_mask:0xf bound_ctrl:1
	v_add_f32_dpp v194, v194, v194 quad_perm:[2,3,0,1] row_mask:0xf bank_mask:0xf bound_ctrl:1
	v_add_f32_dpp v195, v195, v195 quad_perm:[2,3,0,1] row_mask:0xf bank_mask:0xf bound_ctrl:1
	v_pk_fma_f32 v[102:103], v[146:147], v[72:73], v[102:103] op_sel:[0,1,0] op_sel_hi:[1,1,1]
	v_pk_fma_f32 v[104:105], v[146:147], v[74:75], v[104:105] op_sel:[0,0,0] op_sel_hi:[1,0,1]
	v_pk_fma_f32 v[106:107], v[146:147], v[74:75], v[106:107] op_sel:[0,1,0] op_sel_hi:[1,1,1]
	v_add_f32_dpp v192, v192, v192 row_half_mirror row_mask:0xf bank_mask:0xf bound_ctrl:1
	v_add_f32_dpp v193, v193, v193 row_half_mirror row_mask:0xf bank_mask:0xf bound_ctrl:1
	v_add_f32_dpp v194, v194, v194 row_half_mirror row_mask:0xf bank_mask:0xf bound_ctrl:1
	v_add_f32_dpp v195, v195, v195 row_half_mirror row_mask:0xf bank_mask:0xf bound_ctrl:1
	v_pk_fma_f32 v[108:109], v[146:147], v[76:77], v[108:109] op_sel:[0,0,0] op_sel_hi:[1,0,1]
	s_mov_b64 exec, s[10:11]
	ds_write_b64 v45, v[192:193] offset:512
	s_mov_b64 exec, s[0:1]
	v_pk_fma_f32 v[110:111], v[146:147], v[76:77], v[110:111] op_sel:[0,1,0] op_sel_hi:[1,1,1]
	s_nop 0
	v_pk_fma_f32 v[96:97], v[194:195], v[78:79], v[96:97] op_sel:[0,0,0] op_sel_hi:[1,0,1]
	v_pk_fma_f32 v[98:99], v[194:195], v[78:79], v[98:99] op_sel:[0,1,0] op_sel_hi:[1,1,1]
	v_pk_fma_f32 v[100:101], v[194:195], v[80:81], v[100:101] op_sel:[0,0,0] op_sel_hi:[1,0,1]
	v_pk_fma_f32 v[102:103], v[194:195], v[80:81], v[102:103] op_sel:[0,1,0] op_sel_hi:[1,1,1]
	v_pk_fma_f32 v[104:105], v[194:195], v[82:83], v[104:105] op_sel:[0,0,0] op_sel_hi:[1,0,1]
	v_pk_fma_f32 v[106:107], v[194:195], v[82:83], v[106:107] op_sel:[0,1,0] op_sel_hi:[1,1,1]
	v_pk_fma_f32 v[108:109], v[194:195], v[84:85], v[108:109] op_sel:[0,0,0] op_sel_hi:[1,0,1]
	v_pk_fma_f32 v[110:111], v[194:195], v[84:85], v[110:111] op_sel:[0,1,0] op_sel_hi:[1,1,1]
	v_pk_mul_f32 v[184:185], v[96:97], v[86:87] op_sel:[0,0] op_sel_hi:[1,0]
	v_pk_mul_f32 v[188:189], v[96:97], v[148:149] op_sel:[0,0] op_sel_hi:[1,0]
	v_pk_mul_f32 v[186:187], v[98:99], v[86:87] op_sel:[0,1] op_sel_hi:[1,1]
	v_pk_mul_f32 v[190:191], v[98:99], v[148:149] op_sel:[0,1] op_sel_hi:[1,1]
	v_pk_fma_f32 v[184:185], v[100:101], v[88:89], v[184:185] op_sel:[0,0,0] op_sel_hi:[1,0,1]
	v_pk_fma_f32 v[188:189], v[100:101], v[150:151], v[188:189] op_sel:[0,0,0] op_sel_hi:[1,0,1]
	v_pk_fma_f32 v[186:187], v[102:103], v[88:89], v[186:187] op_sel:[0,1,0] op_sel_hi:[1,1,1]
	v_pk_fma_f32 v[190:191], v[102:103], v[150:151], v[190:191] op_sel:[0,1,0] op_sel_hi:[1,1,1]
	v_pk_fma_f32 v[184:185], v[104:105], v[90:91], v[184:185] op_sel:[0,0,0] op_sel_hi:[1,0,1]
	v_pk_fma_f32 v[188:189], v[104:105], v[152:153], v[188:189] op_sel:[0,0,0] op_sel_hi:[1,0,1]
	v_pk_fma_f32 v[186:187], v[106:107], v[90:91], v[186:187] op_sel:[0,1,0] op_sel_hi:[1,1,1]
	v_pk_fma_f32 v[190:191], v[106:107], v[152:153], v[190:191] op_sel:[0,1,0] op_sel_hi:[1,1,1]
	v_pk_fma_f32 v[184:185], v[108:109], v[92:93], v[184:185] op_sel:[0,0,0] op_sel_hi:[1,0,1]
	v_pk_fma_f32 v[188:189], v[108:109], v[154:155], v[188:189] op_sel:[0,0,0] op_sel_hi:[1,0,1]
	v_pk_fma_f32 v[186:187], v[110:111], v[92:93], v[186:187] op_sel:[0,1,0] op_sel_hi:[1,1,1]
	v_pk_fma_f32 v[190:191], v[110:111], v[154:155], v[190:191] op_sel:[0,1,0] op_sel_hi:[1,1,1]
	v_pk_add_f32 v[192:193], v[184:185], v[186:187]
	v_pk_add_f32 v[194:195], v[188:189], v[190:191]
	ds_read_b128 v[70:73], v44 offset:7936
	ds_read_b128 v[74:77], v44 offset:7952
	ds_read_b128 v[78:81], v44 offset:8448
	ds_read_b128 v[82:85], v44 offset:8464
	ds_read_b128 v[86:89], v44 offset:8704
	ds_read_b128 v[90:93], v44 offset:8720
	ds_read_b64 v[146:147], v46 offset:7680
	ds_read_b128 v[148:151], v44 offset:9728
	ds_read_b128 v[152:155], v44 offset:9744
	s_waitcnt lgkmcnt(10)
; #define LAS __attribute__((address_space(3)))
; __device__ __forceinline__ float red8(float x) { x += dpp_mov<0xB1>(x); x += dpp_mov<0x4E>(x); x += dpp_mov<0x141>(x); return x; }
; __device__ __forceinline__ void scan_phase(const KP& P, LAS unsigned char* lds, const int tid, const int bx, const int G) {
;     ...
;             for (int s = 0; s < 32; ++s) {
;                 const LAS float* p = cb + s * 384;
;                 const f32x4 w0 = *(const LAS f32x4*)(p), w1 = *(const LAS f32x4*)(p + 4);
;                 const f32x4 k0 = *(const LAS f32x4*)(p + 64), k1 = *(const LAS f32x4*)(p + 68);
;                 const f32x4 a0 = *(const LAS f32x4*)(p + 128), a1 = *(const LAS f32x4*)(p + 132);
;                 const f32x4 b0 = *(const LAS f32x4*)(p + 192), b1 = *(const LAS f32x4*)(p + 196);
;                 const f32x4 r0 = *(const LAS f32x4*)(p + 256), r1 = *(const LAS f32x4*)(p + 260);
;                 const float vv = buf[(c & 1) * 12288 + s * 384 + 320 + v];
;                 f32x2 sa2 = S[0] * (f32x2){a0.x, a0.y};
;                 sa2 += S[1] * (f32x2){a0.z, a0.w}; sa2 += S[2] * (f32x2){a1.x, a1.y}; sa2 += S[3] * (f32x2){a1.z, a1.w};
;                 const float sa = red8(sa2.x + sa2.y);
;                 const f32x2 sav = {sa, sa}, vv2 = {vv, vv};
;                 S[0] = S[0] * (f32x2){w0.x, w0.y} + sav * (f32x2){b0.x, b0.y} + vv2 * (f32x2){k0.x, k0.y};
;                 S[1] = S[1] * (f32x2){w0.z, w0.w} + sav * (f32x2){b0.z, b0.w} + vv2 * (f32x2){k0.z, k0.w};
;                 S[2] = S[2] * (f32x2){w1.x, w1.y} + sav * (f32x2){b1.x, b1.y} + vv2 * (f32x2){k1.x, k1.y};
;                 S[3] = S[3] * (f32x2){w1.z, w1.w} + sav * (f32x2){b1.z, b1.w} + vv2 * (f32x2){k1.z, k1.w};
;                 f32x2 y2 = S[0] * (f32x2){r0.x, r0.y};
;                 y2 += S[1] * (f32x2){r0.z, r0.w}; y2 += S[2] * (f32x2){r1.x, r1.y}; y2 += S[3] * (f32x2){r1.z, r1.w};
;                 const float y = red8(y2.x + y2.y);
;                 if (kc == 0) ybuf[s * 64 + v] = y;
	v_add_f32_dpp v192, v192, v192 quad_perm:[1,0,3,2] row_mask:0xf bank_mask:0xf bound_ctrl:1
	v_add_f32_dpp v193, v193, v193 quad_perm:[1,0,3,2] row_mask:0xf bank_mask:0xf bound_ctrl:1
	v_add_f32_dpp v194, v194, v194 quad_perm:[1,0,3,2] row_mask:0xf bank_mask:0xf bound_ctrl:1
	v_add_f32_dpp v195, v195, v195 quad_perm:[1,0,3,2] row_mask:0xf bank_mask:0xf bound_ctrl:1
	v_pk_fma_f32 v[96:97], v[144:145], v[120:121], v[96:97] op_sel:[0,0,0] op_sel_hi:[1,0,1]
	v_pk_fma_f32 v[98:99], v[144:145], v[120:121], v[98:99] op_sel:[0,1,0] op_sel_hi:[1,1,1]
	v_pk_fma_f32 v[100:101], v[144:145], v[122:123], v[100:101] op_sel:[0,0,0] op_sel_hi:[1,0,1]
	v_add_f32_dpp v192, v192, v192 quad_perm:[2,3,0,1] row_mask:0xf bank_mask:0xf bound_ctrl:1
	v_add_f32_dpp v193, v193, v193 quad_perm:[2,3,0,1] row_mask:0xf bank_mask:0xf bound_ctrl:1
	v_add_f32_dpp v194, v194, v194 quad_perm:[2,3,0,1] row_mask:0xf bank_mask:0xf bound_ctrl:1
	v_add_f32_dpp v195, v195, v195 quad_perm:[2,3,0,1] row_mask:0xf bank_mask:0xf bound_ctrl:1
	v_pk_fma_f32 v[102:103], v[144:145], v[122:123], v[102:103] op_sel:[0,1,0] op_sel_hi:[1,1,1]
	v_pk_fma_f32 v[104:105], v[144:145], v[124:125], v[104:105] op_sel:[0,0,0] op_sel_hi:[1,0,1]
	v_pk_fma_f32 v[106:107], v[144:145], v[124:125], v[106:107] op_sel:[0,1,0] op_sel_hi:[1,1,1]
	v_add_f32_dpp v192, v192, v192 row_half_mirror row_mask:0xf bank_mask:0xf bound_ctrl:1
	v_add_f32_dpp v193, v193, v193 row_half_mirror row_mask:0xf bank_mask:0xf bound_ctrl:1
	v_add_f32_dpp v194, v194, v194 row_half_mirror row_mask:0xf bank_mask:0xf bound_ctrl:1
	v_add_f32_dpp v195, v195, v195 row_half_mirror row_mask:0xf bank_mask:0xf bound_ctrl:1
	v_pk_fma_f32 v[108:109], v[144:145], v[126:127], v[108:109] op_sel:[0,0,0] op_sel_hi:[1,0,1]
	s_mov_b64 exec, s[10:11]
	ds_write_b64 v45, v[192:193] offset:768
	s_mov_b64 exec, s[0:1]
	v_pk_fma_f32 v[110:111], v[144:145], v[126:127], v[110:111] op_sel:[0,1,0] op_sel_hi:[1,1,1]
	s_nop 0
	v_pk_fma_f32 v[96:97], v[194:195], v[128:129], v[96:97] op_sel:[0,0,0] op_sel_hi:[1,0,1]
	v_pk_fma_f32 v[98:99], v[194:195], v[128:129], v[98:99] op_sel:[0,1,0] op_sel_hi:[1,1,1]
	v_pk_fma_f32 v[100:101], v[194:195], v[130:131], v[100:101] op_sel:[0,0,0] op_sel_hi:[1,0,1]
	v_pk_fma_f32 v[102:103], v[194:195], v[130:131], v[102:103] op_sel:[0,1,0] op_sel_hi:[1,1,1]
	v_pk_fma_f32 v[104:105], v[194:195], v[132:133], v[104:105] op_sel:[0,0,0] op_sel_hi:[1,0,1]
	v_pk_fma_f32 v[106:107], v[194:195], v[132:133], v[106:107] op_sel:[0,1,0] op_sel_hi:[1,1,1]
	v_pk_fma_f32 v[108:109], v[194:195], v[134:135], v[108:109] op_sel:[0,0,0] op_sel_hi:[1,0,1]
	v_pk_fma_f32 v[110:111], v[194:195], v[134:135], v[110:111] op_sel:[0,1,0] op_sel_hi:[1,1,1]
	v_pk_mul_f32 v[184:185], v[96:97], v[136:137] op_sel:[0,0] op_sel_hi:[1,0]
	v_pk_mul_f32 v[188:189], v[96:97], v[156:157] op_sel:[0,0] op_sel_hi:[1,0]
	v_pk_mul_f32 v[186:187], v[98:99], v[136:137] op_sel:[0,1] op_sel_hi:[1,1]
	v_pk_mul_f32 v[190:191], v[98:99], v[156:157] op_sel:[0,1] op_sel_hi:[1,1]
	v_pk_fma_f32 v[184:185], v[100:101], v[138:139], v[184:185] op_sel:[0,0,0] op_sel_hi:[1,0,1]
	v_pk_fma_f32 v[188:189], v[100:101], v[158:159], v[188:189] op_sel:[0,0,0] op_sel_hi:[1,0,1]
	v_pk_fma_f32 v[186:187], v[102:103], v[138:139], v[186:187] op_sel:[0,1,0] op_sel_hi:[1,1,1]
	v_pk_fma_f32 v[190:191], v[102:103], v[158:159], v[190:191] op_sel:[0,1,0] op_sel_hi:[1,1,1]
	v_pk_fma_f32 v[184:185], v[104:105], v[140:141], v[184:185] op_sel:[0,0,0] op_sel_hi:[1,0,1]
	v_pk_fma_f32 v[188:189], v[104:105], v[160:161], v[188:189] op_sel:[0,0,0] op_sel_hi:[1,0,1]
	v_pk_fma_f32 v[186:187], v[106:107], v[140:141], v[186:187] op_sel:[0,1,0] op_sel_hi:[1,1,1]
	v_pk_fma_f32 v[190:191], v[106:107], v[160:161], v[190:191] op_sel:[0,1,0] op_sel_hi:[1,1,1]
	v_pk_fma_f32 v[184:185], v[108:109], v[142:143], v[184:185] op_sel:[0,0,0] op_sel_hi:[1,0,1]
	v_pk_fma_f32 v[188:189], v[108:109], v[162:163], v[188:189] op_sel:[0,0,0] op_sel_hi:[1,0,1]
	v_pk_fma_f32 v[186:187], v[110:111], v[142:143], v[186:187] op_sel:[0,1,0] op_sel_hi:[1,1,1]
	v_pk_fma_f32 v[190:191], v[110:111], v[162:163], v[190:191] op_sel:[0,1,0] op_sel_hi:[1,1,1]
	v_pk_add_f32 v[192:193], v[184:185], v[186:187]
	v_pk_add_f32 v[194:195], v[188:189], v[190:191]
	ds_read_b128 v[120:123], v44 offset:9472
	ds_read_b128 v[124:127], v44 offset:9488
	ds_read_b128 v[128:131], v44 offset:9984
	ds_read_b128 v[132:135], v44 offset:10000
	ds_read_b128 v[136:139], v44 offset:10240
	ds_read_b128 v[140:143], v44 offset:10256
	ds_read_b64 v[144:145], v46 offset:9216
	ds_read_b128 v[156:159], v44 offset:11264
	ds_read_b128 v[160:163], v44 offset:11280
	s_waitcnt lgkmcnt(10)
; #define LAS __attribute__((address_space(3)))
; __device__ __forceinline__ float red8(float x) { x += dpp_mov<0xB1>(x); x += dpp_mov<0x4E>(x); x += dpp_mov<0x141>(x); return x; }
; __device__ __forceinline__ void scan_phase(const KP& P, LAS unsigned char* lds, const int tid, const int bx, const int G) {
;     ...
;             for (int s = 0; s < 32; ++s) {
;                 const LAS float* p = cb + s * 384;
;                 const f32x4 w0 = *(const LAS f32x4*)(p), w1 = *(const LAS f32x4*)(p + 4);
;                 const f32x4 k0 = *(const LAS f32x4*)(p + 64), k1 = *(const LAS f32x4*)(p + 68);
;                 const f32x4 a0 = *(const LAS f32x4*)(p + 128), a1 = *(const LAS f32x4*)(p + 132);
;                 const f32x4 b0 = *(const LAS f32x4*)(p + 192), b1 = *(const LAS f32x4*)(p + 196);
;                 const f32x4 r0 = *(const LAS f32x4*)(p + 256), r1 = *(const LAS f32x4*)(p + 260);
;                 const float vv = buf[(c & 1) * 12288 + s * 384 + 320 + v];
;                 f32x2 sa2 = S[0] * (f32x2){a0.x, a0.y};
;                 sa2 += S[1] * (f32x2){a0.z, a0.w}; sa2 += S[2] * (f32x2){a1.x, a1.y}; sa2 += S[3] * (f32x2){a1.z, a1.w};
;                 const float sa = red8(sa2.x + sa2.y);
;                 const f32x2 sav = {sa, sa}, vv2 = {vv, vv};
;                 S[0] = S[0] * (f32x2){w0.x, w0.y} + sav * (f32x2){b0.x, b0.y} + vv2 * (f32x2){k0.x, k0.y};
;                 S[1] = S[1] * (f32x2){w0.z, w0.w} + sav * (f32x2){b0.z, b0.w} + vv2 * (f32x2){k0.z, k0.w};
;                 S[2] = S[2] * (f32x2){w1.x, w1.y} + sav * (f32x2){b1.x, b1.y} + vv2 * (f32x2){k1.x, k1.y};
;                 S[3] = S[3] * (f32x2){w1.z, w1.w} + sav * (f32x2){b1.z, b1.w} + vv2 * (f32x2){k1.z, k1.w};
;                 f32x2 y2 = S[0] * (f32x2){r0.x, r0.y};
;                 y2 += S[1] * (f32x2){r0.z, r0.w}; y2 += S[2] * (f32x2){r1.x, r1.y}; y2 += S[3] * (f32x2){r1.z, r1.w};
;                 const float y = red8(y2.x + y2.y);
;                 if (kc == 0) ybuf[s * 64 + v] = y;
	v_add_f32_dpp v192, v192, v192 quad_perm:[1,0,3,2] row_mask:0xf bank_mask:0xf bound_ctrl:1
	v_add_f32_dpp v193, v193, v193 quad_perm:[1,0,3,2] row_mask:0xf bank_mask:0xf bound_ctrl:1
	v_add_f32_dpp v194, v194, v194 quad_perm:[1,0,3,2] row_mask:0xf bank_mask:0xf bound_ctrl:1
	v_add_f32_dpp v195, v195, v195 quad_perm:[1,0,3,2] row_mask:0xf bank_mask:0xf bound_ctrl:1
	v_pk_fma_f32 v[96:97], v[146:147], v[70:71], v[96:97] op_sel:[0,0,0] op_sel_hi:[1,0,1]
	v_pk_fma_f32 v[98:99], v[146:147], v[70:71], v[98:99] op_sel:[0,1,0] op_sel_hi:[1,1,1]
	v_pk_fma_f32 v[100:101], v[146:147], v[72:73], v[100:101] op_sel:[0,0,0] op_sel_hi:[1,0,1]
	v_add_f32_dpp v192, v192, v192 quad_perm:[2,3,0,1] row_mask:0xf bank_mask:0xf bound_ctrl:1
	v_add_f32_dpp v193, v193, v193 quad_perm:[2,3,0,1] row_mask:0xf bank_mask:0xf bound_ctrl:1
	v_add_f32_dpp v194, v194, v194 quad_perm:[2,3,0,1] row_mask:0xf bank_mask:0xf bound_ctrl:1
	v_add_f32_dpp v195, v195, v195 quad_perm:[2,3,0,1] row_mask:0xf bank_mask:0xf bound_ctrl:1
	v_pk_fma_f32 v[102:103], v[146:147], v[72:73], v[102:103] op_sel:[0,1,0] op_sel_hi:[1,1,1]
	v_pk_fma_f32 v[104:105], v[146:147], v[74:75], v[104:105] op_sel:[0,0,0] op_sel_hi:[1,0,1]
	v_pk_fma_f32 v[106:107], v[146:147], v[74:75], v[106:107] op_sel:[0,1,0] op_sel_hi:[1,1,1]
	v_add_f32_dpp v192, v192, v192 row_half_mirror row_mask:0xf bank_mask:0xf bound_ctrl:1
	v_add_f32_dpp v193, v193, v193 row_half_mirror row_mask:0xf bank_mask:0xf bound_ctrl:1
	v_add_f32_dpp v194, v194, v194 row_half_mirror row_mask:0xf bank_mask:0xf bound_ctrl:1
	v_add_f32_dpp v195, v195, v195 row_half_mirror row_mask:0xf bank_mask:0xf bound_ctrl:1
	v_pk_fma_f32 v[108:109], v[146:147], v[76:77], v[108:109] op_sel:[0,0,0] op_sel_hi:[1,0,1]
	s_mov_b64 exec, s[10:11]
	ds_write_b64 v45, v[192:193] offset:1024
	s_mov_b64 exec, s[0:1]
	v_pk_fma_f32 v[110:111], v[146:147], v[76:77], v[110:111] op_sel:[0,1,0] op_sel_hi:[1,1,1]
	s_nop 0
	v_pk_fma_f32 v[96:97], v[194:195], v[78:79], v[96:97] op_sel:[0,0,0] op_sel_hi:[1,0,1]
	v_pk_fma_f32 v[98:99], v[194:195], v[78:79], v[98:99] op_sel:[0,1,0] op_sel_hi:[1,1,1]
	v_pk_fma_f32 v[100:101], v[194:195], v[80:81], v[100:101] op_sel:[0,0,0] op_sel_hi:[1,0,1]
	v_pk_fma_f32 v[102:103], v[194:195], v[80:81], v[102:103] op_sel:[0,1,0] op_sel_hi:[1,1,1]
	v_pk_fma_f32 v[104:105], v[194:195], v[82:83], v[104:105] op_sel:[0,0,0] op_sel_hi:[1,0,1]
	v_pk_fma_f32 v[106:107], v[194:195], v[82:83], v[106:107] op_sel:[0,1,0] op_sel_hi:[1,1,1]
	v_pk_fma_f32 v[108:109], v[194:195], v[84:85], v[108:109] op_sel:[0,0,0] op_sel_hi:[1,0,1]
	v_pk_fma_f32 v[110:111], v[194:195], v[84:85], v[110:111] op_sel:[0,1,0] op_sel_hi:[1,1,1]
	v_pk_mul_f32 v[184:185], v[96:97], v[86:87] op_sel:[0,0] op_sel_hi:[1,0]
	v_pk_mul_f32 v[188:189], v[96:97], v[148:149] op_sel:[0,0] op_sel_hi:[1,0]
	v_pk_mul_f32 v[186:187], v[98:99], v[86:87] op_sel:[0,1] op_sel_hi:[1,1]
	v_pk_mul_f32 v[190:191], v[98:99], v[148:149] op_sel:[0,1] op_sel_hi:[1,1]
	v_pk_fma_f32 v[184:185], v[100:101], v[88:89], v[184:185] op_sel:[0,0,0] op_sel_hi:[1,0,1]
	v_pk_fma_f32 v[188:189], v[100:101], v[150:151], v[188:189] op_sel:[0,0,0] op_sel_hi:[1,0,1]
	v_pk_fma_f32 v[186:187], v[102:103], v[88:89], v[186:187] op_sel:[0,1,0] op_sel_hi:[1,1,1]
	v_pk_fma_f32 v[190:191], v[102:103], v[150:151], v[190:191] op_sel:[0,1,0] op_sel_hi:[1,1,1]
	v_pk_fma_f32 v[184:185], v[104:105], v[90:91], v[184:185] op_sel:[0,0,0] op_sel_hi:[1,0,1]
	v_pk_fma_f32 v[188:189], v[104:105], v[152:153], v[188:189] op_sel:[0,0,0] op_sel_hi:[1,0,1]
	v_pk_fma_f32 v[186:187], v[106:107], v[90:91], v[186:187] op_sel:[0,1,0] op_sel_hi:[1,1,1]
	v_pk_fma_f32 v[190:191], v[106:107], v[152:153], v[190:191] op_sel:[0,1,0] op_sel_hi:[1,1,1]
	v_pk_fma_f32 v[184:185], v[108:109], v[92:93], v[184:185] op_sel:[0,0,0] op_sel_hi:[1,0,1]
	v_pk_fma_f32 v[188:189], v[108:109], v[154:155], v[188:189] op_sel:[0,0,0] op_sel_hi:[1,0,1]
	v_pk_fma_f32 v[186:187], v[110:111], v[92:93], v[186:187] op_sel:[0,1,0] op_sel_hi:[1,1,1]
	v_pk_fma_f32 v[190:191], v[110:111], v[154:155], v[190:191] op_sel:[0,1,0] op_sel_hi:[1,1,1]
	v_pk_add_f32 v[192:193], v[184:185], v[186:187]
	v_pk_add_f32 v[194:195], v[188:189], v[190:191]
	ds_read_b128 v[70:73], v44 offset:11008
	ds_read_b128 v[74:77], v44 offset:11024
	ds_read_b128 v[78:81], v44 offset:11520
	ds_read_b128 v[82:85], v44 offset:11536
	ds_read_b128 v[86:89], v44 offset:11776
	ds_read_b128 v[90:93], v44 offset:11792
	ds_read_b64 v[146:147], v46 offset:10752
	ds_read_b128 v[148:151], v44 offset:12800
	ds_read_b128 v[152:155], v44 offset:12816
	s_waitcnt lgkmcnt(10)
; #define LAS __attribute__((address_space(3)))
; __device__ __forceinline__ float red8(float x) { x += dpp_mov<0xB1>(x); x += dpp_mov<0x4E>(x); x += dpp_mov<0x141>(x); return x; }
; __device__ __forceinline__ void scan_phase(const KP& P, LAS unsigned char* lds, const int tid, const int bx, const int G) {
;     ...
;             for (int s = 0; s < 32; ++s) {
;                 const LAS float* p = cb + s * 384;
;                 const f32x4 w0 = *(const LAS f32x4*)(p), w1 = *(const LAS f32x4*)(p + 4);
;                 const f32x4 k0 = *(const LAS f32x4*)(p + 64), k1 = *(const LAS f32x4*)(p + 68);
;                 const f32x4 a0 = *(const LAS f32x4*)(p + 128), a1 = *(const LAS f32x4*)(p + 132);
;                 const f32x4 b0 = *(const LAS f32x4*)(p + 192), b1 = *(const LAS f32x4*)(p + 196);
;                 const f32x4 r0 = *(const LAS f32x4*)(p + 256), r1 = *(const LAS f32x4*)(p + 260);
;                 const float vv = buf[(c & 1) * 12288 + s * 384 + 320 + v];
;                 f32x2 sa2 = S[0] * (f32x2){a0.x, a0.y};
;                 sa2 += S[1] * (f32x2){a0.z, a0.w}; sa2 += S[2] * (f32x2){a1.x, a1.y}; sa2 += S[3] * (f32x2){a1.z, a1.w};
;                 const float sa = red8(sa2.x + sa2.y);
;                 const f32x2 sav = {sa, sa}, vv2 = {vv, vv};
;                 S[0] = S[0] * (f32x2){w0.x, w0.y} + sav * (f32x2){b0.x, b0.y} + vv2 * (f32x2){k0.x, k0.y};
;                 S[1] = S[1] * (f32x2){w0.z, w0.w} + sav * (f32x2){b0.z, b0.w} + vv2 * (f32x2){k0.z, k0.w};
;                 S[2] = S[2] * (f32x2){w1.x, w1.y} + sav * (f32x2){b1.x, b1.y} + vv2 * (f32x2){k1.x, k1.y};
;                 S[3] = S[3] * (f32x2){w1.z, w1.w} + sav * (f32x2){b1.z, b1.w} + vv2 * (f32x2){k1.z, k1.w};
;                 f32x2 y2 = S[0] * (f32x2){r0.x, r0.y};
;                 y2 += S[1] * (f32x2){r0.z, r0.w}; y2 += S[2] * (f32x2){r1.x, r1.y}; y2 += S[3] * (f32x2){r1.z, r1.w};
;                 const float y = red8(y2.x + y2.y);
;                 if (kc == 0) ybuf[s * 64 + v] = y;
	v_add_f32_dpp v192, v192, v192 quad_perm:[1,0,3,2] row_mask:0xf bank_mask:0xf bound_ctrl:1
	v_add_f32_dpp v193, v193, v193 quad_perm:[1,0,3,2] row_mask:0xf bank_mask:0xf bound_ctrl:1
	v_add_f32_dpp v194, v194, v194 quad_perm:[1,0,3,2] row_mask:0xf bank_mask:0xf bound_ctrl:1
	v_add_f32_dpp v195, v195, v195 quad_perm:[1,0,3,2] row_mask:0xf bank_mask:0xf bound_ctrl:1
	v_pk_fma_f32 v[96:97], v[144:145], v[120:121], v[96:97] op_sel:[0,0,0] op_sel_hi:[1,0,1]
	v_pk_fma_f32 v[98:99], v[144:145], v[120:121], v[98:99] op_sel:[0,1,0] op_sel_hi:[1,1,1]
	v_pk_fma_f32 v[100:101], v[144:145], v[122:123], v[100:101] op_sel:[0,0,0] op_sel_hi:[1,0,1]
	v_add_f32_dpp v192, v192, v192 quad_perm:[2,3,0,1] row_mask:0xf bank_mask:0xf bound_ctrl:1
	v_add_f32_dpp v193, v193, v193 quad_perm:[2,3,0,1] row_mask:0xf bank_mask:0xf bound_ctrl:1
	v_add_f32_dpp v194, v194, v194 quad_perm:[2,3,0,1] row_mask:0xf bank_mask:0xf bound_ctrl:1
	v_add_f32_dpp v195, v195, v195 quad_perm:[2,3,0,1] row_mask:0xf bank_mask:0xf bound_ctrl:1
	v_pk_fma_f32 v[102:103], v[144:145], v[122:123], v[102:103] op_sel:[0,1,0] op_sel_hi:[1,1,1]
	v_pk_fma_f32 v[104:105], v[144:145], v[124:125], v[104:105] op_sel:[0,0,0] op_sel_hi:[1,0,1]
	v_pk_fma_f32 v[106:107], v[144:145], v[124:125], v[106:107] op_sel:[0,1,0] op_sel_hi:[1,1,1]
	v_add_f32_dpp v192, v192, v192 row_half_mirror row_mask:0xf bank_mask:0xf bound_ctrl:1
	v_add_f32_dpp v193, v193, v193 row_half_mirror row_mask:0xf bank_mask:0xf bound_ctrl:1
	v_add_f32_dpp v194, v194, v194 row_half_mirror row_mask:0xf bank_mask:0xf bound_ctrl:1
	v_add_f32_dpp v195, v195, v195 row_half_mirror row_mask:0xf bank_mask:0xf bound_ctrl:1
	v_pk_fma_f32 v[108:109], v[144:145], v[126:127], v[108:109] op_sel:[0,0,0] op_sel_hi:[1,0,1]
	s_mov_b64 exec, s[10:11]
	ds_write_b64 v45, v[192:193] offset:1280
	s_mov_b64 exec, s[0:1]
	v_pk_fma_f32 v[110:111], v[144:145], v[126:127], v[110:111] op_sel:[0,1,0] op_sel_hi:[1,1,1]
	s_nop 0
	v_pk_fma_f32 v[96:97], v[194:195], v[128:129], v[96:97] op_sel:[0,0,0] op_sel_hi:[1,0,1]
	v_pk_fma_f32 v[98:99], v[194:195], v[128:129], v[98:99] op_sel:[0,1,0] op_sel_hi:[1,1,1]
	v_pk_fma_f32 v[100:101], v[194:195], v[130:131], v[100:101] op_sel:[0,0,0] op_sel_hi:[1,0,1]
	v_pk_fma_f32 v[102:103], v[194:195], v[130:131], v[102:103] op_sel:[0,1,0] op_sel_hi:[1,1,1]
	v_pk_fma_f32 v[104:105], v[194:195], v[132:133], v[104:105] op_sel:[0,0,0] op_sel_hi:[1,0,1]
	v_pk_fma_f32 v[106:107], v[194:195], v[132:133], v[106:107] op_sel:[0,1,0] op_sel_hi:[1,1,1]
	v_pk_fma_f32 v[108:109], v[194:195], v[134:135], v[108:109] op_sel:[0,0,0] op_sel_hi:[1,0,1]
	v_pk_fma_f32 v[110:111], v[194:195], v[134:135], v[110:111] op_sel:[0,1,0] op_sel_hi:[1,1,1]
	v_pk_mul_f32 v[184:185], v[96:97], v[136:137] op_sel:[0,0] op_sel_hi:[1,0]
	v_pk_mul_f32 v[188:189], v[96:97], v[156:157] op_sel:[0,0] op_sel_hi:[1,0]
	v_pk_mul_f32 v[186:187], v[98:99], v[136:137] op_sel:[0,1] op_sel_hi:[1,1]
	v_pk_mul_f32 v[190:191], v[98:99], v[156:157] op_sel:[0,1] op_sel_hi:[1,1]
	v_pk_fma_f32 v[184:185], v[100:101], v[138:139], v[184:185] op_sel:[0,0,0] op_sel_hi:[1,0,1]
	v_pk_fma_f32 v[188:189], v[100:101], v[158:159], v[188:189] op_sel:[0,0,0] op_sel_hi:[1,0,1]
	v_pk_fma_f32 v[186:187], v[102:103], v[138:139], v[186:187] op_sel:[0,1,0] op_sel_hi:[1,1,1]
	v_pk_fma_f32 v[190:191], v[102:103], v[158:159], v[190:191] op_sel:[0,1,0] op_sel_hi:[1,1,1]
	v_pk_fma_f32 v[184:185], v[104:105], v[140:141], v[184:185] op_sel:[0,0,0] op_sel_hi:[1,0,1]
	v_pk_fma_f32 v[188:189], v[104:105], v[160:161], v[188:189] op_sel:[0,0,0] op_sel_hi:[1,0,1]
	v_pk_fma_f32 v[186:187], v[106:107], v[140:141], v[186:187] op_sel:[0,1,0] op_sel_hi:[1,1,1]
	v_pk_fma_f32 v[190:191], v[106:107], v[160:161], v[190:191] op_sel:[0,1,0] op_sel_hi:[1,1,1]
	v_pk_fma_f32 v[184:185], v[108:109], v[142:143], v[184:185] op_sel:[0,0,0] op_sel_hi:[1,0,1]
	v_pk_fma_f32 v[188:189], v[108:109], v[162:163], v[188:189] op_sel:[0,0,0] op_sel_hi:[1,0,1]
	v_pk_fma_f32 v[186:187], v[110:111], v[142:143], v[186:187] op_sel:[0,1,0] op_sel_hi:[1,1,1]
	v_pk_fma_f32 v[190:191], v[110:111], v[162:163], v[190:191] op_sel:[0,1,0] op_sel_hi:[1,1,1]
	v_pk_add_f32 v[192:193], v[184:185], v[186:187]
	v_pk_add_f32 v[194:195], v[188:189], v[190:191]
	ds_read_b128 v[120:123], v44 offset:12544
	ds_read_b128 v[124:127], v44 offset:12560
	ds_read_b128 v[128:131], v44 offset:13056
	ds_read_b128 v[132:135], v44 offset:13072
	ds_read_b128 v[136:139], v44 offset:13312
	ds_read_b128 v[140:143], v44 offset:13328
	ds_read_b64 v[144:145], v46 offset:12288
	ds_read_b128 v[156:159], v44 offset:14336
	ds_read_b128 v[160:163], v44 offset:14352
	s_waitcnt lgkmcnt(10)
; #define LAS __attribute__((address_space(3)))
; __device__ __forceinline__ float red8(float x) { x += dpp_mov<0xB1>(x); x += dpp_mov<0x4E>(x); x += dpp_mov<0x141>(x); return x; }
; __device__ __forceinline__ void scan_phase(const KP& P, LAS unsigned char* lds, const int tid, const int bx, const int G) {
;     ...
;             for (int s = 0; s < 32; ++s) {
;                 const LAS float* p = cb + s * 384;
;                 const f32x4 w0 = *(const LAS f32x4*)(p), w1 = *(const LAS f32x4*)(p + 4);
;                 const f32x4 k0 = *(const LAS f32x4*)(p + 64), k1 = *(const LAS f32x4*)(p + 68);
;                 const f32x4 a0 = *(const LAS f32x4*)(p + 128), a1 = *(const LAS f32x4*)(p + 132);
;                 const f32x4 b0 = *(const LAS f32x4*)(p + 192), b1 = *(const LAS f32x4*)(p + 196);
;                 const f32x4 r0 = *(const LAS f32x4*)(p + 256), r1 = *(const LAS f32x4*)(p + 260);
;                 const float vv = buf[(c & 1) * 12288 + s * 384 + 320 + v];
;                 f32x2 sa2 = S[0] * (f32x2){a0.x, a0.y};
;                 sa2 += S[1] * (f32x2){a0.z, a0.w}; sa2 += S[2] * (f32x2){a1.x, a1.y}; sa2 += S[3] * (f32x2){a1.z, a1.w};
;                 const float sa = red8(sa2.x + sa2.y);
;                 const f32x2 sav = {sa, sa}, vv2 = {vv, vv};
;                 S[0] = S[0] * (f32x2){w0.x, w0.y} + sav * (f32x2){b0.x, b0.y} + vv2 * (f32x2){k0.x, k0.y};
;                 S[1] = S[1] * (f32x2){w0.z, w0.w} + sav * (f32x2){b0.z, b0.w} + vv2 * (f32x2){k0.z, k0.w};
;                 S[2] = S[2] * (f32x2){w1.x, w1.y} + sav * (f32x2){b1.x, b1.y} + vv2 * (f32x2){k1.x, k1.y};
;                 S[3] = S[3] * (f32x2){w1.z, w1.w} + sav * (f32x2){b1.z, b1.w} + vv2 * (f32x2){k1.z, k1.w};
;                 f32x2 y2 = S[0] * (f32x2){r0.x, r0.y};
;                 y2 += S[1] * (f32x2){r0.z, r0.w}; y2 += S[2] * (f32x2){r1.x, r1.y}; y2 += S[3] * (f32x2){r1.z, r1.w};
;                 const float y = red8(y2.x + y2.y);
;                 if (kc == 0) ybuf[s * 64 + v] = y;
	v_add_f32_dpp v192, v192, v192 quad_perm:[1,0,3,2] row_mask:0xf bank_mask:0xf bound_ctrl:1
	v_add_f32_dpp v193, v193, v193 quad_perm:[1,0,3,2] row_mask:0xf bank_mask:0xf bound_ctrl:1
	v_add_f32_dpp v194, v194, v194 quad_perm:[1,0,3,2] row_mask:0xf bank_mask:0xf bound_ctrl:1
	v_add_f32_dpp v195, v195, v195 quad_perm:[1,0,3,2] row_mask:0xf bank_mask:0xf bound_ctrl:1
	v_pk_fma_f32 v[96:97], v[146:147], v[70:71], v[96:97] op_sel:[0,0,0] op_sel_hi:[1,0,1]
	v_pk_fma_f32 v[98:99], v[146:147], v[70:71], v[98:99] op_sel:[0,1,0] op_sel_hi:[1,1,1]
	v_pk_fma_f32 v[100:101], v[146:147], v[72:73], v[100:101] op_sel:[0,0,0] op_sel_hi:[1,0,1]
	v_add_f32_dpp v192, v192, v192 quad_perm:[2,3,0,1] row_mask:0xf bank_mask:0xf bound_ctrl:1
	v_add_f32_dpp v193, v193, v193 quad_perm:[2,3,0,1] row_mask:0xf bank_mask:0xf bound_ctrl:1
	v_add_f32_dpp v194, v194, v194 quad_perm:[2,3,0,1] row_mask:0xf bank_mask:0xf bound_ctrl:1
	v_add_f32_dpp v195, v195, v195 quad_perm:[2,3,0,1] row_mask:0xf bank_mask:0xf bound_ctrl:1
	v_pk_fma_f32 v[102:103], v[146:147], v[72:73], v[102:103] op_sel:[0,1,0] op_sel_hi:[1,1,1]
	v_pk_fma_f32 v[104:105], v[146:147], v[74:75], v[104:105] op_sel:[0,0,0] op_sel_hi:[1,0,1]
	v_pk_fma_f32 v[106:107], v[146:147], v[74:75], v[106:107] op_sel:[0,1,0] op_sel_hi:[1,1,1]
	v_add_f32_dpp v192, v192, v192 row_half_mirror row_mask:0xf bank_mask:0xf bound_ctrl:1
	v_add_f32_dpp v193, v193, v193 row_half_mirror row_mask:0xf bank_mask:0xf bound_ctrl:1
	v_add_f32_dpp v194, v194, v194 row_half_mirror row_mask:0xf bank_mask:0xf bound_ctrl:1
	v_add_f32_dpp v195, v195, v195 row_half_mirror row_mask:0xf bank_mask:0xf bound_ctrl:1
	v_pk_fma_f32 v[108:109], v[146:147], v[76:77], v[108:109] op_sel:[0,0,0] op_sel_hi:[1,0,1]
	s_mov_b64 exec, s[10:11]
	ds_write_b64 v45, v[192:193] offset:1536
	s_mov_b64 exec, s[0:1]
	v_pk_fma_f32 v[110:111], v[146:147], v[76:77], v[110:111] op_sel:[0,1,0] op_sel_hi:[1,1,1]
	s_nop 0
	v_pk_fma_f32 v[96:97], v[194:195], v[78:79], v[96:97] op_sel:[0,0,0] op_sel_hi:[1,0,1]
	v_pk_fma_f32 v[98:99], v[194:195], v[78:79], v[98:99] op_sel:[0,1,0] op_sel_hi:[1,1,1]
	v_pk_fma_f32 v[100:101], v[194:195], v[80:81], v[100:101] op_sel:[0,0,0] op_sel_hi:[1,0,1]
	v_pk_fma_f32 v[102:103], v[194:195], v[80:81], v[102:103] op_sel:[0,1,0] op_sel_hi:[1,1,1]
	v_pk_fma_f32 v[104:105], v[194:195], v[82:83], v[104:105] op_sel:[0,0,0] op_sel_hi:[1,0,1]
	v_pk_fma_f32 v[106:107], v[194:195], v[82:83], v[106:107] op_sel:[0,1,0] op_sel_hi:[1,1,1]
	v_pk_fma_f32 v[108:109], v[194:195], v[84:85], v[108:109] op_sel:[0,0,0] op_sel_hi:[1,0,1]
	v_pk_fma_f32 v[110:111], v[194:195], v[84:85], v[110:111] op_sel:[0,1,0] op_sel_hi:[1,1,1]
	v_pk_mul_f32 v[184:185], v[96:97], v[86:87] op_sel:[0,0] op_sel_hi:[1,0]
	v_pk_mul_f32 v[188:189], v[96:97], v[148:149] op_sel:[0,0] op_sel_hi:[1,0]
	v_pk_mul_f32 v[186:187], v[98:99], v[86:87] op_sel:[0,1] op_sel_hi:[1,1]
	v_pk_mul_f32 v[190:191], v[98:99], v[148:149] op_sel:[0,1] op_sel_hi:[1,1]
	v_pk_fma_f32 v[184:185], v[100:101], v[88:89], v[184:185] op_sel:[0,0,0] op_sel_hi:[1,0,1]
	v_pk_fma_f32 v[188:189], v[100:101], v[150:151], v[188:189] op_sel:[0,0,0] op_sel_hi:[1,0,1]
	v_pk_fma_f32 v[186:187], v[102:103], v[88:89], v[186:187] op_sel:[0,1,0] op_sel_hi:[1,1,1]
	v_pk_fma_f32 v[190:191], v[102:103], v[150:151], v[190:191] op_sel:[0,1,0] op_sel_hi:[1,1,1]
	v_pk_fma_f32 v[184:185], v[104:105], v[90:91], v[184:185] op_sel:[0,0,0] op_sel_hi:[1,0,1]
	v_pk_fma_f32 v[188:189], v[104:105], v[152:153], v[188:189] op_sel:[0,0,0] op_sel_hi:[1,0,1]
	v_pk_fma_f32 v[186:187], v[106:107], v[90:91], v[186:187] op_sel:[0,1,0] op_sel_hi:[1,1,1]
	v_pk_fma_f32 v[190:191], v[106:107], v[152:153], v[190:191] op_sel:[0,1,0] op_sel_hi:[1,1,1]
	v_pk_fma_f32 v[184:185], v[108:109], v[92:93], v[184:185] op_sel:[0,0,0] op_sel_hi:[1,0,1]
	v_pk_fma_f32 v[188:189], v[108:109], v[154:155], v[188:189] op_sel:[0,0,0] op_sel_hi:[1,0,1]
	v_pk_fma_f32 v[186:187], v[110:111], v[92:93], v[186:187] op_sel:[0,1,0] op_sel_hi:[1,1,1]
	v_pk_fma_f32 v[190:191], v[110:111], v[154:155], v[190:191] op_sel:[0,1,0] op_sel_hi:[1,1,1]
	v_pk_add_f32 v[192:193], v[184:185], v[186:187]
	v_pk_add_f32 v[194:195], v[188:189], v[190:191]
	ds_read_b128 v[70:73], v44 offset:14080
	ds_read_b128 v[74:77], v44 offset:14096
	ds_read_b128 v[78:81], v44 offset:14592
	ds_read_b128 v[82:85], v44 offset:14608
	ds_read_b128 v[86:89], v44 offset:14848
	ds_read_b128 v[90:93], v44 offset:14864
	ds_read_b64 v[146:147], v46 offset:13824
	ds_read_b128 v[148:151], v44 offset:15872
	ds_read_b128 v[152:155], v44 offset:15888
	s_waitcnt lgkmcnt(10)
; #define LAS __attribute__((address_space(3)))
; __device__ __forceinline__ float red8(float x) { x += dpp_mov<0xB1>(x); x += dpp_mov<0x4E>(x); x += dpp_mov<0x141>(x); return x; }
; __device__ __forceinline__ void scan_phase(const KP& P, LAS unsigned char* lds, const int tid, const int bx, const int G) {
;     ...
;             for (int s = 0; s < 32; ++s) {
;                 const LAS float* p = cb + s * 384;
;                 const f32x4 w0 = *(const LAS f32x4*)(p), w1 = *(const LAS f32x4*)(p + 4);
;                 const f32x4 k0 = *(const LAS f32x4*)(p + 64), k1 = *(const LAS f32x4*)(p + 68);
;                 const f32x4 a0 = *(const LAS f32x4*)(p + 128), a1 = *(const LAS f32x4*)(p + 132);
;                 const f32x4 b0 = *(const LAS f32x4*)(p + 192), b1 = *(const LAS f32x4*)(p + 196);
;                 const f32x4 r0 = *(const LAS f32x4*)(p + 256), r1 = *(const LAS f32x4*)(p + 260);
;                 const float vv = buf[(c & 1) * 12288 + s * 384 + 320 + v];
;                 f32x2 sa2 = S[0] * (f32x2){a0.x, a0.y};
;                 sa2 += S[1] * (f32x2){a0.z, a0.w}; sa2 += S[2] * (f32x2){a1.x, a1.y}; sa2 += S[3] * (f32x2){a1.z, a1.w};
;                 const float sa = red8(sa2.x + sa2.y);
;                 const f32x2 sav = {sa, sa}, vv2 = {vv, vv};
;                 S[0] = S[0] * (f32x2){w0.x, w0.y} + sav * (f32x2){b0.x, b0.y} + vv2 * (f32x2){k0.x, k0.y};
;                 S[1] = S[1] * (f32x2){w0.z, w0.w} + sav * (f32x2){b0.z, b0.w} + vv2 * (f32x2){k0.z, k0.w};
;                 S[2] = S[2] * (f32x2){w1.x, w1.y} + sav * (f32x2){b1.x, b1.y} + vv2 * (f32x2){k1.x, k1.y};
;                 S[3] = S[3] * (f32x2){w1.z, w1.w} + sav * (f32x2){b1.z, b1.w} + vv2 * (f32x2){k1.z, k1.w};
;                 f32x2 y2 = S[0] * (f32x2){r0.x, r0.y};
;                 y2 += S[1] * (f32x2){r0.z, r0.w}; y2 += S[2] * (f32x2){r1.x, r1.y}; y2 += S[3] * (f32x2){r1.z, r1.w};
;                 const float y = red8(y2.x + y2.y);
;                 if (kc == 0) ybuf[s * 64 + v] = y;
	v_add_f32_dpp v192, v192, v192 quad_perm:[1,0,3,2] row_mask:0xf bank_mask:0xf bound_ctrl:1
	v_add_f32_dpp v193, v193, v193 quad_perm:[1,0,3,2] row_mask:0xf bank_mask:0xf bound_ctrl:1
	v_add_f32_dpp v194, v194, v194 quad_perm:[1,0,3,2] row_mask:0xf bank_mask:0xf bound_ctrl:1
	v_add_f32_dpp v195, v195, v195 quad_perm:[1,0,3,2] row_mask:0xf bank_mask:0xf bound_ctrl:1
	v_pk_fma_f32 v[96:97], v[144:145], v[120:121], v[96:97] op_sel:[0,0,0] op_sel_hi:[1,0,1]
	v_pk_fma_f32 v[98:99], v[144:145], v[120:121], v[98:99] op_sel:[0,1,0] op_sel_hi:[1,1,1]
	v_pk_fma_f32 v[100:101], v[144:145], v[122:123], v[100:101] op_sel:[0,0,0] op_sel_hi:[1,0,1]
	v_add_f32_dpp v192, v192, v192 quad_perm:[2,3,0,1] row_mask:0xf bank_mask:0xf bound_ctrl:1
	v_add_f32_dpp v193, v193, v193 quad_perm:[2,3,0,1] row_mask:0xf bank_mask:0xf bound_ctrl:1
	v_add_f32_dpp v194, v194, v194 quad_perm:[2,3,0,1] row_mask:0xf bank_mask:0xf bound_ctrl:1
	v_add_f32_dpp v195, v195, v195 quad_perm:[2,3,0,1] row_mask:0xf bank_mask:0xf bound_ctrl:1
	v_pk_fma_f32 v[102:103], v[144:145], v[122:123], v[102:103] op_sel:[0,1,0] op_sel_hi:[1,1,1]
	v_pk_fma_f32 v[104:105], v[144:145], v[124:125], v[104:105] op_sel:[0,0,0] op_sel_hi:[1,0,1]
	v_pk_fma_f32 v[106:107], v[144:145], v[124:125], v[106:107] op_sel:[0,1,0] op_sel_hi:[1,1,1]
	v_add_f32_dpp v192, v192, v192 row_half_mirror row_mask:0xf bank_mask:0xf bound_ctrl:1
	v_add_f32_dpp v193, v193, v193 row_half_mirror row_mask:0xf bank_mask:0xf bound_ctrl:1
	v_add_f32_dpp v194, v194, v194 row_half_mirror row_mask:0xf bank_mask:0xf bound_ctrl:1
	v_add_f32_dpp v195, v195, v195 row_half_mirror row_mask:0xf bank_mask:0xf bound_ctrl:1
	v_pk_fma_f32 v[108:109], v[144:145], v[126:127], v[108:109] op_sel:[0,0,0] op_sel_hi:[1,0,1]
	s_mov_b64 exec, s[10:11]
	ds_write_b64 v45, v[192:193] offset:1792
	s_mov_b64 exec, s[0:1]
	v_pk_fma_f32 v[110:111], v[144:145], v[126:127], v[110:111] op_sel:[0,1,0] op_sel_hi:[1,1,1]
	s_nop 0
	v_pk_fma_f32 v[96:97], v[194:195], v[128:129], v[96:97] op_sel:[0,0,0] op_sel_hi:[1,0,1]
	v_pk_fma_f32 v[98:99], v[194:195], v[128:129], v[98:99] op_sel:[0,1,0] op_sel_hi:[1,1,1]
	v_pk_fma_f32 v[100:101], v[194:195], v[130:131], v[100:101] op_sel:[0,0,0] op_sel_hi:[1,0,1]
	v_pk_fma_f32 v[102:103], v[194:195], v[130:131], v[102:103] op_sel:[0,1,0] op_sel_hi:[1,1,1]
	v_pk_fma_f32 v[104:105], v[194:195], v[132:133], v[104:105] op_sel:[0,0,0] op_sel_hi:[1,0,1]
	v_pk_fma_f32 v[106:107], v[194:195], v[132:133], v[106:107] op_sel:[0,1,0] op_sel_hi:[1,1,1]
	v_pk_fma_f32 v[108:109], v[194:195], v[134:135], v[108:109] op_sel:[0,0,0] op_sel_hi:[1,0,1]
	v_pk_fma_f32 v[110:111], v[194:195], v[134:135], v[110:111] op_sel:[0,1,0] op_sel_hi:[1,1,1]
	v_pk_mul_f32 v[184:185], v[96:97], v[136:137] op_sel:[0,0] op_sel_hi:[1,0]
	v_pk_mul_f32 v[188:189], v[96:97], v[156:157] op_sel:[0,0] op_sel_hi:[1,0]
	v_pk_mul_f32 v[186:187], v[98:99], v[136:137] op_sel:[0,1] op_sel_hi:[1,1]
	v_pk_mul_f32 v[190:191], v[98:99], v[156:157] op_sel:[0,1] op_sel_hi:[1,1]
	v_pk_fma_f32 v[184:185], v[100:101], v[138:139], v[184:185] op_sel:[0,0,0] op_sel_hi:[1,0,1]
	v_pk_fma_f32 v[188:189], v[100:101], v[158:159], v[188:189] op_sel:[0,0,0] op_sel_hi:[1,0,1]
	v_pk_fma_f32 v[186:187], v[102:103], v[138:139], v[186:187] op_sel:[0,1,0] op_sel_hi:[1,1,1]
	v_pk_fma_f32 v[190:191], v[102:103], v[158:159], v[190:191] op_sel:[0,1,0] op_sel_hi:[1,1,1]
	v_pk_fma_f32 v[184:185], v[104:105], v[140:141], v[184:185] op_sel:[0,0,0] op_sel_hi:[1,0,1]
	v_pk_fma_f32 v[188:189], v[104:105], v[160:161], v[188:189] op_sel:[0,0,0] op_sel_hi:[1,0,1]
	v_pk_fma_f32 v[186:187], v[106:107], v[140:141], v[186:187] op_sel:[0,1,0] op_sel_hi:[1,1,1]
	v_pk_fma_f32 v[190:191], v[106:107], v[160:161], v[190:191] op_sel:[0,1,0] op_sel_hi:[1,1,1]
	v_pk_fma_f32 v[184:185], v[108:109], v[142:143], v[184:185] op_sel:[0,0,0] op_sel_hi:[1,0,1]
	v_pk_fma_f32 v[188:189], v[108:109], v[162:163], v[188:189] op_sel:[0,0,0] op_sel_hi:[1,0,1]
	v_pk_fma_f32 v[186:187], v[110:111], v[142:143], v[186:187] op_sel:[0,1,0] op_sel_hi:[1,1,1]
	v_pk_fma_f32 v[190:191], v[110:111], v[162:163], v[190:191] op_sel:[0,1,0] op_sel_hi:[1,1,1]
	v_pk_add_f32 v[192:193], v[184:185], v[186:187]
	v_pk_add_f32 v[194:195], v[188:189], v[190:191]
	ds_read_b128 v[120:123], v44 offset:15616
	ds_read_b128 v[124:127], v44 offset:15632
	ds_read_b128 v[128:131], v44 offset:16128
	ds_read_b128 v[132:135], v44 offset:16144
	ds_read_b128 v[136:139], v44 offset:16384
	ds_read_b128 v[140:143], v44 offset:16400
	ds_read_b64 v[144:145], v46 offset:15360
	ds_read_b128 v[156:159], v44 offset:17408
	ds_read_b128 v[160:163], v44 offset:17424
	s_waitcnt lgkmcnt(10)
; #define LAS __attribute__((address_space(3)))
; __device__ __forceinline__ float red8(float x) { x += dpp_mov<0xB1>(x); x += dpp_mov<0x4E>(x); x += dpp_mov<0x141>(x); return x; }
; __device__ __forceinline__ void scan_phase(const KP& P, LAS unsigned char* lds, const int tid, const int bx, const int G) {
;     ...
;             for (int s = 0; s < 32; ++s) {
;                 const LAS float* p = cb + s * 384;
;                 const f32x4 w0 = *(const LAS f32x4*)(p), w1 = *(const LAS f32x4*)(p + 4);
;                 const f32x4 k0 = *(const LAS f32x4*)(p + 64), k1 = *(const LAS f32x4*)(p + 68);
;                 const f32x4 a0 = *(const LAS f32x4*)(p + 128), a1 = *(const LAS f32x4*)(p + 132);
;                 const f32x4 b0 = *(const LAS f32x4*)(p + 192), b1 = *(const LAS f32x4*)(p + 196);
;                 const f32x4 r0 = *(const LAS f32x4*)(p + 256), r1 = *(const LAS f32x4*)(p + 260);
;                 const float vv = buf[(c & 1) * 12288 + s * 384 + 320 + v];
;                 f32x2 sa2 = S[0] * (f32x2){a0.x, a0.y};
;                 sa2 += S[1] * (f32x2){a0.z, a0.w}; sa2 += S[2] * (f32x2){a1.x, a1.y}; sa2 += S[3] * (f32x2){a1.z, a1.w};
;                 const float sa = red8(sa2.x + sa2.y);
;                 const f32x2 sav = {sa, sa}, vv2 = {vv, vv};
;                 S[0] = S[0] * (f32x2){w0.x, w0.y} + sav * (f32x2){b0.x, b0.y} + vv2 * (f32x2){k0.x, k0.y};
;                 S[1] = S[1] * (f32x2){w0.z, w0.w} + sav * (f32x2){b0.z, b0.w} + vv2 * (f32x2){k0.z, k0.w};
;                 S[2] = S[2] * (f32x2){w1.x, w1.y} + sav * (f32x2){b1.x, b1.y} + vv2 * (f32x2){k1.x, k1.y};
;                 S[3] = S[3] * (f32x2){w1.z, w1.w} + sav * (f32x2){b1.z, b1.w} + vv2 * (f32x2){k1.z, k1.w};
;                 f32x2 y2 = S[0] * (f32x2){r0.x, r0.y};
;                 y2 += S[1] * (f32x2){r0.z, r0.w}; y2 += S[2] * (f32x2){r1.x, r1.y}; y2 += S[3] * (f32x2){r1.z, r1.w};
;                 const float y = red8(y2.x + y2.y);
;                 if (kc == 0) ybuf[s * 64 + v] = y;
	v_add_f32_dpp v192, v192, v192 quad_perm:[1,0,3,2] row_mask:0xf bank_mask:0xf bound_ctrl:1
	v_add_f32_dpp v193, v193, v193 quad_perm:[1,0,3,2] row_mask:0xf bank_mask:0xf bound_ctrl:1
	v_add_f32_dpp v194, v194, v194 quad_perm:[1,0,3,2] row_mask:0xf bank_mask:0xf bound_ctrl:1
	v_add_f32_dpp v195, v195, v195 quad_perm:[1,0,3,2] row_mask:0xf bank_mask:0xf bound_ctrl:1
	v_pk_fma_f32 v[96:97], v[146:147], v[70:71], v[96:97] op_sel:[0,0,0] op_sel_hi:[1,0,1]
	v_pk_fma_f32 v[98:99], v[146:147], v[70:71], v[98:99] op_sel:[0,1,0] op_sel_hi:[1,1,1]
	v_pk_fma_f32 v[100:101], v[146:147], v[72:73], v[100:101] op_sel:[0,0,0] op_sel_hi:[1,0,1]
	v_add_f32_dpp v192, v192, v192 quad_perm:[2,3,0,1] row_mask:0xf bank_mask:0xf bound_ctrl:1
	v_add_f32_dpp v193, v193, v193 quad_perm:[2,3,0,1] row_mask:0xf bank_mask:0xf bound_ctrl:1
	v_add_f32_dpp v194, v194, v194 quad_perm:[2,3,0,1] row_mask:0xf bank_mask:0xf bound_ctrl:1
	v_add_f32_dpp v195, v195, v195 quad_perm:[2,3,0,1] row_mask:0xf bank_mask:0xf bound_ctrl:1
	v_pk_fma_f32 v[102:103], v[146:147], v[72:73], v[102:103] op_sel:[0,1,0] op_sel_hi:[1,1,1]
	v_pk_fma_f32 v[104:105], v[146:147], v[74:75], v[104:105] op_sel:[0,0,0] op_sel_hi:[1,0,1]
	v_pk_fma_f32 v[106:107], v[146:147], v[74:75], v[106:107] op_sel:[0,1,0] op_sel_hi:[1,1,1]
	v_add_f32_dpp v192, v192, v192 row_half_mirror row_mask:0xf bank_mask:0xf bound_ctrl:1
	v_add_f32_dpp v193, v193, v193 row_half_mirror row_mask:0xf bank_mask:0xf bound_ctrl:1
	v_add_f32_dpp v194, v194, v194 row_half_mirror row_mask:0xf bank_mask:0xf bound_ctrl:1
	v_add_f32_dpp v195, v195, v195 row_half_mirror row_mask:0xf bank_mask:0xf bound_ctrl:1
	v_pk_fma_f32 v[108:109], v[146:147], v[76:77], v[108:109] op_sel:[0,0,0] op_sel_hi:[1,0,1]
	s_mov_b64 exec, s[10:11]
	ds_write_b64 v45, v[192:193] offset:2048
	s_mov_b64 exec, s[0:1]
	v_pk_fma_f32 v[110:111], v[146:147], v[76:77], v[110:111] op_sel:[0,1,0] op_sel_hi:[1,1,1]
	s_nop 0
	v_pk_fma_f32 v[96:97], v[194:195], v[78:79], v[96:97] op_sel:[0,0,0] op_sel_hi:[1,0,1]
	v_pk_fma_f32 v[98:99], v[194:195], v[78:79], v[98:99] op_sel:[0,1,0] op_sel_hi:[1,1,1]
	v_pk_fma_f32 v[100:101], v[194:195], v[80:81], v[100:101] op_sel:[0,0,0] op_sel_hi:[1,0,1]
	v_pk_fma_f32 v[102:103], v[194:195], v[80:81], v[102:103] op_sel:[0,1,0] op_sel_hi:[1,1,1]
	v_pk_fma_f32 v[104:105], v[194:195], v[82:83], v[104:105] op_sel:[0,0,0] op_sel_hi:[1,0,1]
	v_pk_fma_f32 v[106:107], v[194:195], v[82:83], v[106:107] op_sel:[0,1,0] op_sel_hi:[1,1,1]
	v_pk_fma_f32 v[108:109], v[194:195], v[84:85], v[108:109] op_sel:[0,0,0] op_sel_hi:[1,0,1]
	v_pk_fma_f32 v[110:111], v[194:195], v[84:85], v[110:111] op_sel:[0,1,0] op_sel_hi:[1,1,1]
	v_pk_mul_f32 v[184:185], v[96:97], v[86:87] op_sel:[0,0] op_sel_hi:[1,0]
	v_pk_mul_f32 v[188:189], v[96:97], v[148:149] op_sel:[0,0] op_sel_hi:[1,0]
	v_pk_mul_f32 v[186:187], v[98:99], v[86:87] op_sel:[0,1] op_sel_hi:[1,1]
	v_pk_mul_f32 v[190:191], v[98:99], v[148:149] op_sel:[0,1] op_sel_hi:[1,1]
	v_pk_fma_f32 v[184:185], v[100:101], v[88:89], v[184:185] op_sel:[0,0,0] op_sel_hi:[1,0,1]
	v_pk_fma_f32 v[188:189], v[100:101], v[150:151], v[188:189] op_sel:[0,0,0] op_sel_hi:[1,0,1]
	v_pk_fma_f32 v[186:187], v[102:103], v[88:89], v[186:187] op_sel:[0,1,0] op_sel_hi:[1,1,1]
	v_pk_fma_f32 v[190:191], v[102:103], v[150:151], v[190:191] op_sel:[0,1,0] op_sel_hi:[1,1,1]
	v_pk_fma_f32 v[184:185], v[104:105], v[90:91], v[184:185] op_sel:[0,0,0] op_sel_hi:[1,0,1]
	v_pk_fma_f32 v[188:189], v[104:105], v[152:153], v[188:189] op_sel:[0,0,0] op_sel_hi:[1,0,1]
	v_pk_fma_f32 v[186:187], v[106:107], v[90:91], v[186:187] op_sel:[0,1,0] op_sel_hi:[1,1,1]
	v_pk_fma_f32 v[190:191], v[106:107], v[152:153], v[190:191] op_sel:[0,1,0] op_sel_hi:[1,1,1]
	v_pk_fma_f32 v[184:185], v[108:109], v[92:93], v[184:185] op_sel:[0,0,0] op_sel_hi:[1,0,1]
	v_pk_fma_f32 v[188:189], v[108:109], v[154:155], v[188:189] op_sel:[0,0,0] op_sel_hi:[1,0,1]
	v_pk_fma_f32 v[186:187], v[110:111], v[92:93], v[186:187] op_sel:[0,1,0] op_sel_hi:[1,1,1]
	v_pk_fma_f32 v[190:191], v[110:111], v[154:155], v[190:191] op_sel:[0,1,0] op_sel_hi:[1,1,1]
	v_pk_add_f32 v[192:193], v[184:185], v[186:187]
	v_pk_add_f32 v[194:195], v[188:189], v[190:191]
	ds_read_b128 v[70:73], v44 offset:17152
	ds_read_b128 v[74:77], v44 offset:17168
	ds_read_b128 v[78:81], v44 offset:17664
	ds_read_b128 v[82:85], v44 offset:17680
	ds_read_b128 v[86:89], v44 offset:17920
	ds_read_b128 v[90:93], v44 offset:17936
	ds_read_b64 v[146:147], v46 offset:16896
	ds_read_b128 v[148:151], v44 offset:18944
	ds_read_b128 v[152:155], v44 offset:18960
	s_waitcnt lgkmcnt(10)
; #define LAS __attribute__((address_space(3)))
; __device__ __forceinline__ float red8(float x) { x += dpp_mov<0xB1>(x); x += dpp_mov<0x4E>(x); x += dpp_mov<0x141>(x); return x; }
; __device__ __forceinline__ void scan_phase(const KP& P, LAS unsigned char* lds, const int tid, const int bx, const int G) {
;     ...
;             for (int s = 0; s < 32; ++s) {
;                 const LAS float* p = cb + s * 384;
;                 const f32x4 w0 = *(const LAS f32x4*)(p), w1 = *(const LAS f32x4*)(p + 4);
;                 const f32x4 k0 = *(const LAS f32x4*)(p + 64), k1 = *(const LAS f32x4*)(p + 68);
;                 const f32x4 a0 = *(const LAS f32x4*)(p + 128), a1 = *(const LAS f32x4*)(p + 132);
;                 const f32x4 b0 = *(const LAS f32x4*)(p + 192), b1 = *(const LAS f32x4*)(p + 196);
;                 const f32x4 r0 = *(const LAS f32x4*)(p + 256), r1 = *(const LAS f32x4*)(p + 260);
;                 const float vv = buf[(c & 1) * 12288 + s * 384 + 320 + v];
;                 f32x2 sa2 = S[0] * (f32x2){a0.x, a0.y};
;                 sa2 += S[1] * (f32x2){a0.z, a0.w}; sa2 += S[2] * (f32x2){a1.x, a1.y}; sa2 += S[3] * (f32x2){a1.z, a1.w};
;                 const float sa = red8(sa2.x + sa2.y);
;                 const f32x2 sav = {sa, sa}, vv2 = {vv, vv};
;                 S[0] = S[0] * (f32x2){w0.x, w0.y} + sav * (f32x2){b0.x, b0.y} + vv2 * (f32x2){k0.x, k0.y};
;                 S[1] = S[1] * (f32x2){w0.z, w0.w} + sav * (f32x2){b0.z, b0.w} + vv2 * (f32x2){k0.z, k0.w};
;                 S[2] = S[2] * (f32x2){w1.x, w1.y} + sav * (f32x2){b1.x, b1.y} + vv2 * (f32x2){k1.x, k1.y};
;                 S[3] = S[3] * (f32x2){w1.z, w1.w} + sav * (f32x2){b1.z, b1.w} + vv2 * (f32x2){k1.z, k1.w};
;                 f32x2 y2 = S[0] * (f32x2){r0.x, r0.y};
;                 y2 += S[1] * (f32x2){r0.z, r0.w}; y2 += S[2] * (f32x2){r1.x, r1.y}; y2 += S[3] * (f32x2){r1.z, r1.w};
;                 const float y = red8(y2.x + y2.y);
;                 if (kc == 0) ybuf[s * 64 + v] = y;
	v_add_f32_dpp v192, v192, v192 quad_perm:[1,0,3,2] row_mask:0xf bank_mask:0xf bound_ctrl:1
	v_add_f32_dpp v193, v193, v193 quad_perm:[1,0,3,2] row_mask:0xf bank_mask:0xf bound_ctrl:1
	v_add_f32_dpp v194, v194, v194 quad_perm:[1,0,3,2] row_mask:0xf bank_mask:0xf bound_ctrl:1
	v_add_f32_dpp v195, v195, v195 quad_perm:[1,0,3,2] row_mask:0xf bank_mask:0xf bound_ctrl:1
	v_pk_fma_f32 v[96:97], v[144:145], v[120:121], v[96:97] op_sel:[0,0,0] op_sel_hi:[1,0,1]
	v_pk_fma_f32 v[98:99], v[144:145], v[120:121], v[98:99] op_sel:[0,1,0] op_sel_hi:[1,1,1]
	v_pk_fma_f32 v[100:101], v[144:145], v[122:123], v[100:101] op_sel:[0,0,0] op_sel_hi:[1,0,1]
	v_add_f32_dpp v192, v192, v192 quad_perm:[2,3,0,1] row_mask:0xf bank_mask:0xf bound_ctrl:1
	v_add_f32_dpp v193, v193, v193 quad_perm:[2,3,0,1] row_mask:0xf bank_mask:0xf bound_ctrl:1
	v_add_f32_dpp v194, v194, v194 quad_perm:[2,3,0,1] row_mask:0xf bank_mask:0xf bound_ctrl:1
	v_add_f32_dpp v195, v195, v195 quad_perm:[2,3,0,1] row_mask:0xf bank_mask:0xf bound_ctrl:1
	v_pk_fma_f32 v[102:103], v[144:145], v[122:123], v[102:103] op_sel:[0,1,0] op_sel_hi:[1,1,1]
	v_pk_fma_f32 v[104:105], v[144:145], v[124:125], v[104:105] op_sel:[0,0,0] op_sel_hi:[1,0,1]
	v_pk_fma_f32 v[106:107], v[144:145], v[124:125], v[106:107] op_sel:[0,1,0] op_sel_hi:[1,1,1]
	v_add_f32_dpp v192, v192, v192 row_half_mirror row_mask:0xf bank_mask:0xf bound_ctrl:1
	v_add_f32_dpp v193, v193, v193 row_half_mirror row_mask:0xf bank_mask:0xf bound_ctrl:1
	v_add_f32_dpp v194, v194, v194 row_half_mirror row_mask:0xf bank_mask:0xf bound_ctrl:1
	v_add_f32_dpp v195, v195, v195 row_half_mirror row_mask:0xf bank_mask:0xf bound_ctrl:1
	v_pk_fma_f32 v[108:109], v[144:145], v[126:127], v[108:109] op_sel:[0,0,0] op_sel_hi:[1,0,1]
	s_mov_b64 exec, s[10:11]
	ds_write_b64 v45, v[192:193] offset:2304
	s_mov_b64 exec, s[0:1]
	v_pk_fma_f32 v[110:111], v[144:145], v[126:127], v[110:111] op_sel:[0,1,0] op_sel_hi:[1,1,1]
	s_nop 0
	v_pk_fma_f32 v[96:97], v[194:195], v[128:129], v[96:97] op_sel:[0,0,0] op_sel_hi:[1,0,1]
	v_pk_fma_f32 v[98:99], v[194:195], v[128:129], v[98:99] op_sel:[0,1,0] op_sel_hi:[1,1,1]
	v_pk_fma_f32 v[100:101], v[194:195], v[130:131], v[100:101] op_sel:[0,0,0] op_sel_hi:[1,0,1]
	v_pk_fma_f32 v[102:103], v[194:195], v[130:131], v[102:103] op_sel:[0,1,0] op_sel_hi:[1,1,1]
	v_pk_fma_f32 v[104:105], v[194:195], v[132:133], v[104:105] op_sel:[0,0,0] op_sel_hi:[1,0,1]
	v_pk_fma_f32 v[106:107], v[194:195], v[132:133], v[106:107] op_sel:[0,1,0] op_sel_hi:[1,1,1]
	v_pk_fma_f32 v[108:109], v[194:195], v[134:135], v[108:109] op_sel:[0,0,0] op_sel_hi:[1,0,1]
	v_pk_fma_f32 v[110:111], v[194:195], v[134:135], v[110:111] op_sel:[0,1,0] op_sel_hi:[1,1,1]
	v_pk_mul_f32 v[184:185], v[96:97], v[136:137] op_sel:[0,0] op_sel_hi:[1,0]
	v_pk_mul_f32 v[188:189], v[96:97], v[156:157] op_sel:[0,0] op_sel_hi:[1,0]
	v_pk_mul_f32 v[186:187], v[98:99], v[136:137] op_sel:[0,1] op_sel_hi:[1,1]
	v_pk_mul_f32 v[190:191], v[98:99], v[156:157] op_sel:[0,1] op_sel_hi:[1,1]
	v_pk_fma_f32 v[184:185], v[100:101], v[138:139], v[184:185] op_sel:[0,0,0] op_sel_hi:[1,0,1]
	v_pk_fma_f32 v[188:189], v[100:101], v[158:159], v[188:189] op_sel:[0,0,0] op_sel_hi:[1,0,1]
	v_pk_fma_f32 v[186:187], v[102:103], v[138:139], v[186:187] op_sel:[0,1,0] op_sel_hi:[1,1,1]
	v_pk_fma_f32 v[190:191], v[102:103], v[158:159], v[190:191] op_sel:[0,1,0] op_sel_hi:[1,1,1]
	v_pk_fma_f32 v[184:185], v[104:105], v[140:141], v[184:185] op_sel:[0,0,0] op_sel_hi:[1,0,1]
	v_pk_fma_f32 v[188:189], v[104:105], v[160:161], v[188:189] op_sel:[0,0,0] op_sel_hi:[1,0,1]
	v_pk_fma_f32 v[186:187], v[106:107], v[140:141], v[186:187] op_sel:[0,1,0] op_sel_hi:[1,1,1]
	v_pk_fma_f32 v[190:191], v[106:107], v[160:161], v[190:191] op_sel:[0,1,0] op_sel_hi:[1,1,1]
	v_pk_fma_f32 v[184:185], v[108:109], v[142:143], v[184:185] op_sel:[0,0,0] op_sel_hi:[1,0,1]
	v_pk_fma_f32 v[188:189], v[108:109], v[162:163], v[188:189] op_sel:[0,0,0] op_sel_hi:[1,0,1]
	v_pk_fma_f32 v[186:187], v[110:111], v[142:143], v[186:187] op_sel:[0,1,0] op_sel_hi:[1,1,1]
	v_pk_fma_f32 v[190:191], v[110:111], v[162:163], v[190:191] op_sel:[0,1,0] op_sel_hi:[1,1,1]
	v_pk_add_f32 v[192:193], v[184:185], v[186:187]
	v_pk_add_f32 v[194:195], v[188:189], v[190:191]
	ds_read_b128 v[120:123], v44 offset:18688
	ds_read_b128 v[124:127], v44 offset:18704
	ds_read_b128 v[128:131], v44 offset:19200
	ds_read_b128 v[132:135], v44 offset:19216
	ds_read_b128 v[136:139], v44 offset:19456
	ds_read_b128 v[140:143], v44 offset:19472
	ds_read_b64 v[144:145], v46 offset:18432
	ds_read_b128 v[156:159], v44 offset:20480
	ds_read_b128 v[160:163], v44 offset:20496
	s_waitcnt lgkmcnt(10)
; #define LAS __attribute__((address_space(3)))
; __device__ __forceinline__ float red8(float x) { x += dpp_mov<0xB1>(x); x += dpp_mov<0x4E>(x); x += dpp_mov<0x141>(x); return x; }
; __device__ __forceinline__ void scan_phase(const KP& P, LAS unsigned char* lds, const int tid, const int bx, const int G) {
;     ...
;             for (int s = 0; s < 32; ++s) {
;                 const LAS float* p = cb + s * 384;
;                 const f32x4 w0 = *(const LAS f32x4*)(p), w1 = *(const LAS f32x4*)(p + 4);
;                 const f32x4 k0 = *(const LAS f32x4*)(p + 64), k1 = *(const LAS f32x4*)(p + 68);
;                 const f32x4 a0 = *(const LAS f32x4*)(p + 128), a1 = *(const LAS f32x4*)(p + 132);
;                 const f32x4 b0 = *(const LAS f32x4*)(p + 192), b1 = *(const LAS f32x4*)(p + 196);
;                 const f32x4 r0 = *(const LAS f32x4*)(p + 256), r1 = *(const LAS f32x4*)(p + 260);
;                 const float vv = buf[(c & 1) * 12288 + s * 384 + 320 + v];
;                 f32x2 sa2 = S[0] * (f32x2){a0.x, a0.y};
;                 sa2 += S[1] * (f32x2){a0.z, a0.w}; sa2 += S[2] * (f32x2){a1.x, a1.y}; sa2 += S[3] * (f32x2){a1.z, a1.w};
;                 const float sa = red8(sa2.x + sa2.y);
;                 const f32x2 sav = {sa, sa}, vv2 = {vv, vv};
;                 S[0] = S[0] * (f32x2){w0.x, w0.y} + sav * (f32x2){b0.x, b0.y} + vv2 * (f32x2){k0.x, k0.y};
;                 S[1] = S[1] * (f32x2){w0.z, w0.w} + sav * (f32x2){b0.z, b0.w} + vv2 * (f32x2){k0.z, k0.w};
;                 S[2] = S[2] * (f32x2){w1.x, w1.y} + sav * (f32x2){b1.x, b1.y} + vv2 * (f32x2){k1.x, k1.y};
;                 S[3] = S[3] * (f32x2){w1.z, w1.w} + sav * (f32x2){b1.z, b1.w} + vv2 * (f32x2){k1.z, k1.w};
;                 f32x2 y2 = S[0] * (f32x2){r0.x, r0.y};
;                 y2 += S[1] * (f32x2){r0.z, r0.w}; y2 += S[2] * (f32x2){r1.x, r1.y}; y2 += S[3] * (f32x2){r1.z, r1.w};
;                 const float y = red8(y2.x + y2.y);
;                 if (kc == 0) ybuf[s * 64 + v] = y;
	v_add_f32_dpp v192, v192, v192 quad_perm:[1,0,3,2] row_mask:0xf bank_mask:0xf bound_ctrl:1
	v_add_f32_dpp v193, v193, v193 quad_perm:[1,0,3,2] row_mask:0xf bank_mask:0xf bound_ctrl:1
	v_add_f32_dpp v194, v194, v194 quad_perm:[1,0,3,2] row_mask:0xf bank_mask:0xf bound_ctrl:1
	v_add_f32_dpp v195, v195, v195 quad_perm:[1,0,3,2] row_mask:0xf bank_mask:0xf bound_ctrl:1
	v_pk_fma_f32 v[96:97], v[146:147], v[70:71], v[96:97] op_sel:[0,0,0] op_sel_hi:[1,0,1]
	v_pk_fma_f32 v[98:99], v[146:147], v[70:71], v[98:99] op_sel:[0,1,0] op_sel_hi:[1,1,1]
	v_pk_fma_f32 v[100:101], v[146:147], v[72:73], v[100:101] op_sel:[0,0,0] op_sel_hi:[1,0,1]
	v_add_f32_dpp v192, v192, v192 quad_perm:[2,3,0,1] row_mask:0xf bank_mask:0xf bound_ctrl:1
	v_add_f32_dpp v193, v193, v193 quad_perm:[2,3,0,1] row_mask:0xf bank_mask:0xf bound_ctrl:1
	v_add_f32_dpp v194, v194, v194 quad_perm:[2,3,0,1] row_mask:0xf bank_mask:0xf bound_ctrl:1
	v_add_f32_dpp v195, v195, v195 quad_perm:[2,3,0,1] row_mask:0xf bank_mask:0xf bound_ctrl:1
	v_pk_fma_f32 v[102:103], v[146:147], v[72:73], v[102:103] op_sel:[0,1,0] op_sel_hi:[1,1,1]
	v_pk_fma_f32 v[104:105], v[146:147], v[74:75], v[104:105] op_sel:[0,0,0] op_sel_hi:[1,0,1]
	v_pk_fma_f32 v[106:107], v[146:147], v[74:75], v[106:107] op_sel:[0,1,0] op_sel_hi:[1,1,1]
	v_add_f32_dpp v192, v192, v192 row_half_mirror row_mask:0xf bank_mask:0xf bound_ctrl:1
	v_add_f32_dpp v193, v193, v193 row_half_mirror row_mask:0xf bank_mask:0xf bound_ctrl:1
	v_add_f32_dpp v194, v194, v194 row_half_mirror row_mask:0xf bank_mask:0xf bound_ctrl:1
	v_add_f32_dpp v195, v195, v195 row_half_mirror row_mask:0xf bank_mask:0xf bound_ctrl:1
	v_pk_fma_f32 v[108:109], v[146:147], v[76:77], v[108:109] op_sel:[0,0,0] op_sel_hi:[1,0,1]
	s_mov_b64 exec, s[10:11]
	ds_write_b64 v45, v[192:193] offset:2560
	s_mov_b64 exec, s[0:1]
	v_pk_fma_f32 v[110:111], v[146:147], v[76:77], v[110:111] op_sel:[0,1,0] op_sel_hi:[1,1,1]
	s_nop 0
	v_pk_fma_f32 v[96:97], v[194:195], v[78:79], v[96:97] op_sel:[0,0,0] op_sel_hi:[1,0,1]
	v_pk_fma_f32 v[98:99], v[194:195], v[78:79], v[98:99] op_sel:[0,1,0] op_sel_hi:[1,1,1]
	v_pk_fma_f32 v[100:101], v[194:195], v[80:81], v[100:101] op_sel:[0,0,0] op_sel_hi:[1,0,1]
	v_pk_fma_f32 v[102:103], v[194:195], v[80:81], v[102:103] op_sel:[0,1,0] op_sel_hi:[1,1,1]
	v_pk_fma_f32 v[104:105], v[194:195], v[82:83], v[104:105] op_sel:[0,0,0] op_sel_hi:[1,0,1]
	v_pk_fma_f32 v[106:107], v[194:195], v[82:83], v[106:107] op_sel:[0,1,0] op_sel_hi:[1,1,1]
	v_pk_fma_f32 v[108:109], v[194:195], v[84:85], v[108:109] op_sel:[0,0,0] op_sel_hi:[1,0,1]
	v_pk_fma_f32 v[110:111], v[194:195], v[84:85], v[110:111] op_sel:[0,1,0] op_sel_hi:[1,1,1]
	v_pk_mul_f32 v[184:185], v[96:97], v[86:87] op_sel:[0,0] op_sel_hi:[1,0]
	v_pk_mul_f32 v[188:189], v[96:97], v[148:149] op_sel:[0,0] op_sel_hi:[1,0]
	v_pk_mul_f32 v[186:187], v[98:99], v[86:87] op_sel:[0,1] op_sel_hi:[1,1]
	v_pk_mul_f32 v[190:191], v[98:99], v[148:149] op_sel:[0,1] op_sel_hi:[1,1]
	v_pk_fma_f32 v[184:185], v[100:101], v[88:89], v[184:185] op_sel:[0,0,0] op_sel_hi:[1,0,1]
	v_pk_fma_f32 v[188:189], v[100:101], v[150:151], v[188:189] op_sel:[0,0,0] op_sel_hi:[1,0,1]
	v_pk_fma_f32 v[186:187], v[102:103], v[88:89], v[186:187] op_sel:[0,1,0] op_sel_hi:[1,1,1]
	v_pk_fma_f32 v[190:191], v[102:103], v[150:151], v[190:191] op_sel:[0,1,0] op_sel_hi:[1,1,1]
	v_pk_fma_f32 v[184:185], v[104:105], v[90:91], v[184:185] op_sel:[0,0,0] op_sel_hi:[1,0,1]
	v_pk_fma_f32 v[188:189], v[104:105], v[152:153], v[188:189] op_sel:[0,0,0] op_sel_hi:[1,0,1]
	v_pk_fma_f32 v[186:187], v[106:107], v[90:91], v[186:187] op_sel:[0,1,0] op_sel_hi:[1,1,1]
	v_pk_fma_f32 v[190:191], v[106:107], v[152:153], v[190:191] op_sel:[0,1,0] op_sel_hi:[1,1,1]
	v_pk_fma_f32 v[184:185], v[108:109], v[92:93], v[184:185] op_sel:[0,0,0] op_sel_hi:[1,0,1]
	v_pk_fma_f32 v[188:189], v[108:109], v[154:155], v[188:189] op_sel:[0,0,0] op_sel_hi:[1,0,1]
	v_pk_fma_f32 v[186:187], v[110:111], v[92:93], v[186:187] op_sel:[0,1,0] op_sel_hi:[1,1,1]
	v_pk_fma_f32 v[190:191], v[110:111], v[154:155], v[190:191] op_sel:[0,1,0] op_sel_hi:[1,1,1]
	v_pk_add_f32 v[192:193], v[184:185], v[186:187]
	v_pk_add_f32 v[194:195], v[188:189], v[190:191]
	ds_read_b128 v[70:73], v44 offset:20224
	ds_read_b128 v[74:77], v44 offset:20240
	ds_read_b128 v[78:81], v44 offset:20736
	ds_read_b128 v[82:85], v44 offset:20752
	ds_read_b128 v[86:89], v44 offset:20992
	ds_read_b128 v[90:93], v44 offset:21008
	ds_read_b64 v[146:147], v46 offset:19968
	ds_read_b128 v[148:151], v44 offset:22016
	ds_read_b128 v[152:155], v44 offset:22032
	s_waitcnt lgkmcnt(10)
; #define LAS __attribute__((address_space(3)))
; __device__ __forceinline__ float red8(float x) { x += dpp_mov<0xB1>(x); x += dpp_mov<0x4E>(x); x += dpp_mov<0x141>(x); return x; }
; __device__ __forceinline__ void scan_phase(const KP& P, LAS unsigned char* lds, const int tid, const int bx, const int G) {
;     ...
;             for (int s = 0; s < 32; ++s) {
;                 const LAS float* p = cb + s * 384;
;                 const f32x4 w0 = *(const LAS f32x4*)(p), w1 = *(const LAS f32x4*)(p + 4);
;                 const f32x4 k0 = *(const LAS f32x4*)(p + 64), k1 = *(const LAS f32x4*)(p + 68);
;                 const f32x4 a0 = *(const LAS f32x4*)(p + 128), a1 = *(const LAS f32x4*)(p + 132);
;                 const f32x4 b0 = *(const LAS f32x4*)(p + 192), b1 = *(const LAS f32x4*)(p + 196);
;                 const f32x4 r0 = *(const LAS f32x4*)(p + 256), r1 = *(const LAS f32x4*)(p + 260);
;                 const float vv = buf[(c & 1) * 12288 + s * 384 + 320 + v];
;                 f32x2 sa2 = S[0] * (f32x2){a0.x, a0.y};
;                 sa2 += S[1] * (f32x2){a0.z, a0.w}; sa2 += S[2] * (f32x2){a1.x, a1.y}; sa2 += S[3] * (f32x2){a1.z, a1.w};
;                 const float sa = red8(sa2.x + sa2.y);
;                 const f32x2 sav = {sa, sa}, vv2 = {vv, vv};
;                 S[0] = S[0] * (f32x2){w0.x, w0.y} + sav * (f32x2){b0.x, b0.y} + vv2 * (f32x2){k0.x, k0.y};
;                 S[1] = S[1] * (f32x2){w0.z, w0.w} + sav * (f32x2){b0.z, b0.w} + vv2 * (f32x2){k0.z, k0.w};
;                 S[2] = S[2] * (f32x2){w1.x, w1.y} + sav * (f32x2){b1.x, b1.y} + vv2 * (f32x2){k1.x, k1.y};
;                 S[3] = S[3] * (f32x2){w1.z, w1.w} + sav * (f32x2){b1.z, b1.w} + vv2 * (f32x2){k1.z, k1.w};
;                 f32x2 y2 = S[0] * (f32x2){r0.x, r0.y};
;                 y2 += S[1] * (f32x2){r0.z, r0.w}; y2 += S[2] * (f32x2){r1.x, r1.y}; y2 += S[3] * (f32x2){r1.z, r1.w};
;                 const float y = red8(y2.x + y2.y);
;                 if (kc == 0) ybuf[s * 64 + v] = y;
	v_add_f32_dpp v192, v192, v192 quad_perm:[1,0,3,2] row_mask:0xf bank_mask:0xf bound_ctrl:1
	v_add_f32_dpp v193, v193, v193 quad_perm:[1,0,3,2] row_mask:0xf bank_mask:0xf bound_ctrl:1
	v_add_f32_dpp v194, v194, v194 quad_perm:[1,0,3,2] row_mask:0xf bank_mask:0xf bound_ctrl:1
	v_add_f32_dpp v195, v195, v195 quad_perm:[1,0,3,2] row_mask:0xf bank_mask:0xf bound_ctrl:1
	v_pk_fma_f32 v[96:97], v[144:145], v[120:121], v[96:97] op_sel:[0,0,0] op_sel_hi:[1,0,1]
	v_pk_fma_f32 v[98:99], v[144:145], v[120:121], v[98:99] op_sel:[0,1,0] op_sel_hi:[1,1,1]
	v_pk_fma_f32 v[100:101], v[144:145], v[122:123], v[100:101] op_sel:[0,0,0] op_sel_hi:[1,0,1]
	v_add_f32_dpp v192, v192, v192 quad_perm:[2,3,0,1] row_mask:0xf bank_mask:0xf bound_ctrl:1
	v_add_f32_dpp v193, v193, v193 quad_perm:[2,3,0,1] row_mask:0xf bank_mask:0xf bound_ctrl:1
	v_add_f32_dpp v194, v194, v194 quad_perm:[2,3,0,1] row_mask:0xf bank_mask:0xf bound_ctrl:1
	v_add_f32_dpp v195, v195, v195 quad_perm:[2,3,0,1] row_mask:0xf bank_mask:0xf bound_ctrl:1
	v_pk_fma_f32 v[102:103], v[144:145], v[122:123], v[102:103] op_sel:[0,1,0] op_sel_hi:[1,1,1]
	v_pk_fma_f32 v[104:105], v[144:145], v[124:125], v[104:105] op_sel:[0,0,0] op_sel_hi:[1,0,1]
	v_pk_fma_f32 v[106:107], v[144:145], v[124:125], v[106:107] op_sel:[0,1,0] op_sel_hi:[1,1,1]
	v_add_f32_dpp v192, v192, v192 row_half_mirror row_mask:0xf bank_mask:0xf bound_ctrl:1
	v_add_f32_dpp v193, v193, v193 row_half_mirror row_mask:0xf bank_mask:0xf bound_ctrl:1
	v_add_f32_dpp v194, v194, v194 row_half_mirror row_mask:0xf bank_mask:0xf bound_ctrl:1
	v_add_f32_dpp v195, v195, v195 row_half_mirror row_mask:0xf bank_mask:0xf bound_ctrl:1
	v_pk_fma_f32 v[108:109], v[144:145], v[126:127], v[108:109] op_sel:[0,0,0] op_sel_hi:[1,0,1]
	s_mov_b64 exec, s[10:11]
	ds_write_b64 v45, v[192:193] offset:2816
	s_mov_b64 exec, s[0:1]
	v_pk_fma_f32 v[110:111], v[144:145], v[126:127], v[110:111] op_sel:[0,1,0] op_sel_hi:[1,1,1]
	s_nop 0
	v_pk_fma_f32 v[96:97], v[194:195], v[128:129], v[96:97] op_sel:[0,0,0] op_sel_hi:[1,0,1]
	v_pk_fma_f32 v[98:99], v[194:195], v[128:129], v[98:99] op_sel:[0,1,0] op_sel_hi:[1,1,1]
	v_pk_fma_f32 v[100:101], v[194:195], v[130:131], v[100:101] op_sel:[0,0,0] op_sel_hi:[1,0,1]
	v_pk_fma_f32 v[102:103], v[194:195], v[130:131], v[102:103] op_sel:[0,1,0] op_sel_hi:[1,1,1]
	v_pk_fma_f32 v[104:105], v[194:195], v[132:133], v[104:105] op_sel:[0,0,0] op_sel_hi:[1,0,1]
	v_pk_fma_f32 v[106:107], v[194:195], v[132:133], v[106:107] op_sel:[0,1,0] op_sel_hi:[1,1,1]
	v_pk_fma_f32 v[108:109], v[194:195], v[134:135], v[108:109] op_sel:[0,0,0] op_sel_hi:[1,0,1]
	v_pk_fma_f32 v[110:111], v[194:195], v[134:135], v[110:111] op_sel:[0,1,0] op_sel_hi:[1,1,1]
	v_pk_mul_f32 v[184:185], v[96:97], v[136:137] op_sel:[0,0] op_sel_hi:[1,0]
	v_pk_mul_f32 v[188:189], v[96:97], v[156:157] op_sel:[0,0] op_sel_hi:[1,0]
	v_pk_mul_f32 v[186:187], v[98:99], v[136:137] op_sel:[0,1] op_sel_hi:[1,1]
	v_pk_mul_f32 v[190:191], v[98:99], v[156:157] op_sel:[0,1] op_sel_hi:[1,1]
	v_pk_fma_f32 v[184:185], v[100:101], v[138:139], v[184:185] op_sel:[0,0,0] op_sel_hi:[1,0,1]
	v_pk_fma_f32 v[188:189], v[100:101], v[158:159], v[188:189] op_sel:[0,0,0] op_sel_hi:[1,0,1]
	v_pk_fma_f32 v[186:187], v[102:103], v[138:139], v[186:187] op_sel:[0,1,0] op_sel_hi:[1,1,1]
	v_pk_fma_f32 v[190:191], v[102:103], v[158:159], v[190:191] op_sel:[0,1,0] op_sel_hi:[1,1,1]
	v_pk_fma_f32 v[184:185], v[104:105], v[140:141], v[184:185] op_sel:[0,0,0] op_sel_hi:[1,0,1]
	v_pk_fma_f32 v[188:189], v[104:105], v[160:161], v[188:189] op_sel:[0,0,0] op_sel_hi:[1,0,1]
	v_pk_fma_f32 v[186:187], v[106:107], v[140:141], v[186:187] op_sel:[0,1,0] op_sel_hi:[1,1,1]
	v_pk_fma_f32 v[190:191], v[106:107], v[160:161], v[190:191] op_sel:[0,1,0] op_sel_hi:[1,1,1]
	v_pk_fma_f32 v[184:185], v[108:109], v[142:143], v[184:185] op_sel:[0,0,0] op_sel_hi:[1,0,1]
	v_pk_fma_f32 v[188:189], v[108:109], v[162:163], v[188:189] op_sel:[0,0,0] op_sel_hi:[1,0,1]
	v_pk_fma_f32 v[186:187], v[110:111], v[142:143], v[186:187] op_sel:[0,1,0] op_sel_hi:[1,1,1]
	v_pk_fma_f32 v[190:191], v[110:111], v[162:163], v[190:191] op_sel:[0,1,0] op_sel_hi:[1,1,1]
	v_pk_add_f32 v[192:193], v[184:185], v[186:187]
	v_pk_add_f32 v[194:195], v[188:189], v[190:191]
	ds_read_b128 v[120:123], v44 offset:21760
	ds_read_b128 v[124:127], v44 offset:21776
	ds_read_b128 v[128:131], v44 offset:22272
	ds_read_b128 v[132:135], v44 offset:22288
	ds_read_b128 v[136:139], v44 offset:22528
	ds_read_b128 v[140:143], v44 offset:22544
	ds_read_b64 v[144:145], v46 offset:21504
	ds_read_b128 v[156:159], v44 offset:23552
	ds_read_b128 v[160:163], v44 offset:23568
	s_waitcnt lgkmcnt(10)
; #define LAS __attribute__((address_space(3)))
; __device__ __forceinline__ float red8(float x) { x += dpp_mov<0xB1>(x); x += dpp_mov<0x4E>(x); x += dpp_mov<0x141>(x); return x; }
; __device__ __forceinline__ void scan_phase(const KP& P, LAS unsigned char* lds, const int tid, const int bx, const int G) {
;     ...
;             for (int s = 0; s < 32; ++s) {
;                 const LAS float* p = cb + s * 384;
;                 const f32x4 w0 = *(const LAS f32x4*)(p), w1 = *(const LAS f32x4*)(p + 4);
;                 const f32x4 k0 = *(const LAS f32x4*)(p + 64), k1 = *(const LAS f32x4*)(p + 68);
;                 const f32x4 a0 = *(const LAS f32x4*)(p + 128), a1 = *(const LAS f32x4*)(p + 132);
;                 const f32x4 b0 = *(const LAS f32x4*)(p + 192), b1 = *(const LAS f32x4*)(p + 196);
;                 const f32x4 r0 = *(const LAS f32x4*)(p + 256), r1 = *(const LAS f32x4*)(p + 260);
;                 const float vv = buf[(c & 1) * 12288 + s * 384 + 320 + v];
;                 f32x2 sa2 = S[0] * (f32x2){a0.x, a0.y};
;                 sa2 += S[1] * (f32x2){a0.z, a0.w}; sa2 += S[2] * (f32x2){a1.x, a1.y}; sa2 += S[3] * (f32x2){a1.z, a1.w};
;                 const float sa = red8(sa2.x + sa2.y);
;                 const f32x2 sav = {sa, sa}, vv2 = {vv, vv};
;                 S[0] = S[0] * (f32x2){w0.x, w0.y} + sav * (f32x2){b0.x, b0.y} + vv2 * (f32x2){k0.x, k0.y};
;                 S[1] = S[1] * (f32x2){w0.z, w0.w} + sav * (f32x2){b0.z, b0.w} + vv2 * (f32x2){k0.z, k0.w};
;                 S[2] = S[2] * (f32x2){w1.x, w1.y} + sav * (f32x2){b1.x, b1.y} + vv2 * (f32x2){k1.x, k1.y};
;                 S[3] = S[3] * (f32x2){w1.z, w1.w} + sav * (f32x2){b1.z, b1.w} + vv2 * (f32x2){k1.z, k1.w};
;                 f32x2 y2 = S[0] * (f32x2){r0.x, r0.y};
;                 y2 += S[1] * (f32x2){r0.z, r0.w}; y2 += S[2] * (f32x2){r1.x, r1.y}; y2 += S[3] * (f32x2){r1.z, r1.w};
;                 const float y = red8(y2.x + y2.y);
;                 if (kc == 0) ybuf[s * 64 + v] = y;
	v_add_f32_dpp v192, v192, v192 quad_perm:[1,0,3,2] row_mask:0xf bank_mask:0xf bound_ctrl:1
	v_add_f32_dpp v193, v193, v193 quad_perm:[1,0,3,2] row_mask:0xf bank_mask:0xf bound_ctrl:1
	v_add_f32_dpp v194, v194, v194 quad_perm:[1,0,3,2] row_mask:0xf bank_mask:0xf bound_ctrl:1
	v_add_f32_dpp v195, v195, v195 quad_perm:[1,0,3,2] row_mask:0xf bank_mask:0xf bound_ctrl:1
	v_pk_fma_f32 v[96:97], v[146:147], v[70:71], v[96:97] op_sel:[0,0,0] op_sel_hi:[1,0,1]
	v_pk_fma_f32 v[98:99], v[146:147], v[70:71], v[98:99] op_sel:[0,1,0] op_sel_hi:[1,1,1]
	v_pk_fma_f32 v[100:101], v[146:147], v[72:73], v[100:101] op_sel:[0,0,0] op_sel_hi:[1,0,1]
	v_add_f32_dpp v192, v192, v192 quad_perm:[2,3,0,1] row_mask:0xf bank_mask:0xf bound_ctrl:1
	v_add_f32_dpp v193, v193, v193 quad_perm:[2,3,0,1] row_mask:0xf bank_mask:0xf bound_ctrl:1
	v_add_f32_dpp v194, v194, v194 quad_perm:[2,3,0,1] row_mask:0xf bank_mask:0xf bound_ctrl:1
	v_add_f32_dpp v195, v195, v195 quad_perm:[2,3,0,1] row_mask:0xf bank_mask:0xf bound_ctrl:1
	v_pk_fma_f32 v[102:103], v[146:147], v[72:73], v[102:103] op_sel:[0,1,0] op_sel_hi:[1,1,1]
	v_pk_fma_f32 v[104:105], v[146:147], v[74:75], v[104:105] op_sel:[0,0,0] op_sel_hi:[1,0,1]
	v_pk_fma_f32 v[106:107], v[146:147], v[74:75], v[106:107] op_sel:[0,1,0] op_sel_hi:[1,1,1]
	v_add_f32_dpp v192, v192, v192 row_half_mirror row_mask:0xf bank_mask:0xf bound_ctrl:1
	v_add_f32_dpp v193, v193, v193 row_half_mirror row_mask:0xf bank_mask:0xf bound_ctrl:1
	v_add_f32_dpp v194, v194, v194 row_half_mirror row_mask:0xf bank_mask:0xf bound_ctrl:1
	v_add_f32_dpp v195, v195, v195 row_half_mirror row_mask:0xf bank_mask:0xf bound_ctrl:1
	v_pk_fma_f32 v[108:109], v[146:147], v[76:77], v[108:109] op_sel:[0,0,0] op_sel_hi:[1,0,1]
	s_mov_b64 exec, s[10:11]
	ds_write_b64 v45, v[192:193] offset:3072
	s_mov_b64 exec, s[0:1]
	v_pk_fma_f32 v[110:111], v[146:147], v[76:77], v[110:111] op_sel:[0,1,0] op_sel_hi:[1,1,1]
	s_nop 0
	v_pk_fma_f32 v[96:97], v[194:195], v[78:79], v[96:97] op_sel:[0,0,0] op_sel_hi:[1,0,1]
	v_pk_fma_f32 v[98:99], v[194:195], v[78:79], v[98:99] op_sel:[0,1,0] op_sel_hi:[1,1,1]
	v_pk_fma_f32 v[100:101], v[194:195], v[80:81], v[100:101] op_sel:[0,0,0] op_sel_hi:[1,0,1]
	v_pk_fma_f32 v[102:103], v[194:195], v[80:81], v[102:103] op_sel:[0,1,0] op_sel_hi:[1,1,1]
	v_pk_fma_f32 v[104:105], v[194:195], v[82:83], v[104:105] op_sel:[0,0,0] op_sel_hi:[1,0,1]
	v_pk_fma_f32 v[106:107], v[194:195], v[82:83], v[106:107] op_sel:[0,1,0] op_sel_hi:[1,1,1]
	v_pk_fma_f32 v[108:109], v[194:195], v[84:85], v[108:109] op_sel:[0,0,0] op_sel_hi:[1,0,1]
	v_pk_fma_f32 v[110:111], v[194:195], v[84:85], v[110:111] op_sel:[0,1,0] op_sel_hi:[1,1,1]
	v_pk_mul_f32 v[184:185], v[96:97], v[86:87] op_sel:[0,0] op_sel_hi:[1,0]
	v_pk_mul_f32 v[188:189], v[96:97], v[148:149] op_sel:[0,0] op_sel_hi:[1,0]
	v_pk_mul_f32 v[186:187], v[98:99], v[86:87] op_sel:[0,1] op_sel_hi:[1,1]
	v_pk_mul_f32 v[190:191], v[98:99], v[148:149] op_sel:[0,1] op_sel_hi:[1,1]
	v_pk_fma_f32 v[184:185], v[100:101], v[88:89], v[184:185] op_sel:[0,0,0] op_sel_hi:[1,0,1]
	v_pk_fma_f32 v[188:189], v[100:101], v[150:151], v[188:189] op_sel:[0,0,0] op_sel_hi:[1,0,1]
	v_pk_fma_f32 v[186:187], v[102:103], v[88:89], v[186:187] op_sel:[0,1,0] op_sel_hi:[1,1,1]
	v_pk_fma_f32 v[190:191], v[102:103], v[150:151], v[190:191] op_sel:[0,1,0] op_sel_hi:[1,1,1]
	v_pk_fma_f32 v[184:185], v[104:105], v[90:91], v[184:185] op_sel:[0,0,0] op_sel_hi:[1,0,1]
	v_pk_fma_f32 v[188:189], v[104:105], v[152:153], v[188:189] op_sel:[0,0,0] op_sel_hi:[1,0,1]
	v_pk_fma_f32 v[186:187], v[106:107], v[90:91], v[186:187] op_sel:[0,1,0] op_sel_hi:[1,1,1]
	v_pk_fma_f32 v[190:191], v[106:107], v[152:153], v[190:191] op_sel:[0,1,0] op_sel_hi:[1,1,1]
	v_pk_fma_f32 v[184:185], v[108:109], v[92:93], v[184:185] op_sel:[0,0,0] op_sel_hi:[1,0,1]
	v_pk_fma_f32 v[188:189], v[108:109], v[154:155], v[188:189] op_sel:[0,0,0] op_sel_hi:[1,0,1]
	v_pk_fma_f32 v[186:187], v[110:111], v[92:93], v[186:187] op_sel:[0,1,0] op_sel_hi:[1,1,1]
	v_pk_fma_f32 v[190:191], v[110:111], v[154:155], v[190:191] op_sel:[0,1,0] op_sel_hi:[1,1,1]
	v_pk_add_f32 v[192:193], v[184:185], v[186:187]
	v_pk_add_f32 v[194:195], v[188:189], v[190:191]
	ds_read_b128 v[70:73], v44 offset:23296
	ds_read_b128 v[74:77], v44 offset:23312
	ds_read_b128 v[78:81], v44 offset:23808
	ds_read_b128 v[82:85], v44 offset:23824
	ds_read_b128 v[86:89], v44 offset:24064
	ds_read_b128 v[90:93], v44 offset:24080
	ds_read_b64 v[146:147], v46 offset:23040
	ds_read_b128 v[148:151], v44 offset:25088
	ds_read_b128 v[152:155], v44 offset:25104
	s_waitcnt lgkmcnt(10)
; #define LAS __attribute__((address_space(3)))
; __device__ __forceinline__ float red8(float x) { x += dpp_mov<0xB1>(x); x += dpp_mov<0x4E>(x); x += dpp_mov<0x141>(x); return x; }
; __device__ __forceinline__ void scan_phase(const KP& P, LAS unsigned char* lds, const int tid, const int bx, const int G) {
;     ...
;             for (int s = 0; s < 32; ++s) {
;                 const LAS float* p = cb + s * 384;
;                 const f32x4 w0 = *(const LAS f32x4*)(p), w1 = *(const LAS f32x4*)(p + 4);
;                 const f32x4 k0 = *(const LAS f32x4*)(p + 64), k1 = *(const LAS f32x4*)(p + 68);
;                 const f32x4 a0 = *(const LAS f32x4*)(p + 128), a1 = *(const LAS f32x4*)(p + 132);
;                 const f32x4 b0 = *(const LAS f32x4*)(p + 192), b1 = *(const LAS f32x4*)(p + 196);
;                 const f32x4 r0 = *(const LAS f32x4*)(p + 256), r1 = *(const LAS f32x4*)(p + 260);
;                 const float vv = buf[(c & 1) * 12288 + s * 384 + 320 + v];
;                 f32x2 sa2 = S[0] * (f32x2){a0.x, a0.y};
;                 sa2 += S[1] * (f32x2){a0.z, a0.w}; sa2 += S[2] * (f32x2){a1.x, a1.y}; sa2 += S[3] * (f32x2){a1.z, a1.w};
;                 const float sa = red8(sa2.x + sa2.y);
;                 const f32x2 sav = {sa, sa}, vv2 = {vv, vv};
;                 S[0] = S[0] * (f32x2){w0.x, w0.y} + sav * (f32x2){b0.x, b0.y} + vv2 * (f32x2){k0.x, k0.y};
;                 S[1] = S[1] * (f32x2){w0.z, w0.w} + sav * (f32x2){b0.z, b0.w} + vv2 * (f32x2){k0.z, k0.w};
;                 S[2] = S[2] * (f32x2){w1.x, w1.y} + sav * (f32x2){b1.x, b1.y} + vv2 * (f32x2){k1.x, k1.y};
;                 S[3] = S[3] * (f32x2){w1.z, w1.w} + sav * (f32x2){b1.z, b1.w} + vv2 * (f32x2){k1.z, k1.w};
;                 f32x2 y2 = S[0] * (f32x2){r0.x, r0.y};
;                 y2 += S[1] * (f32x2){r0.z, r0.w}; y2 += S[2] * (f32x2){r1.x, r1.y}; y2 += S[3] * (f32x2){r1.z, r1.w};
;                 const float y = red8(y2.x + y2.y);
;                 if (kc == 0) ybuf[s * 64 + v] = y;
	v_add_f32_dpp v192, v192, v192 quad_perm:[1,0,3,2] row_mask:0xf bank_mask:0xf bound_ctrl:1
	v_add_f32_dpp v193, v193, v193 quad_perm:[1,0,3,2] row_mask:0xf bank_mask:0xf bound_ctrl:1
	v_add_f32_dpp v194, v194, v194 quad_perm:[1,0,3,2] row_mask:0xf bank_mask:0xf bound_ctrl:1
	v_add_f32_dpp v195, v195, v195 quad_perm:[1,0,3,2] row_mask:0xf bank_mask:0xf bound_ctrl:1
	v_pk_fma_f32 v[96:97], v[144:145], v[120:121], v[96:97] op_sel:[0,0,0] op_sel_hi:[1,0,1]
	v_pk_fma_f32 v[98:99], v[144:145], v[120:121], v[98:99] op_sel:[0,1,0] op_sel_hi:[1,1,1]
	v_pk_fma_f32 v[100:101], v[144:145], v[122:123], v[100:101] op_sel:[0,0,0] op_sel_hi:[1,0,1]
	v_add_f32_dpp v192, v192, v192 quad_perm:[2,3,0,1] row_mask:0xf bank_mask:0xf bound_ctrl:1
	v_add_f32_dpp v193, v193, v193 quad_perm:[2,3,0,1] row_mask:0xf bank_mask:0xf bound_ctrl:1
	v_add_f32_dpp v194, v194, v194 quad_perm:[2,3,0,1] row_mask:0xf bank_mask:0xf bound_ctrl:1
	v_add_f32_dpp v195, v195, v195 quad_perm:[2,3,0,1] row_mask:0xf bank_mask:0xf bound_ctrl:1
	v_pk_fma_f32 v[102:103], v[144:145], v[122:123], v[102:103] op_sel:[0,1,0] op_sel_hi:[1,1,1]
	v_pk_fma_f32 v[104:105], v[144:145], v[124:125], v[104:105] op_sel:[0,0,0] op_sel_hi:[1,0,1]
	v_pk_fma_f32 v[106:107], v[144:145], v[124:125], v[106:107] op_sel:[0,1,0] op_sel_hi:[1,1,1]
	v_add_f32_dpp v192, v192, v192 row_half_mirror row_mask:0xf bank_mask:0xf bound_ctrl:1
	v_add_f32_dpp v193, v193, v193 row_half_mirror row_mask:0xf bank_mask:0xf bound_ctrl:1
	v_add_f32_dpp v194, v194, v194 row_half_mirror row_mask:0xf bank_mask:0xf bound_ctrl:1
	v_add_f32_dpp v195, v195, v195 row_half_mirror row_mask:0xf bank_mask:0xf bound_ctrl:1
	v_pk_fma_f32 v[108:109], v[144:145], v[126:127], v[108:109] op_sel:[0,0,0] op_sel_hi:[1,0,1]
	s_mov_b64 exec, s[10:11]
	ds_write_b64 v45, v[192:193] offset:3328
	s_mov_b64 exec, s[0:1]
	v_pk_fma_f32 v[110:111], v[144:145], v[126:127], v[110:111] op_sel:[0,1,0] op_sel_hi:[1,1,1]
	s_nop 0
	v_pk_fma_f32 v[96:97], v[194:195], v[128:129], v[96:97] op_sel:[0,0,0] op_sel_hi:[1,0,1]
	v_pk_fma_f32 v[98:99], v[194:195], v[128:129], v[98:99] op_sel:[0,1,0] op_sel_hi:[1,1,1]
	v_pk_fma_f32 v[100:101], v[194:195], v[130:131], v[100:101] op_sel:[0,0,0] op_sel_hi:[1,0,1]
	v_pk_fma_f32 v[102:103], v[194:195], v[130:131], v[102:103] op_sel:[0,1,0] op_sel_hi:[1,1,1]
	v_pk_fma_f32 v[104:105], v[194:195], v[132:133], v[104:105] op_sel:[0,0,0] op_sel_hi:[1,0,1]
	v_pk_fma_f32 v[106:107], v[194:195], v[132:133], v[106:107] op_sel:[0,1,0] op_sel_hi:[1,1,1]
	v_pk_fma_f32 v[108:109], v[194:195], v[134:135], v[108:109] op_sel:[0,0,0] op_sel_hi:[1,0,1]
	v_pk_fma_f32 v[110:111], v[194:195], v[134:135], v[110:111] op_sel:[0,1,0] op_sel_hi:[1,1,1]
	v_pk_mul_f32 v[184:185], v[96:97], v[136:137] op_sel:[0,0] op_sel_hi:[1,0]
	v_pk_mul_f32 v[188:189], v[96:97], v[156:157] op_sel:[0,0] op_sel_hi:[1,0]
	v_pk_mul_f32 v[186:187], v[98:99], v[136:137] op_sel:[0,1] op_sel_hi:[1,1]
	v_pk_mul_f32 v[190:191], v[98:99], v[156:157] op_sel:[0,1] op_sel_hi:[1,1]
	v_pk_fma_f32 v[184:185], v[100:101], v[138:139], v[184:185] op_sel:[0,0,0] op_sel_hi:[1,0,1]
	v_pk_fma_f32 v[188:189], v[100:101], v[158:159], v[188:189] op_sel:[0,0,0] op_sel_hi:[1,0,1]
	v_pk_fma_f32 v[186:187], v[102:103], v[138:139], v[186:187] op_sel:[0,1,0] op_sel_hi:[1,1,1]
	v_pk_fma_f32 v[190:191], v[102:103], v[158:159], v[190:191] op_sel:[0,1,0] op_sel_hi:[1,1,1]
	v_pk_fma_f32 v[184:185], v[104:105], v[140:141], v[184:185] op_sel:[0,0,0] op_sel_hi:[1,0,1]
	v_pk_fma_f32 v[188:189], v[104:105], v[160:161], v[188:189] op_sel:[0,0,0] op_sel_hi:[1,0,1]
	v_pk_fma_f32 v[186:187], v[106:107], v[140:141], v[186:187] op_sel:[0,1,0] op_sel_hi:[1,1,1]
	v_pk_fma_f32 v[190:191], v[106:107], v[160:161], v[190:191] op_sel:[0,1,0] op_sel_hi:[1,1,1]
	v_pk_fma_f32 v[184:185], v[108:109], v[142:143], v[184:185] op_sel:[0,0,0] op_sel_hi:[1,0,1]
	v_pk_fma_f32 v[188:189], v[108:109], v[162:163], v[188:189] op_sel:[0,0,0] op_sel_hi:[1,0,1]
	v_pk_fma_f32 v[186:187], v[110:111], v[142:143], v[186:187] op_sel:[0,1,0] op_sel_hi:[1,1,1]
	v_pk_fma_f32 v[190:191], v[110:111], v[162:163], v[190:191] op_sel:[0,1,0] op_sel_hi:[1,1,1]
	v_pk_add_f32 v[192:193], v[184:185], v[186:187]
	v_pk_add_f32 v[194:195], v[188:189], v[190:191]
	ds_read_b128 v[120:123], v44 offset:24832
	ds_read_b128 v[124:127], v44 offset:24848
	ds_read_b128 v[128:131], v44 offset:25344
	ds_read_b128 v[132:135], v44 offset:25360
	ds_read_b128 v[136:139], v44 offset:25600
	ds_read_b128 v[140:143], v44 offset:25616
	ds_read_b64 v[144:145], v46 offset:24576
	ds_read_b128 v[156:159], v44 offset:26624
	ds_read_b128 v[160:163], v44 offset:26640
	s_waitcnt lgkmcnt(10)
; #define LAS __attribute__((address_space(3)))
; __device__ __forceinline__ float red8(float x) { x += dpp_mov<0xB1>(x); x += dpp_mov<0x4E>(x); x += dpp_mov<0x141>(x); return x; }
; __device__ __forceinline__ void scan_phase(const KP& P, LAS unsigned char* lds, const int tid, const int bx, const int G) {
;     ...
;             for (int s = 0; s < 32; ++s) {
;                 const LAS float* p = cb + s * 384;
;                 const f32x4 w0 = *(const LAS f32x4*)(p), w1 = *(const LAS f32x4*)(p + 4);
;                 const f32x4 k0 = *(const LAS f32x4*)(p + 64), k1 = *(const LAS f32x4*)(p + 68);
;                 const f32x4 a0 = *(const LAS f32x4*)(p + 128), a1 = *(const LAS f32x4*)(p + 132);
;                 const f32x4 b0 = *(const LAS f32x4*)(p + 192), b1 = *(const LAS f32x4*)(p + 196);
;                 const f32x4 r0 = *(const LAS f32x4*)(p + 256), r1 = *(const LAS f32x4*)(p + 260);
;                 const float vv = buf[(c & 1) * 12288 + s * 384 + 320 + v];
;                 f32x2 sa2 = S[0] * (f32x2){a0.x, a0.y};
;                 sa2 += S[1] * (f32x2){a0.z, a0.w}; sa2 += S[2] * (f32x2){a1.x, a1.y}; sa2 += S[3] * (f32x2){a1.z, a1.w};
;                 const float sa = red8(sa2.x + sa2.y);
;                 const f32x2 sav = {sa, sa}, vv2 = {vv, vv};
;                 S[0] = S[0] * (f32x2){w0.x, w0.y} + sav * (f32x2){b0.x, b0.y} + vv2 * (f32x2){k0.x, k0.y};
;                 S[1] = S[1] * (f32x2){w0.z, w0.w} + sav * (f32x2){b0.z, b0.w} + vv2 * (f32x2){k0.z, k0.w};
;                 S[2] = S[2] * (f32x2){w1.x, w1.y} + sav * (f32x2){b1.x, b1.y} + vv2 * (f32x2){k1.x, k1.y};
;                 S[3] = S[3] * (f32x2){w1.z, w1.w} + sav * (f32x2){b1.z, b1.w} + vv2 * (f32x2){k1.z, k1.w};
;                 f32x2 y2 = S[0] * (f32x2){r0.x, r0.y};
;                 y2 += S[1] * (f32x2){r0.z, r0.w}; y2 += S[2] * (f32x2){r1.x, r1.y}; y2 += S[3] * (f32x2){r1.z, r1.w};
;                 const float y = red8(y2.x + y2.y);
;                 if (kc == 0) ybuf[s * 64 + v] = y;
	v_add_f32_dpp v192, v192, v192 quad_perm:[1,0,3,2] row_mask:0xf bank_mask:0xf bound_ctrl:1
	v_add_f32_dpp v193, v193, v193 quad_perm:[1,0,3,2] row_mask:0xf bank_mask:0xf bound_ctrl:1
	v_add_f32_dpp v194, v194, v194 quad_perm:[1,0,3,2] row_mask:0xf bank_mask:0xf bound_ctrl:1
	v_add_f32_dpp v195, v195, v195 quad_perm:[1,0,3,2] row_mask:0xf bank_mask:0xf bound_ctrl:1
	v_pk_fma_f32 v[96:97], v[146:147], v[70:71], v[96:97] op_sel:[0,0,0] op_sel_hi:[1,0,1]
	v_pk_fma_f32 v[98:99], v[146:147], v[70:71], v[98:99] op_sel:[0,1,0] op_sel_hi:[1,1,1]
	v_pk_fma_f32 v[100:101], v[146:147], v[72:73], v[100:101] op_sel:[0,0,0] op_sel_hi:[1,0,1]
	v_add_f32_dpp v192, v192, v192 quad_perm:[2,3,0,1] row_mask:0xf bank_mask:0xf bound_ctrl:1
	v_add_f32_dpp v193, v193, v193 quad_perm:[2,3,0,1] row_mask:0xf bank_mask:0xf bound_ctrl:1
	v_add_f32_dpp v194, v194, v194 quad_perm:[2,3,0,1] row_mask:0xf bank_mask:0xf bound_ctrl:1
	v_add_f32_dpp v195, v195, v195 quad_perm:[2,3,0,1] row_mask:0xf bank_mask:0xf bound_ctrl:1
	v_pk_fma_f32 v[102:103], v[146:147], v[72:73], v[102:103] op_sel:[0,1,0] op_sel_hi:[1,1,1]
	v_pk_fma_f32 v[104:105], v[146:147], v[74:75], v[104:105] op_sel:[0,0,0] op_sel_hi:[1,0,1]
	v_pk_fma_f32 v[106:107], v[146:147], v[74:75], v[106:107] op_sel:[0,1,0] op_sel_hi:[1,1,1]
	v_add_f32_dpp v192, v192, v192 row_half_mirror row_mask:0xf bank_mask:0xf bound_ctrl:1
	v_add_f32_dpp v193, v193, v193 row_half_mirror row_mask:0xf bank_mask:0xf bound_ctrl:1
	v_add_f32_dpp v194, v194, v194 row_half_mirror row_mask:0xf bank_mask:0xf bound_ctrl:1
	v_add_f32_dpp v195, v195, v195 row_half_mirror row_mask:0xf bank_mask:0xf bound_ctrl:1
	v_pk_fma_f32 v[108:109], v[146:147], v[76:77], v[108:109] op_sel:[0,0,0] op_sel_hi:[1,0,1]
	s_mov_b64 exec, s[10:11]
	ds_write_b64 v45, v[192:193] offset:3584
	s_mov_b64 exec, s[0:1]
	v_pk_fma_f32 v[110:111], v[146:147], v[76:77], v[110:111] op_sel:[0,1,0] op_sel_hi:[1,1,1]
	s_nop 0
	v_pk_fma_f32 v[96:97], v[194:195], v[78:79], v[96:97] op_sel:[0,0,0] op_sel_hi:[1,0,1]
	v_pk_fma_f32 v[98:99], v[194:195], v[78:79], v[98:99] op_sel:[0,1,0] op_sel_hi:[1,1,1]
	v_pk_fma_f32 v[100:101], v[194:195], v[80:81], v[100:101] op_sel:[0,0,0] op_sel_hi:[1,0,1]
	v_pk_fma_f32 v[102:103], v[194:195], v[80:81], v[102:103] op_sel:[0,1,0] op_sel_hi:[1,1,1]
	v_pk_fma_f32 v[104:105], v[194:195], v[82:83], v[104:105] op_sel:[0,0,0] op_sel_hi:[1,0,1]
	v_pk_fma_f32 v[106:107], v[194:195], v[82:83], v[106:107] op_sel:[0,1,0] op_sel_hi:[1,1,1]
	v_pk_fma_f32 v[108:109], v[194:195], v[84:85], v[108:109] op_sel:[0,0,0] op_sel_hi:[1,0,1]
	v_pk_fma_f32 v[110:111], v[194:195], v[84:85], v[110:111] op_sel:[0,1,0] op_sel_hi:[1,1,1]
	v_pk_mul_f32 v[184:185], v[96:97], v[86:87] op_sel:[0,0] op_sel_hi:[1,0]
	v_pk_mul_f32 v[188:189], v[96:97], v[148:149] op_sel:[0,0] op_sel_hi:[1,0]
	v_pk_mul_f32 v[186:187], v[98:99], v[86:87] op_sel:[0,1] op_sel_hi:[1,1]
	v_pk_mul_f32 v[190:191], v[98:99], v[148:149] op_sel:[0,1] op_sel_hi:[1,1]
	v_pk_fma_f32 v[184:185], v[100:101], v[88:89], v[184:185] op_sel:[0,0,0] op_sel_hi:[1,0,1]
	v_pk_fma_f32 v[188:189], v[100:101], v[150:151], v[188:189] op_sel:[0,0,0] op_sel_hi:[1,0,1]
	v_pk_fma_f32 v[186:187], v[102:103], v[88:89], v[186:187] op_sel:[0,1,0] op_sel_hi:[1,1,1]
	v_pk_fma_f32 v[190:191], v[102:103], v[150:151], v[190:191] op_sel:[0,1,0] op_sel_hi:[1,1,1]
	v_pk_fma_f32 v[184:185], v[104:105], v[90:91], v[184:185] op_sel:[0,0,0] op_sel_hi:[1,0,1]
	v_pk_fma_f32 v[188:189], v[104:105], v[152:153], v[188:189] op_sel:[0,0,0] op_sel_hi:[1,0,1]
	v_pk_fma_f32 v[186:187], v[106:107], v[90:91], v[186:187] op_sel:[0,1,0] op_sel_hi:[1,1,1]
	v_pk_fma_f32 v[190:191], v[106:107], v[152:153], v[190:191] op_sel:[0,1,0] op_sel_hi:[1,1,1]
	v_pk_fma_f32 v[184:185], v[108:109], v[92:93], v[184:185] op_sel:[0,0,0] op_sel_hi:[1,0,1]
	v_pk_fma_f32 v[188:189], v[108:109], v[154:155], v[188:189] op_sel:[0,0,0] op_sel_hi:[1,0,1]
	v_pk_fma_f32 v[186:187], v[110:111], v[92:93], v[186:187] op_sel:[0,1,0] op_sel_hi:[1,1,1]
	v_pk_fma_f32 v[190:191], v[110:111], v[154:155], v[190:191] op_sel:[0,1,0] op_sel_hi:[1,1,1]
	v_pk_add_f32 v[192:193], v[184:185], v[186:187]
	v_pk_add_f32 v[194:195], v[188:189], v[190:191]
	ds_read_b128 v[70:73], v44 offset:26368
	ds_read_b128 v[74:77], v44 offset:26384
	ds_read_b128 v[78:81], v44 offset:26880
	ds_read_b128 v[82:85], v44 offset:26896
	ds_read_b128 v[86:89], v44 offset:27136
	ds_read_b128 v[90:93], v44 offset:27152
	ds_read_b64 v[146:147], v46 offset:26112
	ds_read_b128 v[148:151], v44 offset:28160
	ds_read_b128 v[152:155], v44 offset:28176
	s_waitcnt lgkmcnt(10)
; #define LAS __attribute__((address_space(3)))
; __device__ __forceinline__ float red8(float x) { x += dpp_mov<0xB1>(x); x += dpp_mov<0x4E>(x); x += dpp_mov<0x141>(x); return x; }
; __device__ __forceinline__ void scan_phase(const KP& P, LAS unsigned char* lds, const int tid, const int bx, const int G) {
;     ...
;             for (int s = 0; s < 32; ++s) {
;                 const LAS float* p = cb + s * 384;
;                 const f32x4 w0 = *(const LAS f32x4*)(p), w1 = *(const LAS f32x4*)(p + 4);
;                 const f32x4 k0 = *(const LAS f32x4*)(p + 64), k1 = *(const LAS f32x4*)(p + 68);
;                 const f32x4 a0 = *(const LAS f32x4*)(p + 128), a1 = *(const LAS f32x4*)(p + 132);
;                 const f32x4 b0 = *(const LAS f32x4*)(p + 192), b1 = *(const LAS f32x4*)(p + 196);
;                 const f32x4 r0 = *(const LAS f32x4*)(p + 256), r1 = *(const LAS f32x4*)(p + 260);
;                 const float vv = buf[(c & 1) * 12288 + s * 384 + 320 + v];
;                 f32x2 sa2 = S[0] * (f32x2){a0.x, a0.y};
;                 sa2 += S[1] * (f32x2){a0.z, a0.w}; sa2 += S[2] * (f32x2){a1.x, a1.y}; sa2 += S[3] * (f32x2){a1.z, a1.w};
;                 const float sa = red8(sa2.x + sa2.y);
;                 const f32x2 sav = {sa, sa}, vv2 = {vv, vv};
;                 S[0] = S[0] * (f32x2){w0.x, w0.y} + sav * (f32x2){b0.x, b0.y} + vv2 * (f32x2){k0.x, k0.y};
;                 S[1] = S[1] * (f32x2){w0.z, w0.w} + sav * (f32x2){b0.z, b0.w} + vv2 * (f32x2){k0.z, k0.w};
;                 S[2] = S[2] * (f32x2){w1.x, w1.y} + sav * (f32x2){b1.x, b1.y} + vv2 * (f32x2){k1.x, k1.y};
;                 S[3] = S[3] * (f32x2){w1.z, w1.w} + sav * (f32x2){b1.z, b1.w} + vv2 * (f32x2){k1.z, k1.w};
;                 f32x2 y2 = S[0] * (f32x2){r0.x, r0.y};
;                 y2 += S[1] * (f32x2){r0.z, r0.w}; y2 += S[2] * (f32x2){r1.x, r1.y}; y2 += S[3] * (f32x2){r1.z, r1.w};
;                 const float y = red8(y2.x + y2.y);
;                 if (kc == 0) ybuf[s * 64 + v] = y;
	v_add_f32_dpp v192, v192, v192 quad_perm:[1,0,3,2] row_mask:0xf bank_mask:0xf bound_ctrl:1
	v_add_f32_dpp v193, v193, v193 quad_perm:[1,0,3,2] row_mask:0xf bank_mask:0xf bound_ctrl:1
	v_add_f32_dpp v194, v194, v194 quad_perm:[1,0,3,2] row_mask:0xf bank_mask:0xf bound_ctrl:1
	v_add_f32_dpp v195, v195, v195 quad_perm:[1,0,3,2] row_mask:0xf bank_mask:0xf bound_ctrl:1
	v_pk_fma_f32 v[96:97], v[144:145], v[120:121], v[96:97] op_sel:[0,0,0] op_sel_hi:[1,0,1]
	v_pk_fma_f32 v[98:99], v[144:145], v[120:121], v[98:99] op_sel:[0,1,0] op_sel_hi:[1,1,1]
	v_pk_fma_f32 v[100:101], v[144:145], v[122:123], v[100:101] op_sel:[0,0,0] op_sel_hi:[1,0,1]
	v_add_f32_dpp v192, v192, v192 quad_perm:[2,3,0,1] row_mask:0xf bank_mask:0xf bound_ctrl:1
	v_add_f32_dpp v193, v193, v193 quad_perm:[2,3,0,1] row_mask:0xf bank_mask:0xf bound_ctrl:1
	v_add_f32_dpp v194, v194, v194 quad_perm:[2,3,0,1] row_mask:0xf bank_mask:0xf bound_ctrl:1
	v_add_f32_dpp v195, v195, v195 quad_perm:[2,3,0,1] row_mask:0xf bank_mask:0xf bound_ctrl:1
	v_pk_fma_f32 v[102:103], v[144:145], v[122:123], v[102:103] op_sel:[0,1,0] op_sel_hi:[1,1,1]
	v_pk_fma_f32 v[104:105], v[144:145], v[124:125], v[104:105] op_sel:[0,0,0] op_sel_hi:[1,0,1]
	v_pk_fma_f32 v[106:107], v[144:145], v[124:125], v[106:107] op_sel:[0,1,0] op_sel_hi:[1,1,1]
	v_add_f32_dpp v192, v192, v192 row_half_mirror row_mask:0xf bank_mask:0xf bound_ctrl:1
	v_add_f32_dpp v193, v193, v193 row_half_mirror row_mask:0xf bank_mask:0xf bound_ctrl:1
	v_add_f32_dpp v194, v194, v194 row_half_mirror row_mask:0xf bank_mask:0xf bound_ctrl:1
	v_add_f32_dpp v195, v195, v195 row_half_mirror row_mask:0xf bank_mask:0xf bound_ctrl:1
	v_pk_fma_f32 v[108:109], v[144:145], v[126:127], v[108:109] op_sel:[0,0,0] op_sel_hi:[1,0,1]
	s_mov_b64 exec, s[10:11]
	ds_write_b64 v45, v[192:193] offset:3840
	s_mov_b64 exec, s[0:1]
	v_pk_fma_f32 v[110:111], v[144:145], v[126:127], v[110:111] op_sel:[0,1,0] op_sel_hi:[1,1,1]
	s_nop 0
	v_pk_fma_f32 v[96:97], v[194:195], v[128:129], v[96:97] op_sel:[0,0,0] op_sel_hi:[1,0,1]
	v_pk_fma_f32 v[98:99], v[194:195], v[128:129], v[98:99] op_sel:[0,1,0] op_sel_hi:[1,1,1]
	v_pk_fma_f32 v[100:101], v[194:195], v[130:131], v[100:101] op_sel:[0,0,0] op_sel_hi:[1,0,1]
	v_pk_fma_f32 v[102:103], v[194:195], v[130:131], v[102:103] op_sel:[0,1,0] op_sel_hi:[1,1,1]
	v_pk_fma_f32 v[104:105], v[194:195], v[132:133], v[104:105] op_sel:[0,0,0] op_sel_hi:[1,0,1]
	v_pk_fma_f32 v[106:107], v[194:195], v[132:133], v[106:107] op_sel:[0,1,0] op_sel_hi:[1,1,1]
	v_pk_fma_f32 v[108:109], v[194:195], v[134:135], v[108:109] op_sel:[0,0,0] op_sel_hi:[1,0,1]
	v_pk_fma_f32 v[110:111], v[194:195], v[134:135], v[110:111] op_sel:[0,1,0] op_sel_hi:[1,1,1]
	v_pk_mul_f32 v[184:185], v[96:97], v[136:137] op_sel:[0,0] op_sel_hi:[1,0]
	v_pk_mul_f32 v[188:189], v[96:97], v[156:157] op_sel:[0,0] op_sel_hi:[1,0]
	v_pk_mul_f32 v[186:187], v[98:99], v[136:137] op_sel:[0,1] op_sel_hi:[1,1]
	v_pk_mul_f32 v[190:191], v[98:99], v[156:157] op_sel:[0,1] op_sel_hi:[1,1]
	v_pk_fma_f32 v[184:185], v[100:101], v[138:139], v[184:185] op_sel:[0,0,0] op_sel_hi:[1,0,1]
	v_pk_fma_f32 v[188:189], v[100:101], v[158:159], v[188:189] op_sel:[0,0,0] op_sel_hi:[1,0,1]
	v_pk_fma_f32 v[186:187], v[102:103], v[138:139], v[186:187] op_sel:[0,1,0] op_sel_hi:[1,1,1]
	v_pk_fma_f32 v[190:191], v[102:103], v[158:159], v[190:191] op_sel:[0,1,0] op_sel_hi:[1,1,1]
	v_pk_fma_f32 v[184:185], v[104:105], v[140:141], v[184:185] op_sel:[0,0,0] op_sel_hi:[1,0,1]
	v_pk_fma_f32 v[188:189], v[104:105], v[160:161], v[188:189] op_sel:[0,0,0] op_sel_hi:[1,0,1]
	v_pk_fma_f32 v[186:187], v[106:107], v[140:141], v[186:187] op_sel:[0,1,0] op_sel_hi:[1,1,1]
	v_pk_fma_f32 v[190:191], v[106:107], v[160:161], v[190:191] op_sel:[0,1,0] op_sel_hi:[1,1,1]
	v_pk_fma_f32 v[184:185], v[108:109], v[142:143], v[184:185] op_sel:[0,0,0] op_sel_hi:[1,0,1]
	v_pk_fma_f32 v[188:189], v[108:109], v[162:163], v[188:189] op_sel:[0,0,0] op_sel_hi:[1,0,1]
	v_pk_fma_f32 v[186:187], v[110:111], v[142:143], v[186:187] op_sel:[0,1,0] op_sel_hi:[1,1,1]
	v_pk_fma_f32 v[190:191], v[110:111], v[162:163], v[190:191] op_sel:[0,1,0] op_sel_hi:[1,1,1]
	v_pk_add_f32 v[192:193], v[184:185], v[186:187]
	v_pk_add_f32 v[194:195], v[188:189], v[190:191]
	ds_read_b128 v[120:123], v44 offset:27904
	ds_read_b128 v[124:127], v44 offset:27920
	ds_read_b128 v[128:131], v44 offset:28416
	ds_read_b128 v[132:135], v44 offset:28432
	ds_read_b128 v[136:139], v44 offset:28672
	ds_read_b128 v[140:143], v44 offset:28688
	ds_read_b64 v[144:145], v46 offset:27648
	ds_read_b128 v[156:159], v44 offset:29696
	ds_read_b128 v[160:163], v44 offset:29712
	s_waitcnt lgkmcnt(10)
; #define LAS __attribute__((address_space(3)))
; __device__ __forceinline__ float red8(float x) { x += dpp_mov<0xB1>(x); x += dpp_mov<0x4E>(x); x += dpp_mov<0x141>(x); return x; }
; __device__ __forceinline__ void scan_phase(const KP& P, LAS unsigned char* lds, const int tid, const int bx, const int G) {
;     ...
;             for (int s = 0; s < 32; ++s) {
;                 const LAS float* p = cb + s * 384;
;                 const f32x4 w0 = *(const LAS f32x4*)(p), w1 = *(const LAS f32x4*)(p + 4);
;                 const f32x4 k0 = *(const LAS f32x4*)(p + 64), k1 = *(const LAS f32x4*)(p + 68);
;                 const f32x4 a0 = *(const LAS f32x4*)(p + 128), a1 = *(const LAS f32x4*)(p + 132);
;                 const f32x4 b0 = *(const LAS f32x4*)(p + 192), b1 = *(const LAS f32x4*)(p + 196);
;                 const f32x4 r0 = *(const LAS f32x4*)(p + 256), r1 = *(const LAS f32x4*)(p + 260);
;                 const float vv = buf[(c & 1) * 12288 + s * 384 + 320 + v];
;                 f32x2 sa2 = S[0] * (f32x2){a0.x, a0.y};
;                 sa2 += S[1] * (f32x2){a0.z, a0.w}; sa2 += S[2] * (f32x2){a1.x, a1.y}; sa2 += S[3] * (f32x2){a1.z, a1.w};
;                 const float sa = red8(sa2.x + sa2.y);
;                 const f32x2 sav = {sa, sa}, vv2 = {vv, vv};
;                 S[0] = S[0] * (f32x2){w0.x, w0.y} + sav * (f32x2){b0.x, b0.y} + vv2 * (f32x2){k0.x, k0.y};
;                 S[1] = S[1] * (f32x2){w0.z, w0.w} + sav * (f32x2){b0.z, b0.w} + vv2 * (f32x2){k0.z, k0.w};
;                 S[2] = S[2] * (f32x2){w1.x, w1.y} + sav * (f32x2){b1.x, b1.y} + vv2 * (f32x2){k1.x, k1.y};
;                 S[3] = S[3] * (f32x2){w1.z, w1.w} + sav * (f32x2){b1.z, b1.w} + vv2 * (f32x2){k1.z, k1.w};
;                 f32x2 y2 = S[0] * (f32x2){r0.x, r0.y};
;                 y2 += S[1] * (f32x2){r0.z, r0.w}; y2 += S[2] * (f32x2){r1.x, r1.y}; y2 += S[3] * (f32x2){r1.z, r1.w};
;                 const float y = red8(y2.x + y2.y);
;                 if (kc == 0) ybuf[s * 64 + v] = y;
	v_add_f32_dpp v192, v192, v192 quad_perm:[1,0,3,2] row_mask:0xf bank_mask:0xf bound_ctrl:1
	v_add_f32_dpp v193, v193, v193 quad_perm:[1,0,3,2] row_mask:0xf bank_mask:0xf bound_ctrl:1
	v_add_f32_dpp v194, v194, v194 quad_perm:[1,0,3,2] row_mask:0xf bank_mask:0xf bound_ctrl:1
	v_add_f32_dpp v195, v195, v195 quad_perm:[1,0,3,2] row_mask:0xf bank_mask:0xf bound_ctrl:1
	v_pk_fma_f32 v[96:97], v[146:147], v[70:71], v[96:97] op_sel:[0,0,0] op_sel_hi:[1,0,1]
	v_pk_fma_f32 v[98:99], v[146:147], v[70:71], v[98:99] op_sel:[0,1,0] op_sel_hi:[1,1,1]
	v_pk_fma_f32 v[100:101], v[146:147], v[72:73], v[100:101] op_sel:[0,0,0] op_sel_hi:[1,0,1]
	v_add_f32_dpp v192, v192, v192 quad_perm:[2,3,0,1] row_mask:0xf bank_mask:0xf bound_ctrl:1
	v_add_f32_dpp v193, v193, v193 quad_perm:[2,3,0,1] row_mask:0xf bank_mask:0xf bound_ctrl:1
	v_add_f32_dpp v194, v194, v194 quad_perm:[2,3,0,1] row_mask:0xf bank_mask:0xf bound_ctrl:1
	v_add_f32_dpp v195, v195, v195 quad_perm:[2,3,0,1] row_mask:0xf bank_mask:0xf bound_ctrl:1
	v_pk_fma_f32 v[102:103], v[146:147], v[72:73], v[102:103] op_sel:[0,1,0] op_sel_hi:[1,1,1]
	v_pk_fma_f32 v[104:105], v[146:147], v[74:75], v[104:105] op_sel:[0,0,0] op_sel_hi:[1,0,1]
	v_pk_fma_f32 v[106:107], v[146:147], v[74:75], v[106:107] op_sel:[0,1,0] op_sel_hi:[1,1,1]
	v_add_f32_dpp v192, v192, v192 row_half_mirror row_mask:0xf bank_mask:0xf bound_ctrl:1
	v_add_f32_dpp v193, v193, v193 row_half_mirror row_mask:0xf bank_mask:0xf bound_ctrl:1
	v_add_f32_dpp v194, v194, v194 row_half_mirror row_mask:0xf bank_mask:0xf bound_ctrl:1
	v_add_f32_dpp v195, v195, v195 row_half_mirror row_mask:0xf bank_mask:0xf bound_ctrl:1
	v_pk_fma_f32 v[108:109], v[146:147], v[76:77], v[108:109] op_sel:[0,0,0] op_sel_hi:[1,0,1]
	s_mov_b64 exec, s[10:11]
	ds_write_b64 v45, v[192:193] offset:4096
	s_mov_b64 exec, s[0:1]
	v_pk_fma_f32 v[110:111], v[146:147], v[76:77], v[110:111] op_sel:[0,1,0] op_sel_hi:[1,1,1]
	s_nop 0
	v_pk_fma_f32 v[96:97], v[194:195], v[78:79], v[96:97] op_sel:[0,0,0] op_sel_hi:[1,0,1]
	v_pk_fma_f32 v[98:99], v[194:195], v[78:79], v[98:99] op_sel:[0,1,0] op_sel_hi:[1,1,1]
	v_pk_fma_f32 v[100:101], v[194:195], v[80:81], v[100:101] op_sel:[0,0,0] op_sel_hi:[1,0,1]
	v_pk_fma_f32 v[102:103], v[194:195], v[80:81], v[102:103] op_sel:[0,1,0] op_sel_hi:[1,1,1]
	v_pk_fma_f32 v[104:105], v[194:195], v[82:83], v[104:105] op_sel:[0,0,0] op_sel_hi:[1,0,1]
	v_pk_fma_f32 v[106:107], v[194:195], v[82:83], v[106:107] op_sel:[0,1,0] op_sel_hi:[1,1,1]
	v_pk_fma_f32 v[108:109], v[194:195], v[84:85], v[108:109] op_sel:[0,0,0] op_sel_hi:[1,0,1]
	v_pk_fma_f32 v[110:111], v[194:195], v[84:85], v[110:111] op_sel:[0,1,0] op_sel_hi:[1,1,1]
	v_pk_mul_f32 v[184:185], v[96:97], v[86:87] op_sel:[0,0] op_sel_hi:[1,0]
	v_pk_mul_f32 v[188:189], v[96:97], v[148:149] op_sel:[0,0] op_sel_hi:[1,0]
	v_pk_mul_f32 v[186:187], v[98:99], v[86:87] op_sel:[0,1] op_sel_hi:[1,1]
	v_pk_mul_f32 v[190:191], v[98:99], v[148:149] op_sel:[0,1] op_sel_hi:[1,1]
	v_pk_fma_f32 v[184:185], v[100:101], v[88:89], v[184:185] op_sel:[0,0,0] op_sel_hi:[1,0,1]
	v_pk_fma_f32 v[188:189], v[100:101], v[150:151], v[188:189] op_sel:[0,0,0] op_sel_hi:[1,0,1]
	v_pk_fma_f32 v[186:187], v[102:103], v[88:89], v[186:187] op_sel:[0,1,0] op_sel_hi:[1,1,1]
	v_pk_fma_f32 v[190:191], v[102:103], v[150:151], v[190:191] op_sel:[0,1,0] op_sel_hi:[1,1,1]
	v_pk_fma_f32 v[184:185], v[104:105], v[90:91], v[184:185] op_sel:[0,0,0] op_sel_hi:[1,0,1]
	v_pk_fma_f32 v[188:189], v[104:105], v[152:153], v[188:189] op_sel:[0,0,0] op_sel_hi:[1,0,1]
	v_pk_fma_f32 v[186:187], v[106:107], v[90:91], v[186:187] op_sel:[0,1,0] op_sel_hi:[1,1,1]
	v_pk_fma_f32 v[190:191], v[106:107], v[152:153], v[190:191] op_sel:[0,1,0] op_sel_hi:[1,1,1]
	v_pk_fma_f32 v[184:185], v[108:109], v[92:93], v[184:185] op_sel:[0,0,0] op_sel_hi:[1,0,1]
	v_pk_fma_f32 v[188:189], v[108:109], v[154:155], v[188:189] op_sel:[0,0,0] op_sel_hi:[1,0,1]
	v_pk_fma_f32 v[186:187], v[110:111], v[92:93], v[186:187] op_sel:[0,1,0] op_sel_hi:[1,1,1]
	v_pk_fma_f32 v[190:191], v[110:111], v[154:155], v[190:191] op_sel:[0,1,0] op_sel_hi:[1,1,1]
	v_pk_add_f32 v[192:193], v[184:185], v[186:187]
	v_pk_add_f32 v[194:195], v[188:189], v[190:191]
	ds_read_b128 v[70:73], v44 offset:29440
	ds_read_b128 v[74:77], v44 offset:29456
	ds_read_b128 v[78:81], v44 offset:29952
	ds_read_b128 v[82:85], v44 offset:29968
	ds_read_b128 v[86:89], v44 offset:30208
	ds_read_b128 v[90:93], v44 offset:30224
	ds_read_b64 v[146:147], v46 offset:29184
	ds_read_b128 v[148:151], v44 offset:31232
	ds_read_b128 v[152:155], v44 offset:31248
	s_waitcnt lgkmcnt(10)
; #define LAS __attribute__((address_space(3)))
; __device__ __forceinline__ float red8(float x) { x += dpp_mov<0xB1>(x); x += dpp_mov<0x4E>(x); x += dpp_mov<0x141>(x); return x; }
; __device__ __forceinline__ void scan_phase(const KP& P, LAS unsigned char* lds, const int tid, const int bx, const int G) {
;     ...
;             for (int s = 0; s < 32; ++s) {
;                 const LAS float* p = cb + s * 384;
;                 const f32x4 w0 = *(const LAS f32x4*)(p), w1 = *(const LAS f32x4*)(p + 4);
;                 const f32x4 k0 = *(const LAS f32x4*)(p + 64), k1 = *(const LAS f32x4*)(p + 68);
;                 const f32x4 a0 = *(const LAS f32x4*)(p + 128), a1 = *(const LAS f32x4*)(p + 132);
;                 const f32x4 b0 = *(const LAS f32x4*)(p + 192), b1 = *(const LAS f32x4*)(p + 196);
;                 const f32x4 r0 = *(const LAS f32x4*)(p + 256), r1 = *(const LAS f32x4*)(p + 260);
;                 const float vv = buf[(c & 1) * 12288 + s * 384 + 320 + v];
;                 f32x2 sa2 = S[0] * (f32x2){a0.x, a0.y};
;                 sa2 += S[1] * (f32x2){a0.z, a0.w}; sa2 += S[2] * (f32x2){a1.x, a1.y}; sa2 += S[3] * (f32x2){a1.z, a1.w};
;                 const float sa = red8(sa2.x + sa2.y);
;                 const f32x2 sav = {sa, sa}, vv2 = {vv, vv};
;                 S[0] = S[0] * (f32x2){w0.x, w0.y} + sav * (f32x2){b0.x, b0.y} + vv2 * (f32x2){k0.x, k0.y};
;                 S[1] = S[1] * (f32x2){w0.z, w0.w} + sav * (f32x2){b0.z, b0.w} + vv2 * (f32x2){k0.z, k0.w};
;                 S[2] = S[2] * (f32x2){w1.x, w1.y} + sav * (f32x2){b1.x, b1.y} + vv2 * (f32x2){k1.x, k1.y};
;                 S[3] = S[3] * (f32x2){w1.z, w1.w} + sav * (f32x2){b1.z, b1.w} + vv2 * (f32x2){k1.z, k1.w};
;                 f32x2 y2 = S[0] * (f32x2){r0.x, r0.y};
;                 y2 += S[1] * (f32x2){r0.z, r0.w}; y2 += S[2] * (f32x2){r1.x, r1.y}; y2 += S[3] * (f32x2){r1.z, r1.w};
;                 const float y = red8(y2.x + y2.y);
;                 if (kc == 0) ybuf[s * 64 + v] = y;
	v_add_f32_dpp v192, v192, v192 quad_perm:[1,0,3,2] row_mask:0xf bank_mask:0xf bound_ctrl:1
	v_add_f32_dpp v193, v193, v193 quad_perm:[1,0,3,2] row_mask:0xf bank_mask:0xf bound_ctrl:1
	v_add_f32_dpp v194, v194, v194 quad_perm:[1,0,3,2] row_mask:0xf bank_mask:0xf bound_ctrl:1
	v_add_f32_dpp v195, v195, v195 quad_perm:[1,0,3,2] row_mask:0xf bank_mask:0xf bound_ctrl:1
	v_pk_fma_f32 v[96:97], v[144:145], v[120:121], v[96:97] op_sel:[0,0,0] op_sel_hi:[1,0,1]
	v_pk_fma_f32 v[98:99], v[144:145], v[120:121], v[98:99] op_sel:[0,1,0] op_sel_hi:[1,1,1]
	v_pk_fma_f32 v[100:101], v[144:145], v[122:123], v[100:101] op_sel:[0,0,0] op_sel_hi:[1,0,1]
	v_add_f32_dpp v192, v192, v192 quad_perm:[2,3,0,1] row_mask:0xf bank_mask:0xf bound_ctrl:1
	v_add_f32_dpp v193, v193, v193 quad_perm:[2,3,0,1] row_mask:0xf bank_mask:0xf bound_ctrl:1
	v_add_f32_dpp v194, v194, v194 quad_perm:[2,3,0,1] row_mask:0xf bank_mask:0xf bound_ctrl:1
	v_add_f32_dpp v195, v195, v195 quad_perm:[2,3,0,1] row_mask:0xf bank_mask:0xf bound_ctrl:1
	v_pk_fma_f32 v[102:103], v[144:145], v[122:123], v[102:103] op_sel:[0,1,0] op_sel_hi:[1,1,1]
	v_pk_fma_f32 v[104:105], v[144:145], v[124:125], v[104:105] op_sel:[0,0,0] op_sel_hi:[1,0,1]
	v_pk_fma_f32 v[106:107], v[144:145], v[124:125], v[106:107] op_sel:[0,1,0] op_sel_hi:[1,1,1]
	v_add_f32_dpp v192, v192, v192 row_half_mirror row_mask:0xf bank_mask:0xf bound_ctrl:1
	v_add_f32_dpp v193, v193, v193 row_half_mirror row_mask:0xf bank_mask:0xf bound_ctrl:1
	v_add_f32_dpp v194, v194, v194 row_half_mirror row_mask:0xf bank_mask:0xf bound_ctrl:1
	v_add_f32_dpp v195, v195, v195 row_half_mirror row_mask:0xf bank_mask:0xf bound_ctrl:1
	v_pk_fma_f32 v[108:109], v[144:145], v[126:127], v[108:109] op_sel:[0,0,0] op_sel_hi:[1,0,1]
	s_mov_b64 exec, s[10:11]
	ds_write_b64 v45, v[192:193] offset:4352
	s_mov_b64 exec, s[0:1]
	v_pk_fma_f32 v[110:111], v[144:145], v[126:127], v[110:111] op_sel:[0,1,0] op_sel_hi:[1,1,1]
	s_nop 0
	v_pk_fma_f32 v[96:97], v[194:195], v[128:129], v[96:97] op_sel:[0,0,0] op_sel_hi:[1,0,1]
	v_pk_fma_f32 v[98:99], v[194:195], v[128:129], v[98:99] op_sel:[0,1,0] op_sel_hi:[1,1,1]
	v_pk_fma_f32 v[100:101], v[194:195], v[130:131], v[100:101] op_sel:[0,0,0] op_sel_hi:[1,0,1]
	v_pk_fma_f32 v[102:103], v[194:195], v[130:131], v[102:103] op_sel:[0,1,0] op_sel_hi:[1,1,1]
	v_pk_fma_f32 v[104:105], v[194:195], v[132:133], v[104:105] op_sel:[0,0,0] op_sel_hi:[1,0,1]
	v_pk_fma_f32 v[106:107], v[194:195], v[132:133], v[106:107] op_sel:[0,1,0] op_sel_hi:[1,1,1]
	v_pk_fma_f32 v[108:109], v[194:195], v[134:135], v[108:109] op_sel:[0,0,0] op_sel_hi:[1,0,1]
	v_pk_fma_f32 v[110:111], v[194:195], v[134:135], v[110:111] op_sel:[0,1,0] op_sel_hi:[1,1,1]
	v_pk_mul_f32 v[184:185], v[96:97], v[136:137] op_sel:[0,0] op_sel_hi:[1,0]
	v_pk_mul_f32 v[188:189], v[96:97], v[156:157] op_sel:[0,0] op_sel_hi:[1,0]
	v_pk_mul_f32 v[186:187], v[98:99], v[136:137] op_sel:[0,1] op_sel_hi:[1,1]
	v_pk_mul_f32 v[190:191], v[98:99], v[156:157] op_sel:[0,1] op_sel_hi:[1,1]
	v_pk_fma_f32 v[184:185], v[100:101], v[138:139], v[184:185] op_sel:[0,0,0] op_sel_hi:[1,0,1]
	v_pk_fma_f32 v[188:189], v[100:101], v[158:159], v[188:189] op_sel:[0,0,0] op_sel_hi:[1,0,1]
	v_pk_fma_f32 v[186:187], v[102:103], v[138:139], v[186:187] op_sel:[0,1,0] op_sel_hi:[1,1,1]
	v_pk_fma_f32 v[190:191], v[102:103], v[158:159], v[190:191] op_sel:[0,1,0] op_sel_hi:[1,1,1]
	v_pk_fma_f32 v[184:185], v[104:105], v[140:141], v[184:185] op_sel:[0,0,0] op_sel_hi:[1,0,1]
	v_pk_fma_f32 v[188:189], v[104:105], v[160:161], v[188:189] op_sel:[0,0,0] op_sel_hi:[1,0,1]
	v_pk_fma_f32 v[186:187], v[106:107], v[140:141], v[186:187] op_sel:[0,1,0] op_sel_hi:[1,1,1]
	v_pk_fma_f32 v[190:191], v[106:107], v[160:161], v[190:191] op_sel:[0,1,0] op_sel_hi:[1,1,1]
	v_pk_fma_f32 v[184:185], v[108:109], v[142:143], v[184:185] op_sel:[0,0,0] op_sel_hi:[1,0,1]
	v_pk_fma_f32 v[188:189], v[108:109], v[162:163], v[188:189] op_sel:[0,0,0] op_sel_hi:[1,0,1]
	v_pk_fma_f32 v[186:187], v[110:111], v[142:143], v[186:187] op_sel:[0,1,0] op_sel_hi:[1,1,1]
	v_pk_fma_f32 v[190:191], v[110:111], v[162:163], v[190:191] op_sel:[0,1,0] op_sel_hi:[1,1,1]
	v_pk_add_f32 v[192:193], v[184:185], v[186:187]
	v_pk_add_f32 v[194:195], v[188:189], v[190:191]
	ds_read_b128 v[120:123], v44 offset:30976
	ds_read_b128 v[124:127], v44 offset:30992
	ds_read_b128 v[128:131], v44 offset:31488
	ds_read_b128 v[132:135], v44 offset:31504
	ds_read_b128 v[136:139], v44 offset:31744
	ds_read_b128 v[140:143], v44 offset:31760
	ds_read_b64 v[144:145], v46 offset:30720
	ds_read_b128 v[156:159], v44 offset:32768
	ds_read_b128 v[160:163], v44 offset:32784
	s_waitcnt lgkmcnt(10)
; #define LAS __attribute__((address_space(3)))
; __device__ __forceinline__ float red8(float x) { x += dpp_mov<0xB1>(x); x += dpp_mov<0x4E>(x); x += dpp_mov<0x141>(x); return x; }
; __device__ __forceinline__ void scan_phase(const KP& P, LAS unsigned char* lds, const int tid, const int bx, const int G) {
;     ...
;             for (int s = 0; s < 32; ++s) {
;                 const LAS float* p = cb + s * 384;
;                 const f32x4 w0 = *(const LAS f32x4*)(p), w1 = *(const LAS f32x4*)(p + 4);
;                 const f32x4 k0 = *(const LAS f32x4*)(p + 64), k1 = *(const LAS f32x4*)(p + 68);
;                 const f32x4 a0 = *(const LAS f32x4*)(p + 128), a1 = *(const LAS f32x4*)(p + 132);
;                 const f32x4 b0 = *(const LAS f32x4*)(p + 192), b1 = *(const LAS f32x4*)(p + 196);
;                 const f32x4 r0 = *(const LAS f32x4*)(p + 256), r1 = *(const LAS f32x4*)(p + 260);
;                 const float vv = buf[(c & 1) * 12288 + s * 384 + 320 + v];
;                 f32x2 sa2 = S[0] * (f32x2){a0.x, a0.y};
;                 sa2 += S[1] * (f32x2){a0.z, a0.w}; sa2 += S[2] * (f32x2){a1.x, a1.y}; sa2 += S[3] * (f32x2){a1.z, a1.w};
;                 const float sa = red8(sa2.x + sa2.y);
;                 const f32x2 sav = {sa, sa}, vv2 = {vv, vv};
;                 S[0] = S[0] * (f32x2){w0.x, w0.y} + sav * (f32x2){b0.x, b0.y} + vv2 * (f32x2){k0.x, k0.y};
;                 S[1] = S[1] * (f32x2){w0.z, w0.w} + sav * (f32x2){b0.z, b0.w} + vv2 * (f32x2){k0.z, k0.w};
;                 S[2] = S[2] * (f32x2){w1.x, w1.y} + sav * (f32x2){b1.x, b1.y} + vv2 * (f32x2){k1.x, k1.y};
;                 S[3] = S[3] * (f32x2){w1.z, w1.w} + sav * (f32x2){b1.z, b1.w} + vv2 * (f32x2){k1.z, k1.w};
;                 f32x2 y2 = S[0] * (f32x2){r0.x, r0.y};
;                 y2 += S[1] * (f32x2){r0.z, r0.w}; y2 += S[2] * (f32x2){r1.x, r1.y}; y2 += S[3] * (f32x2){r1.z, r1.w};
;                 const float y = red8(y2.x + y2.y);
;                 if (kc == 0) ybuf[s * 64 + v] = y;
	v_add_f32_dpp v192, v192, v192 quad_perm:[1,0,3,2] row_mask:0xf bank_mask:0xf bound_ctrl:1
	v_add_f32_dpp v193, v193, v193 quad_perm:[1,0,3,2] row_mask:0xf bank_mask:0xf bound_ctrl:1
	v_add_f32_dpp v194, v194, v194 quad_perm:[1,0,3,2] row_mask:0xf bank_mask:0xf bound_ctrl:1
	v_add_f32_dpp v195, v195, v195 quad_perm:[1,0,3,2] row_mask:0xf bank_mask:0xf bound_ctrl:1
	v_pk_fma_f32 v[96:97], v[146:147], v[70:71], v[96:97] op_sel:[0,0,0] op_sel_hi:[1,0,1]
	v_pk_fma_f32 v[98:99], v[146:147], v[70:71], v[98:99] op_sel:[0,1,0] op_sel_hi:[1,1,1]
	v_pk_fma_f32 v[100:101], v[146:147], v[72:73], v[100:101] op_sel:[0,0,0] op_sel_hi:[1,0,1]
	v_add_f32_dpp v192, v192, v192 quad_perm:[2,3,0,1] row_mask:0xf bank_mask:0xf bound_ctrl:1
	v_add_f32_dpp v193, v193, v193 quad_perm:[2,3,0,1] row_mask:0xf bank_mask:0xf bound_ctrl:1
	v_add_f32_dpp v194, v194, v194 quad_perm:[2,3,0,1] row_mask:0xf bank_mask:0xf bound_ctrl:1
	v_add_f32_dpp v195, v195, v195 quad_perm:[2,3,0,1] row_mask:0xf bank_mask:0xf bound_ctrl:1
	v_pk_fma_f32 v[102:103], v[146:147], v[72:73], v[102:103] op_sel:[0,1,0] op_sel_hi:[1,1,1]
	v_pk_fma_f32 v[104:105], v[146:147], v[74:75], v[104:105] op_sel:[0,0,0] op_sel_hi:[1,0,1]
	v_pk_fma_f32 v[106:107], v[146:147], v[74:75], v[106:107] op_sel:[0,1,0] op_sel_hi:[1,1,1]
	v_add_f32_dpp v192, v192, v192 row_half_mirror row_mask:0xf bank_mask:0xf bound_ctrl:1
	v_add_f32_dpp v193, v193, v193 row_half_mirror row_mask:0xf bank_mask:0xf bound_ctrl:1
	v_add_f32_dpp v194, v194, v194 row_half_mirror row_mask:0xf bank_mask:0xf bound_ctrl:1
	v_add_f32_dpp v195, v195, v195 row_half_mirror row_mask:0xf bank_mask:0xf bound_ctrl:1
	v_pk_fma_f32 v[108:109], v[146:147], v[76:77], v[108:109] op_sel:[0,0,0] op_sel_hi:[1,0,1]
	s_mov_b64 exec, s[10:11]
	ds_write_b64 v45, v[192:193] offset:4608
	s_mov_b64 exec, s[0:1]
	v_pk_fma_f32 v[110:111], v[146:147], v[76:77], v[110:111] op_sel:[0,1,0] op_sel_hi:[1,1,1]
	s_nop 0
	v_pk_fma_f32 v[96:97], v[194:195], v[78:79], v[96:97] op_sel:[0,0,0] op_sel_hi:[1,0,1]
	v_pk_fma_f32 v[98:99], v[194:195], v[78:79], v[98:99] op_sel:[0,1,0] op_sel_hi:[1,1,1]
	v_pk_fma_f32 v[100:101], v[194:195], v[80:81], v[100:101] op_sel:[0,0,0] op_sel_hi:[1,0,1]
	v_pk_fma_f32 v[102:103], v[194:195], v[80:81], v[102:103] op_sel:[0,1,0] op_sel_hi:[1,1,1]
	v_pk_fma_f32 v[104:105], v[194:195], v[82:83], v[104:105] op_sel:[0,0,0] op_sel_hi:[1,0,1]
	v_pk_fma_f32 v[106:107], v[194:195], v[82:83], v[106:107] op_sel:[0,1,0] op_sel_hi:[1,1,1]
	v_pk_fma_f32 v[108:109], v[194:195], v[84:85], v[108:109] op_sel:[0,0,0] op_sel_hi:[1,0,1]
	v_pk_fma_f32 v[110:111], v[194:195], v[84:85], v[110:111] op_sel:[0,1,0] op_sel_hi:[1,1,1]
	v_pk_mul_f32 v[184:185], v[96:97], v[86:87] op_sel:[0,0] op_sel_hi:[1,0]
	v_pk_mul_f32 v[188:189], v[96:97], v[148:149] op_sel:[0,0] op_sel_hi:[1,0]
	v_pk_mul_f32 v[186:187], v[98:99], v[86:87] op_sel:[0,1] op_sel_hi:[1,1]
	v_pk_mul_f32 v[190:191], v[98:99], v[148:149] op_sel:[0,1] op_sel_hi:[1,1]
	v_pk_fma_f32 v[184:185], v[100:101], v[88:89], v[184:185] op_sel:[0,0,0] op_sel_hi:[1,0,1]
	v_pk_fma_f32 v[188:189], v[100:101], v[150:151], v[188:189] op_sel:[0,0,0] op_sel_hi:[1,0,1]
	v_pk_fma_f32 v[186:187], v[102:103], v[88:89], v[186:187] op_sel:[0,1,0] op_sel_hi:[1,1,1]
	v_pk_fma_f32 v[190:191], v[102:103], v[150:151], v[190:191] op_sel:[0,1,0] op_sel_hi:[1,1,1]
	v_pk_fma_f32 v[184:185], v[104:105], v[90:91], v[184:185] op_sel:[0,0,0] op_sel_hi:[1,0,1]
	v_pk_fma_f32 v[188:189], v[104:105], v[152:153], v[188:189] op_sel:[0,0,0] op_sel_hi:[1,0,1]
	v_pk_fma_f32 v[186:187], v[106:107], v[90:91], v[186:187] op_sel:[0,1,0] op_sel_hi:[1,1,1]
	v_pk_fma_f32 v[190:191], v[106:107], v[152:153], v[190:191] op_sel:[0,1,0] op_sel_hi:[1,1,1]
	v_pk_fma_f32 v[184:185], v[108:109], v[92:93], v[184:185] op_sel:[0,0,0] op_sel_hi:[1,0,1]
	v_pk_fma_f32 v[188:189], v[108:109], v[154:155], v[188:189] op_sel:[0,0,0] op_sel_hi:[1,0,1]
	v_pk_fma_f32 v[186:187], v[110:111], v[92:93], v[186:187] op_sel:[0,1,0] op_sel_hi:[1,1,1]
	v_pk_fma_f32 v[190:191], v[110:111], v[154:155], v[190:191] op_sel:[0,1,0] op_sel_hi:[1,1,1]
	v_pk_add_f32 v[192:193], v[184:185], v[186:187]
	v_pk_add_f32 v[194:195], v[188:189], v[190:191]
	ds_read_b128 v[70:73], v44 offset:32512
	ds_read_b128 v[74:77], v44 offset:32528
	ds_read_b128 v[78:81], v44 offset:33024
	ds_read_b128 v[82:85], v44 offset:33040
	ds_read_b128 v[86:89], v44 offset:33280
	ds_read_b128 v[90:93], v44 offset:33296
	ds_read_b64 v[146:147], v46 offset:32256
	ds_read_b128 v[148:151], v44 offset:34304
	ds_read_b128 v[152:155], v44 offset:34320
	s_waitcnt lgkmcnt(10)
; #define LAS __attribute__((address_space(3)))
; __device__ __forceinline__ float red8(float x) { x += dpp_mov<0xB1>(x); x += dpp_mov<0x4E>(x); x += dpp_mov<0x141>(x); return x; }
; __device__ __forceinline__ void scan_phase(const KP& P, LAS unsigned char* lds, const int tid, const int bx, const int G) {
;     ...
;             for (int s = 0; s < 32; ++s) {
;                 const LAS float* p = cb + s * 384;
;                 const f32x4 w0 = *(const LAS f32x4*)(p), w1 = *(const LAS f32x4*)(p + 4);
;                 const f32x4 k0 = *(const LAS f32x4*)(p + 64), k1 = *(const LAS f32x4*)(p + 68);
;                 const f32x4 a0 = *(const LAS f32x4*)(p + 128), a1 = *(const LAS f32x4*)(p + 132);
;                 const f32x4 b0 = *(const LAS f32x4*)(p + 192), b1 = *(const LAS f32x4*)(p + 196);
;                 const f32x4 r0 = *(const LAS f32x4*)(p + 256), r1 = *(const LAS f32x4*)(p + 260);
;                 const float vv = buf[(c & 1) * 12288 + s * 384 + 320 + v];
;                 f32x2 sa2 = S[0] * (f32x2){a0.x, a0.y};
;                 sa2 += S[1] * (f32x2){a0.z, a0.w}; sa2 += S[2] * (f32x2){a1.x, a1.y}; sa2 += S[3] * (f32x2){a1.z, a1.w};
;                 const float sa = red8(sa2.x + sa2.y);
;                 const f32x2 sav = {sa, sa}, vv2 = {vv, vv};
;                 S[0] = S[0] * (f32x2){w0.x, w0.y} + sav * (f32x2){b0.x, b0.y} + vv2 * (f32x2){k0.x, k0.y};
;                 S[1] = S[1] * (f32x2){w0.z, w0.w} + sav * (f32x2){b0.z, b0.w} + vv2 * (f32x2){k0.z, k0.w};
;                 S[2] = S[2] * (f32x2){w1.x, w1.y} + sav * (f32x2){b1.x, b1.y} + vv2 * (f32x2){k1.x, k1.y};
;                 S[3] = S[3] * (f32x2){w1.z, w1.w} + sav * (f32x2){b1.z, b1.w} + vv2 * (f32x2){k1.z, k1.w};
;                 f32x2 y2 = S[0] * (f32x2){r0.x, r0.y};
;                 y2 += S[1] * (f32x2){r0.z, r0.w}; y2 += S[2] * (f32x2){r1.x, r1.y}; y2 += S[3] * (f32x2){r1.z, r1.w};
;                 const float y = red8(y2.x + y2.y);
;                 if (kc == 0) ybuf[s * 64 + v] = y;
	v_add_f32_dpp v192, v192, v192 quad_perm:[1,0,3,2] row_mask:0xf bank_mask:0xf bound_ctrl:1
	v_add_f32_dpp v193, v193, v193 quad_perm:[1,0,3,2] row_mask:0xf bank_mask:0xf bound_ctrl:1
	v_add_f32_dpp v194, v194, v194 quad_perm:[1,0,3,2] row_mask:0xf bank_mask:0xf bound_ctrl:1
	v_add_f32_dpp v195, v195, v195 quad_perm:[1,0,3,2] row_mask:0xf bank_mask:0xf bound_ctrl:1
	v_pk_fma_f32 v[96:97], v[144:145], v[120:121], v[96:97] op_sel:[0,0,0] op_sel_hi:[1,0,1]
	v_pk_fma_f32 v[98:99], v[144:145], v[120:121], v[98:99] op_sel:[0,1,0] op_sel_hi:[1,1,1]
	v_pk_fma_f32 v[100:101], v[144:145], v[122:123], v[100:101] op_sel:[0,0,0] op_sel_hi:[1,0,1]
	v_add_f32_dpp v192, v192, v192 quad_perm:[2,3,0,1] row_mask:0xf bank_mask:0xf bound_ctrl:1
	v_add_f32_dpp v193, v193, v193 quad_perm:[2,3,0,1] row_mask:0xf bank_mask:0xf bound_ctrl:1
	v_add_f32_dpp v194, v194, v194 quad_perm:[2,3,0,1] row_mask:0xf bank_mask:0xf bound_ctrl:1
	v_add_f32_dpp v195, v195, v195 quad_perm:[2,3,0,1] row_mask:0xf bank_mask:0xf bound_ctrl:1
	v_pk_fma_f32 v[102:103], v[144:145], v[122:123], v[102:103] op_sel:[0,1,0] op_sel_hi:[1,1,1]
	v_pk_fma_f32 v[104:105], v[144:145], v[124:125], v[104:105] op_sel:[0,0,0] op_sel_hi:[1,0,1]
	v_pk_fma_f32 v[106:107], v[144:145], v[124:125], v[106:107] op_sel:[0,1,0] op_sel_hi:[1,1,1]
	v_add_f32_dpp v192, v192, v192 row_half_mirror row_mask:0xf bank_mask:0xf bound_ctrl:1
	v_add_f32_dpp v193, v193, v193 row_half_mirror row_mask:0xf bank_mask:0xf bound_ctrl:1
	v_add_f32_dpp v194, v194, v194 row_half_mirror row_mask:0xf bank_mask:0xf bound_ctrl:1
	v_add_f32_dpp v195, v195, v195 row_half_mirror row_mask:0xf bank_mask:0xf bound_ctrl:1
	v_pk_fma_f32 v[108:109], v[144:145], v[126:127], v[108:109] op_sel:[0,0,0] op_sel_hi:[1,0,1]
	s_mov_b64 exec, s[10:11]
	ds_write_b64 v45, v[192:193] offset:4864
	s_mov_b64 exec, s[0:1]
	v_pk_fma_f32 v[110:111], v[144:145], v[126:127], v[110:111] op_sel:[0,1,0] op_sel_hi:[1,1,1]
	s_nop 0
	v_pk_fma_f32 v[96:97], v[194:195], v[128:129], v[96:97] op_sel:[0,0,0] op_sel_hi:[1,0,1]
	v_pk_fma_f32 v[98:99], v[194:195], v[128:129], v[98:99] op_sel:[0,1,0] op_sel_hi:[1,1,1]
	v_pk_fma_f32 v[100:101], v[194:195], v[130:131], v[100:101] op_sel:[0,0,0] op_sel_hi:[1,0,1]
	v_pk_fma_f32 v[102:103], v[194:195], v[130:131], v[102:103] op_sel:[0,1,0] op_sel_hi:[1,1,1]
	v_pk_fma_f32 v[104:105], v[194:195], v[132:133], v[104:105] op_sel:[0,0,0] op_sel_hi:[1,0,1]
	v_pk_fma_f32 v[106:107], v[194:195], v[132:133], v[106:107] op_sel:[0,1,0] op_sel_hi:[1,1,1]
	v_pk_fma_f32 v[108:109], v[194:195], v[134:135], v[108:109] op_sel:[0,0,0] op_sel_hi:[1,0,1]
	v_pk_fma_f32 v[110:111], v[194:195], v[134:135], v[110:111] op_sel:[0,1,0] op_sel_hi:[1,1,1]
	v_pk_mul_f32 v[184:185], v[96:97], v[136:137] op_sel:[0,0] op_sel_hi:[1,0]
	v_pk_mul_f32 v[188:189], v[96:97], v[156:157] op_sel:[0,0] op_sel_hi:[1,0]
	v_pk_mul_f32 v[186:187], v[98:99], v[136:137] op_sel:[0,1] op_sel_hi:[1,1]
	v_pk_mul_f32 v[190:191], v[98:99], v[156:157] op_sel:[0,1] op_sel_hi:[1,1]
	v_pk_fma_f32 v[184:185], v[100:101], v[138:139], v[184:185] op_sel:[0,0,0] op_sel_hi:[1,0,1]
	v_pk_fma_f32 v[188:189], v[100:101], v[158:159], v[188:189] op_sel:[0,0,0] op_sel_hi:[1,0,1]
	v_pk_fma_f32 v[186:187], v[102:103], v[138:139], v[186:187] op_sel:[0,1,0] op_sel_hi:[1,1,1]
	v_pk_fma_f32 v[190:191], v[102:103], v[158:159], v[190:191] op_sel:[0,1,0] op_sel_hi:[1,1,1]
	v_pk_fma_f32 v[184:185], v[104:105], v[140:141], v[184:185] op_sel:[0,0,0] op_sel_hi:[1,0,1]
	v_pk_fma_f32 v[188:189], v[104:105], v[160:161], v[188:189] op_sel:[0,0,0] op_sel_hi:[1,0,1]
	v_pk_fma_f32 v[186:187], v[106:107], v[140:141], v[186:187] op_sel:[0,1,0] op_sel_hi:[1,1,1]
	v_pk_fma_f32 v[190:191], v[106:107], v[160:161], v[190:191] op_sel:[0,1,0] op_sel_hi:[1,1,1]
	v_pk_fma_f32 v[184:185], v[108:109], v[142:143], v[184:185] op_sel:[0,0,0] op_sel_hi:[1,0,1]
	v_pk_fma_f32 v[188:189], v[108:109], v[162:163], v[188:189] op_sel:[0,0,0] op_sel_hi:[1,0,1]
	v_pk_fma_f32 v[186:187], v[110:111], v[142:143], v[186:187] op_sel:[0,1,0] op_sel_hi:[1,1,1]
	v_pk_fma_f32 v[190:191], v[110:111], v[162:163], v[190:191] op_sel:[0,1,0] op_sel_hi:[1,1,1]
	v_pk_add_f32 v[192:193], v[184:185], v[186:187]
	v_pk_add_f32 v[194:195], v[188:189], v[190:191]
	ds_read_b128 v[120:123], v44 offset:34048
	ds_read_b128 v[124:127], v44 offset:34064
	ds_read_b128 v[128:131], v44 offset:34560
	ds_read_b128 v[132:135], v44 offset:34576
	ds_read_b128 v[136:139], v44 offset:34816
	ds_read_b128 v[140:143], v44 offset:34832
	ds_read_b64 v[144:145], v46 offset:33792
	ds_read_b128 v[156:159], v44 offset:35840
	ds_read_b128 v[160:163], v44 offset:35856
	s_waitcnt lgkmcnt(10)
; #define LAS __attribute__((address_space(3)))
; __device__ __forceinline__ float red8(float x) { x += dpp_mov<0xB1>(x); x += dpp_mov<0x4E>(x); x += dpp_mov<0x141>(x); return x; }
; __device__ __forceinline__ void scan_phase(const KP& P, LAS unsigned char* lds, const int tid, const int bx, const int G) {
;     ...
;             for (int s = 0; s < 32; ++s) {
;                 const LAS float* p = cb + s * 384;
;                 const f32x4 w0 = *(const LAS f32x4*)(p), w1 = *(const LAS f32x4*)(p + 4);
;                 const f32x4 k0 = *(const LAS f32x4*)(p + 64), k1 = *(const LAS f32x4*)(p + 68);
;                 const f32x4 a0 = *(const LAS f32x4*)(p + 128), a1 = *(const LAS f32x4*)(p + 132);
;                 const f32x4 b0 = *(const LAS f32x4*)(p + 192), b1 = *(const LAS f32x4*)(p + 196);
;                 const f32x4 r0 = *(const LAS f32x4*)(p + 256), r1 = *(const LAS f32x4*)(p + 260);
;                 const float vv = buf[(c & 1) * 12288 + s * 384 + 320 + v];
;                 f32x2 sa2 = S[0] * (f32x2){a0.x, a0.y};
;                 sa2 += S[1] * (f32x2){a0.z, a0.w}; sa2 += S[2] * (f32x2){a1.x, a1.y}; sa2 += S[3] * (f32x2){a1.z, a1.w};
;                 const float sa = red8(sa2.x + sa2.y);
;                 const f32x2 sav = {sa, sa}, vv2 = {vv, vv};
;                 S[0] = S[0] * (f32x2){w0.x, w0.y} + sav * (f32x2){b0.x, b0.y} + vv2 * (f32x2){k0.x, k0.y};
;                 S[1] = S[1] * (f32x2){w0.z, w0.w} + sav * (f32x2){b0.z, b0.w} + vv2 * (f32x2){k0.z, k0.w};
;                 S[2] = S[2] * (f32x2){w1.x, w1.y} + sav * (f32x2){b1.x, b1.y} + vv2 * (f32x2){k1.x, k1.y};
;                 S[3] = S[3] * (f32x2){w1.z, w1.w} + sav * (f32x2){b1.z, b1.w} + vv2 * (f32x2){k1.z, k1.w};
;                 f32x2 y2 = S[0] * (f32x2){r0.x, r0.y};
;                 y2 += S[1] * (f32x2){r0.z, r0.w}; y2 += S[2] * (f32x2){r1.x, r1.y}; y2 += S[3] * (f32x2){r1.z, r1.w};
;                 const float y = red8(y2.x + y2.y);
;                 if (kc == 0) ybuf[s * 64 + v] = y;
	v_add_f32_dpp v192, v192, v192 quad_perm:[1,0,3,2] row_mask:0xf bank_mask:0xf bound_ctrl:1
	v_add_f32_dpp v193, v193, v193 quad_perm:[1,0,3,2] row_mask:0xf bank_mask:0xf bound_ctrl:1
	v_add_f32_dpp v194, v194, v194 quad_perm:[1,0,3,2] row_mask:0xf bank_mask:0xf bound_ctrl:1
	v_add_f32_dpp v195, v195, v195 quad_perm:[1,0,3,2] row_mask:0xf bank_mask:0xf bound_ctrl:1
	v_pk_fma_f32 v[96:97], v[146:147], v[70:71], v[96:97] op_sel:[0,0,0] op_sel_hi:[1,0,1]
	v_pk_fma_f32 v[98:99], v[146:147], v[70:71], v[98:99] op_sel:[0,1,0] op_sel_hi:[1,1,1]
	v_pk_fma_f32 v[100:101], v[146:147], v[72:73], v[100:101] op_sel:[0,0,0] op_sel_hi:[1,0,1]
	v_add_f32_dpp v192, v192, v192 quad_perm:[2,3,0,1] row_mask:0xf bank_mask:0xf bound_ctrl:1
	v_add_f32_dpp v193, v193, v193 quad_perm:[2,3,0,1] row_mask:0xf bank_mask:0xf bound_ctrl:1
	v_add_f32_dpp v194, v194, v194 quad_perm:[2,3,0,1] row_mask:0xf bank_mask:0xf bound_ctrl:1
	v_add_f32_dpp v195, v195, v195 quad_perm:[2,3,0,1] row_mask:0xf bank_mask:0xf bound_ctrl:1
	v_pk_fma_f32 v[102:103], v[146:147], v[72:73], v[102:103] op_sel:[0,1,0] op_sel_hi:[1,1,1]
	v_pk_fma_f32 v[104:105], v[146:147], v[74:75], v[104:105] op_sel:[0,0,0] op_sel_hi:[1,0,1]
	v_pk_fma_f32 v[106:107], v[146:147], v[74:75], v[106:107] op_sel:[0,1,0] op_sel_hi:[1,1,1]
	v_add_f32_dpp v192, v192, v192 row_half_mirror row_mask:0xf bank_mask:0xf bound_ctrl:1
	v_add_f32_dpp v193, v193, v193 row_half_mirror row_mask:0xf bank_mask:0xf bound_ctrl:1
	v_add_f32_dpp v194, v194, v194 row_half_mirror row_mask:0xf bank_mask:0xf bound_ctrl:1
	v_add_f32_dpp v195, v195, v195 row_half_mirror row_mask:0xf bank_mask:0xf bound_ctrl:1
	v_pk_fma_f32 v[108:109], v[146:147], v[76:77], v[108:109] op_sel:[0,0,0] op_sel_hi:[1,0,1]
	s_mov_b64 exec, s[10:11]
	ds_write_b64 v45, v[192:193] offset:5120
	s_mov_b64 exec, s[0:1]
	v_pk_fma_f32 v[110:111], v[146:147], v[76:77], v[110:111] op_sel:[0,1,0] op_sel_hi:[1,1,1]
	s_nop 0
	v_pk_fma_f32 v[96:97], v[194:195], v[78:79], v[96:97] op_sel:[0,0,0] op_sel_hi:[1,0,1]
	v_pk_fma_f32 v[98:99], v[194:195], v[78:79], v[98:99] op_sel:[0,1,0] op_sel_hi:[1,1,1]
	v_pk_fma_f32 v[100:101], v[194:195], v[80:81], v[100:101] op_sel:[0,0,0] op_sel_hi:[1,0,1]
	v_pk_fma_f32 v[102:103], v[194:195], v[80:81], v[102:103] op_sel:[0,1,0] op_sel_hi:[1,1,1]
	v_pk_fma_f32 v[104:105], v[194:195], v[82:83], v[104:105] op_sel:[0,0,0] op_sel_hi:[1,0,1]
	v_pk_fma_f32 v[106:107], v[194:195], v[82:83], v[106:107] op_sel:[0,1,0] op_sel_hi:[1,1,1]
	v_pk_fma_f32 v[108:109], v[194:195], v[84:85], v[108:109] op_sel:[0,0,0] op_sel_hi:[1,0,1]
	v_pk_fma_f32 v[110:111], v[194:195], v[84:85], v[110:111] op_sel:[0,1,0] op_sel_hi:[1,1,1]
	v_pk_mul_f32 v[184:185], v[96:97], v[86:87] op_sel:[0,0] op_sel_hi:[1,0]
	v_pk_mul_f32 v[188:189], v[96:97], v[148:149] op_sel:[0,0] op_sel_hi:[1,0]
	v_pk_mul_f32 v[186:187], v[98:99], v[86:87] op_sel:[0,1] op_sel_hi:[1,1]
	v_pk_mul_f32 v[190:191], v[98:99], v[148:149] op_sel:[0,1] op_sel_hi:[1,1]
	v_pk_fma_f32 v[184:185], v[100:101], v[88:89], v[184:185] op_sel:[0,0,0] op_sel_hi:[1,0,1]
	v_pk_fma_f32 v[188:189], v[100:101], v[150:151], v[188:189] op_sel:[0,0,0] op_sel_hi:[1,0,1]
	v_pk_fma_f32 v[186:187], v[102:103], v[88:89], v[186:187] op_sel:[0,1,0] op_sel_hi:[1,1,1]
	v_pk_fma_f32 v[190:191], v[102:103], v[150:151], v[190:191] op_sel:[0,1,0] op_sel_hi:[1,1,1]
	v_pk_fma_f32 v[184:185], v[104:105], v[90:91], v[184:185] op_sel:[0,0,0] op_sel_hi:[1,0,1]
	v_pk_fma_f32 v[188:189], v[104:105], v[152:153], v[188:189] op_sel:[0,0,0] op_sel_hi:[1,0,1]
	v_pk_fma_f32 v[186:187], v[106:107], v[90:91], v[186:187] op_sel:[0,1,0] op_sel_hi:[1,1,1]
	v_pk_fma_f32 v[190:191], v[106:107], v[152:153], v[190:191] op_sel:[0,1,0] op_sel_hi:[1,1,1]
	v_pk_fma_f32 v[184:185], v[108:109], v[92:93], v[184:185] op_sel:[0,0,0] op_sel_hi:[1,0,1]
	v_pk_fma_f32 v[188:189], v[108:109], v[154:155], v[188:189] op_sel:[0,0,0] op_sel_hi:[1,0,1]
	v_pk_fma_f32 v[186:187], v[110:111], v[92:93], v[186:187] op_sel:[0,1,0] op_sel_hi:[1,1,1]
	v_pk_fma_f32 v[190:191], v[110:111], v[154:155], v[190:191] op_sel:[0,1,0] op_sel_hi:[1,1,1]
	v_pk_add_f32 v[192:193], v[184:185], v[186:187]
	v_pk_add_f32 v[194:195], v[188:189], v[190:191]
	ds_read_b128 v[70:73], v44 offset:35584
	ds_read_b128 v[74:77], v44 offset:35600
	ds_read_b128 v[78:81], v44 offset:36096
	ds_read_b128 v[82:85], v44 offset:36112
	ds_read_b128 v[86:89], v44 offset:36352
	ds_read_b128 v[90:93], v44 offset:36368
	ds_read_b64 v[146:147], v46 offset:35328
	ds_read_b128 v[148:151], v44 offset:37376
	ds_read_b128 v[152:155], v44 offset:37392
	s_waitcnt lgkmcnt(10)
; #define LAS __attribute__((address_space(3)))
; __device__ __forceinline__ float red8(float x) { x += dpp_mov<0xB1>(x); x += dpp_mov<0x4E>(x); x += dpp_mov<0x141>(x); return x; }
; __device__ __forceinline__ void scan_phase(const KP& P, LAS unsigned char* lds, const int tid, const int bx, const int G) {
;     ...
;             for (int s = 0; s < 32; ++s) {
;                 const LAS float* p = cb + s * 384;
;                 const f32x4 w0 = *(const LAS f32x4*)(p), w1 = *(const LAS f32x4*)(p + 4);
;                 const f32x4 k0 = *(const LAS f32x4*)(p + 64), k1 = *(const LAS f32x4*)(p + 68);
;                 const f32x4 a0 = *(const LAS f32x4*)(p + 128), a1 = *(const LAS f32x4*)(p + 132);
;                 const f32x4 b0 = *(const LAS f32x4*)(p + 192), b1 = *(const LAS f32x4*)(p + 196);
;                 const f32x4 r0 = *(const LAS f32x4*)(p + 256), r1 = *(const LAS f32x4*)(p + 260);
;                 const float vv = buf[(c & 1) * 12288 + s * 384 + 320 + v];
;                 f32x2 sa2 = S[0] * (f32x2){a0.x, a0.y};
;                 sa2 += S[1] * (f32x2){a0.z, a0.w}; sa2 += S[2] * (f32x2){a1.x, a1.y}; sa2 += S[3] * (f32x2){a1.z, a1.w};
;                 const float sa = red8(sa2.x + sa2.y);
;                 const f32x2 sav = {sa, sa}, vv2 = {vv, vv};
;                 S[0] = S[0] * (f32x2){w0.x, w0.y} + sav * (f32x2){b0.x, b0.y} + vv2 * (f32x2){k0.x, k0.y};
;                 S[1] = S[1] * (f32x2){w0.z, w0.w} + sav * (f32x2){b0.z, b0.w} + vv2 * (f32x2){k0.z, k0.w};
;                 S[2] = S[2] * (f32x2){w1.x, w1.y} + sav * (f32x2){b1.x, b1.y} + vv2 * (f32x2){k1.x, k1.y};
;                 S[3] = S[3] * (f32x2){w1.z, w1.w} + sav * (f32x2){b1.z, b1.w} + vv2 * (f32x2){k1.z, k1.w};
;                 f32x2 y2 = S[0] * (f32x2){r0.x, r0.y};
;                 y2 += S[1] * (f32x2){r0.z, r0.w}; y2 += S[2] * (f32x2){r1.x, r1.y}; y2 += S[3] * (f32x2){r1.z, r1.w};
;                 const float y = red8(y2.x + y2.y);
;                 if (kc == 0) ybuf[s * 64 + v] = y;
	v_add_f32_dpp v192, v192, v192 quad_perm:[1,0,3,2] row_mask:0xf bank_mask:0xf bound_ctrl:1
	v_add_f32_dpp v193, v193, v193 quad_perm:[1,0,3,2] row_mask:0xf bank_mask:0xf bound_ctrl:1
	v_add_f32_dpp v194, v194, v194 quad_perm:[1,0,3,2] row_mask:0xf bank_mask:0xf bound_ctrl:1
	v_add_f32_dpp v195, v195, v195 quad_perm:[1,0,3,2] row_mask:0xf bank_mask:0xf bound_ctrl:1
	v_pk_fma_f32 v[96:97], v[144:145], v[120:121], v[96:97] op_sel:[0,0,0] op_sel_hi:[1,0,1]
	v_pk_fma_f32 v[98:99], v[144:145], v[120:121], v[98:99] op_sel:[0,1,0] op_sel_hi:[1,1,1]
	v_pk_fma_f32 v[100:101], v[144:145], v[122:123], v[100:101] op_sel:[0,0,0] op_sel_hi:[1,0,1]
	v_add_f32_dpp v192, v192, v192 quad_perm:[2,3,0,1] row_mask:0xf bank_mask:0xf bound_ctrl:1
	v_add_f32_dpp v193, v193, v193 quad_perm:[2,3,0,1] row_mask:0xf bank_mask:0xf bound_ctrl:1
	v_add_f32_dpp v194, v194, v194 quad_perm:[2,3,0,1] row_mask:0xf bank_mask:0xf bound_ctrl:1
	v_add_f32_dpp v195, v195, v195 quad_perm:[2,3,0,1] row_mask:0xf bank_mask:0xf bound_ctrl:1
	v_pk_fma_f32 v[102:103], v[144:145], v[122:123], v[102:103] op_sel:[0,1,0] op_sel_hi:[1,1,1]
	v_pk_fma_f32 v[104:105], v[144:145], v[124:125], v[104:105] op_sel:[0,0,0] op_sel_hi:[1,0,1]
	v_pk_fma_f32 v[106:107], v[144:145], v[124:125], v[106:107] op_sel:[0,1,0] op_sel_hi:[1,1,1]
	v_add_f32_dpp v192, v192, v192 row_half_mirror row_mask:0xf bank_mask:0xf bound_ctrl:1
	v_add_f32_dpp v193, v193, v193 row_half_mirror row_mask:0xf bank_mask:0xf bound_ctrl:1
	v_add_f32_dpp v194, v194, v194 row_half_mirror row_mask:0xf bank_mask:0xf bound_ctrl:1
	v_add_f32_dpp v195, v195, v195 row_half_mirror row_mask:0xf bank_mask:0xf bound_ctrl:1
	v_pk_fma_f32 v[108:109], v[144:145], v[126:127], v[108:109] op_sel:[0,0,0] op_sel_hi:[1,0,1]
	s_mov_b64 exec, s[10:11]
	ds_write_b64 v45, v[192:193] offset:5376
	s_mov_b64 exec, s[0:1]
	v_pk_fma_f32 v[110:111], v[144:145], v[126:127], v[110:111] op_sel:[0,1,0] op_sel_hi:[1,1,1]
	s_nop 0
	v_pk_fma_f32 v[96:97], v[194:195], v[128:129], v[96:97] op_sel:[0,0,0] op_sel_hi:[1,0,1]
	v_pk_fma_f32 v[98:99], v[194:195], v[128:129], v[98:99] op_sel:[0,1,0] op_sel_hi:[1,1,1]
	v_pk_fma_f32 v[100:101], v[194:195], v[130:131], v[100:101] op_sel:[0,0,0] op_sel_hi:[1,0,1]
	v_pk_fma_f32 v[102:103], v[194:195], v[130:131], v[102:103] op_sel:[0,1,0] op_sel_hi:[1,1,1]
	v_pk_fma_f32 v[104:105], v[194:195], v[132:133], v[104:105] op_sel:[0,0,0] op_sel_hi:[1,0,1]
	v_pk_fma_f32 v[106:107], v[194:195], v[132:133], v[106:107] op_sel:[0,1,0] op_sel_hi:[1,1,1]
	v_pk_fma_f32 v[108:109], v[194:195], v[134:135], v[108:109] op_sel:[0,0,0] op_sel_hi:[1,0,1]
	v_pk_fma_f32 v[110:111], v[194:195], v[134:135], v[110:111] op_sel:[0,1,0] op_sel_hi:[1,1,1]
	v_pk_mul_f32 v[184:185], v[96:97], v[136:137] op_sel:[0,0] op_sel_hi:[1,0]
	v_pk_mul_f32 v[188:189], v[96:97], v[156:157] op_sel:[0,0] op_sel_hi:[1,0]
	v_pk_mul_f32 v[186:187], v[98:99], v[136:137] op_sel:[0,1] op_sel_hi:[1,1]
	v_pk_mul_f32 v[190:191], v[98:99], v[156:157] op_sel:[0,1] op_sel_hi:[1,1]
	v_pk_fma_f32 v[184:185], v[100:101], v[138:139], v[184:185] op_sel:[0,0,0] op_sel_hi:[1,0,1]
	v_pk_fma_f32 v[188:189], v[100:101], v[158:159], v[188:189] op_sel:[0,0,0] op_sel_hi:[1,0,1]
	v_pk_fma_f32 v[186:187], v[102:103], v[138:139], v[186:187] op_sel:[0,1,0] op_sel_hi:[1,1,1]
	v_pk_fma_f32 v[190:191], v[102:103], v[158:159], v[190:191] op_sel:[0,1,0] op_sel_hi:[1,1,1]
	v_pk_fma_f32 v[184:185], v[104:105], v[140:141], v[184:185] op_sel:[0,0,0] op_sel_hi:[1,0,1]
	v_pk_fma_f32 v[188:189], v[104:105], v[160:161], v[188:189] op_sel:[0,0,0] op_sel_hi:[1,0,1]
	v_pk_fma_f32 v[186:187], v[106:107], v[140:141], v[186:187] op_sel:[0,1,0] op_sel_hi:[1,1,1]
	v_pk_fma_f32 v[190:191], v[106:107], v[160:161], v[190:191] op_sel:[0,1,0] op_sel_hi:[1,1,1]
	v_pk_fma_f32 v[184:185], v[108:109], v[142:143], v[184:185] op_sel:[0,0,0] op_sel_hi:[1,0,1]
	v_pk_fma_f32 v[188:189], v[108:109], v[162:163], v[188:189] op_sel:[0,0,0] op_sel_hi:[1,0,1]
	v_pk_fma_f32 v[186:187], v[110:111], v[142:143], v[186:187] op_sel:[0,1,0] op_sel_hi:[1,1,1]
	v_pk_fma_f32 v[190:191], v[110:111], v[162:163], v[190:191] op_sel:[0,1,0] op_sel_hi:[1,1,1]
	v_pk_add_f32 v[192:193], v[184:185], v[186:187]
	v_pk_add_f32 v[194:195], v[188:189], v[190:191]
	ds_read_b128 v[120:123], v44 offset:37120
	ds_read_b128 v[124:127], v44 offset:37136
	ds_read_b128 v[128:131], v44 offset:37632
	ds_read_b128 v[132:135], v44 offset:37648
	ds_read_b128 v[136:139], v44 offset:37888
	ds_read_b128 v[140:143], v44 offset:37904
	ds_read_b64 v[144:145], v46 offset:36864
	ds_read_b128 v[156:159], v44 offset:38912
	ds_read_b128 v[160:163], v44 offset:38928
	s_waitcnt lgkmcnt(10)
; #define LAS __attribute__((address_space(3)))
; __device__ __forceinline__ float red8(float x) { x += dpp_mov<0xB1>(x); x += dpp_mov<0x4E>(x); x += dpp_mov<0x141>(x); return x; }
; __device__ __forceinline__ void scan_phase(const KP& P, LAS unsigned char* lds, const int tid, const int bx, const int G) {
;     ...
;             for (int s = 0; s < 32; ++s) {
;                 const LAS float* p = cb + s * 384;
;                 const f32x4 w0 = *(const LAS f32x4*)(p), w1 = *(const LAS f32x4*)(p + 4);
;                 const f32x4 k0 = *(const LAS f32x4*)(p + 64), k1 = *(const LAS f32x4*)(p + 68);
;                 const f32x4 a0 = *(const LAS f32x4*)(p + 128), a1 = *(const LAS f32x4*)(p + 132);
;                 const f32x4 b0 = *(const LAS f32x4*)(p + 192), b1 = *(const LAS f32x4*)(p + 196);
;                 const f32x4 r0 = *(const LAS f32x4*)(p + 256), r1 = *(const LAS f32x4*)(p + 260);
;                 const float vv = buf[(c & 1) * 12288 + s * 384 + 320 + v];
;                 f32x2 sa2 = S[0] * (f32x2){a0.x, a0.y};
;                 sa2 += S[1] * (f32x2){a0.z, a0.w}; sa2 += S[2] * (f32x2){a1.x, a1.y}; sa2 += S[3] * (f32x2){a1.z, a1.w};
;                 const float sa = red8(sa2.x + sa2.y);
;                 const f32x2 sav = {sa, sa}, vv2 = {vv, vv};
;                 S[0] = S[0] * (f32x2){w0.x, w0.y} + sav * (f32x2){b0.x, b0.y} + vv2 * (f32x2){k0.x, k0.y};
;                 S[1] = S[1] * (f32x2){w0.z, w0.w} + sav * (f32x2){b0.z, b0.w} + vv2 * (f32x2){k0.z, k0.w};
;                 S[2] = S[2] * (f32x2){w1.x, w1.y} + sav * (f32x2){b1.x, b1.y} + vv2 * (f32x2){k1.x, k1.y};
;                 S[3] = S[3] * (f32x2){w1.z, w1.w} + sav * (f32x2){b1.z, b1.w} + vv2 * (f32x2){k1.z, k1.w};
;                 f32x2 y2 = S[0] * (f32x2){r0.x, r0.y};
;                 y2 += S[1] * (f32x2){r0.z, r0.w}; y2 += S[2] * (f32x2){r1.x, r1.y}; y2 += S[3] * (f32x2){r1.z, r1.w};
;                 const float y = red8(y2.x + y2.y);
;                 if (kc == 0) ybuf[s * 64 + v] = y;
	v_add_f32_dpp v192, v192, v192 quad_perm:[1,0,3,2] row_mask:0xf bank_mask:0xf bound_ctrl:1
	v_add_f32_dpp v193, v193, v193 quad_perm:[1,0,3,2] row_mask:0xf bank_mask:0xf bound_ctrl:1
	v_add_f32_dpp v194, v194, v194 quad_perm:[1,0,3,2] row_mask:0xf bank_mask:0xf bound_ctrl:1
	v_add_f32_dpp v195, v195, v195 quad_perm:[1,0,3,2] row_mask:0xf bank_mask:0xf bound_ctrl:1
	v_pk_fma_f32 v[96:97], v[146:147], v[70:71], v[96:97] op_sel:[0,0,0] op_sel_hi:[1,0,1]
	v_pk_fma_f32 v[98:99], v[146:147], v[70:71], v[98:99] op_sel:[0,1,0] op_sel_hi:[1,1,1]
	v_pk_fma_f32 v[100:101], v[146:147], v[72:73], v[100:101] op_sel:[0,0,0] op_sel_hi:[1,0,1]
	v_add_f32_dpp v192, v192, v192 quad_perm:[2,3,0,1] row_mask:0xf bank_mask:0xf bound_ctrl:1
	v_add_f32_dpp v193, v193, v193 quad_perm:[2,3,0,1] row_mask:0xf bank_mask:0xf bound_ctrl:1
	v_add_f32_dpp v194, v194, v194 quad_perm:[2,3,0,1] row_mask:0xf bank_mask:0xf bound_ctrl:1
	v_add_f32_dpp v195, v195, v195 quad_perm:[2,3,0,1] row_mask:0xf bank_mask:0xf bound_ctrl:1
	v_pk_fma_f32 v[102:103], v[146:147], v[72:73], v[102:103] op_sel:[0,1,0] op_sel_hi:[1,1,1]
	v_pk_fma_f32 v[104:105], v[146:147], v[74:75], v[104:105] op_sel:[0,0,0] op_sel_hi:[1,0,1]
	v_pk_fma_f32 v[106:107], v[146:147], v[74:75], v[106:107] op_sel:[0,1,0] op_sel_hi:[1,1,1]
	v_add_f32_dpp v192, v192, v192 row_half_mirror row_mask:0xf bank_mask:0xf bound_ctrl:1
	v_add_f32_dpp v193, v193, v193 row_half_mirror row_mask:0xf bank_mask:0xf bound_ctrl:1
	v_add_f32_dpp v194, v194, v194 row_half_mirror row_mask:0xf bank_mask:0xf bound_ctrl:1
	v_add_f32_dpp v195, v195, v195 row_half_mirror row_mask:0xf bank_mask:0xf bound_ctrl:1
	v_pk_fma_f32 v[108:109], v[146:147], v[76:77], v[108:109] op_sel:[0,0,0] op_sel_hi:[1,0,1]
	s_mov_b64 exec, s[10:11]
	ds_write_b64 v45, v[192:193] offset:5632
	s_mov_b64 exec, s[0:1]
	v_pk_fma_f32 v[110:111], v[146:147], v[76:77], v[110:111] op_sel:[0,1,0] op_sel_hi:[1,1,1]
	s_nop 0
	v_pk_fma_f32 v[96:97], v[194:195], v[78:79], v[96:97] op_sel:[0,0,0] op_sel_hi:[1,0,1]
	v_pk_fma_f32 v[98:99], v[194:195], v[78:79], v[98:99] op_sel:[0,1,0] op_sel_hi:[1,1,1]
	v_pk_fma_f32 v[100:101], v[194:195], v[80:81], v[100:101] op_sel:[0,0,0] op_sel_hi:[1,0,1]
	v_pk_fma_f32 v[102:103], v[194:195], v[80:81], v[102:103] op_sel:[0,1,0] op_sel_hi:[1,1,1]
	v_pk_fma_f32 v[104:105], v[194:195], v[82:83], v[104:105] op_sel:[0,0,0] op_sel_hi:[1,0,1]
	v_pk_fma_f32 v[106:107], v[194:195], v[82:83], v[106:107] op_sel:[0,1,0] op_sel_hi:[1,1,1]
	v_pk_fma_f32 v[108:109], v[194:195], v[84:85], v[108:109] op_sel:[0,0,0] op_sel_hi:[1,0,1]
	v_pk_fma_f32 v[110:111], v[194:195], v[84:85], v[110:111] op_sel:[0,1,0] op_sel_hi:[1,1,1]
	v_pk_mul_f32 v[184:185], v[96:97], v[86:87] op_sel:[0,0] op_sel_hi:[1,0]
	v_pk_mul_f32 v[188:189], v[96:97], v[148:149] op_sel:[0,0] op_sel_hi:[1,0]
	v_pk_mul_f32 v[186:187], v[98:99], v[86:87] op_sel:[0,1] op_sel_hi:[1,1]
	v_pk_mul_f32 v[190:191], v[98:99], v[148:149] op_sel:[0,1] op_sel_hi:[1,1]
	v_pk_fma_f32 v[184:185], v[100:101], v[88:89], v[184:185] op_sel:[0,0,0] op_sel_hi:[1,0,1]
	v_pk_fma_f32 v[188:189], v[100:101], v[150:151], v[188:189] op_sel:[0,0,0] op_sel_hi:[1,0,1]
	v_pk_fma_f32 v[186:187], v[102:103], v[88:89], v[186:187] op_sel:[0,1,0] op_sel_hi:[1,1,1]
	v_pk_fma_f32 v[190:191], v[102:103], v[150:151], v[190:191] op_sel:[0,1,0] op_sel_hi:[1,1,1]
	v_pk_fma_f32 v[184:185], v[104:105], v[90:91], v[184:185] op_sel:[0,0,0] op_sel_hi:[1,0,1]
	v_pk_fma_f32 v[188:189], v[104:105], v[152:153], v[188:189] op_sel:[0,0,0] op_sel_hi:[1,0,1]
	v_pk_fma_f32 v[186:187], v[106:107], v[90:91], v[186:187] op_sel:[0,1,0] op_sel_hi:[1,1,1]
	v_pk_fma_f32 v[190:191], v[106:107], v[152:153], v[190:191] op_sel:[0,1,0] op_sel_hi:[1,1,1]
	v_pk_fma_f32 v[184:185], v[108:109], v[92:93], v[184:185] op_sel:[0,0,0] op_sel_hi:[1,0,1]
	v_pk_fma_f32 v[188:189], v[108:109], v[154:155], v[188:189] op_sel:[0,0,0] op_sel_hi:[1,0,1]
	v_pk_fma_f32 v[186:187], v[110:111], v[92:93], v[186:187] op_sel:[0,1,0] op_sel_hi:[1,1,1]
	v_pk_fma_f32 v[190:191], v[110:111], v[154:155], v[190:191] op_sel:[0,1,0] op_sel_hi:[1,1,1]
	v_pk_add_f32 v[192:193], v[184:185], v[186:187]
	v_pk_add_f32 v[194:195], v[188:189], v[190:191]
	ds_read_b128 v[70:73], v44 offset:38656
	ds_read_b128 v[74:77], v44 offset:38672
	ds_read_b128 v[78:81], v44 offset:39168
	ds_read_b128 v[82:85], v44 offset:39184
	ds_read_b128 v[86:89], v44 offset:39424
	ds_read_b128 v[90:93], v44 offset:39440
	ds_read_b64 v[146:147], v46 offset:38400
	ds_read_b128 v[148:151], v44 offset:40448
	ds_read_b128 v[152:155], v44 offset:40464
	s_waitcnt lgkmcnt(10)
; #define LAS __attribute__((address_space(3)))
; __device__ __forceinline__ float red8(float x) { x += dpp_mov<0xB1>(x); x += dpp_mov<0x4E>(x); x += dpp_mov<0x141>(x); return x; }
; __device__ __forceinline__ void scan_phase(const KP& P, LAS unsigned char* lds, const int tid, const int bx, const int G) {
;     ...
;             for (int s = 0; s < 32; ++s) {
;                 const LAS float* p = cb + s * 384;
;                 const f32x4 w0 = *(const LAS f32x4*)(p), w1 = *(const LAS f32x4*)(p + 4);
;                 const f32x4 k0 = *(const LAS f32x4*)(p + 64), k1 = *(const LAS f32x4*)(p + 68);
;                 const f32x4 a0 = *(const LAS f32x4*)(p + 128), a1 = *(const LAS f32x4*)(p + 132);
;                 const f32x4 b0 = *(const LAS f32x4*)(p + 192), b1 = *(const LAS f32x4*)(p + 196);
;                 const f32x4 r0 = *(const LAS f32x4*)(p + 256), r1 = *(const LAS f32x4*)(p + 260);
;                 const float vv = buf[(c & 1) * 12288 + s * 384 + 320 + v];
;                 f32x2 sa2 = S[0] * (f32x2){a0.x, a0.y};
;                 sa2 += S[1] * (f32x2){a0.z, a0.w}; sa2 += S[2] * (f32x2){a1.x, a1.y}; sa2 += S[3] * (f32x2){a1.z, a1.w};
;                 const float sa = red8(sa2.x + sa2.y);
;                 const f32x2 sav = {sa, sa}, vv2 = {vv, vv};
;                 S[0] = S[0] * (f32x2){w0.x, w0.y} + sav * (f32x2){b0.x, b0.y} + vv2 * (f32x2){k0.x, k0.y};
;                 S[1] = S[1] * (f32x2){w0.z, w0.w} + sav * (f32x2){b0.z, b0.w} + vv2 * (f32x2){k0.z, k0.w};
;                 S[2] = S[2] * (f32x2){w1.x, w1.y} + sav * (f32x2){b1.x, b1.y} + vv2 * (f32x2){k1.x, k1.y};
;                 S[3] = S[3] * (f32x2){w1.z, w1.w} + sav * (f32x2){b1.z, b1.w} + vv2 * (f32x2){k1.z, k1.w};
;                 f32x2 y2 = S[0] * (f32x2){r0.x, r0.y};
;                 y2 += S[1] * (f32x2){r0.z, r0.w}; y2 += S[2] * (f32x2){r1.x, r1.y}; y2 += S[3] * (f32x2){r1.z, r1.w};
;                 const float y = red8(y2.x + y2.y);
;                 if (kc == 0) ybuf[s * 64 + v] = y;
	v_add_f32_dpp v192, v192, v192 quad_perm:[1,0,3,2] row_mask:0xf bank_mask:0xf bound_ctrl:1
	v_add_f32_dpp v193, v193, v193 quad_perm:[1,0,3,2] row_mask:0xf bank_mask:0xf bound_ctrl:1
	v_add_f32_dpp v194, v194, v194 quad_perm:[1,0,3,2] row_mask:0xf bank_mask:0xf bound_ctrl:1
	v_add_f32_dpp v195, v195, v195 quad_perm:[1,0,3,2] row_mask:0xf bank_mask:0xf bound_ctrl:1
	v_pk_fma_f32 v[96:97], v[144:145], v[120:121], v[96:97] op_sel:[0,0,0] op_sel_hi:[1,0,1]
	v_pk_fma_f32 v[98:99], v[144:145], v[120:121], v[98:99] op_sel:[0,1,0] op_sel_hi:[1,1,1]
	v_pk_fma_f32 v[100:101], v[144:145], v[122:123], v[100:101] op_sel:[0,0,0] op_sel_hi:[1,0,1]
	v_add_f32_dpp v192, v192, v192 quad_perm:[2,3,0,1] row_mask:0xf bank_mask:0xf bound_ctrl:1
	v_add_f32_dpp v193, v193, v193 quad_perm:[2,3,0,1] row_mask:0xf bank_mask:0xf bound_ctrl:1
	v_add_f32_dpp v194, v194, v194 quad_perm:[2,3,0,1] row_mask:0xf bank_mask:0xf bound_ctrl:1
	v_add_f32_dpp v195, v195, v195 quad_perm:[2,3,0,1] row_mask:0xf bank_mask:0xf bound_ctrl:1
	v_pk_fma_f32 v[102:103], v[144:145], v[122:123], v[102:103] op_sel:[0,1,0] op_sel_hi:[1,1,1]
	v_pk_fma_f32 v[104:105], v[144:145], v[124:125], v[104:105] op_sel:[0,0,0] op_sel_hi:[1,0,1]
	v_pk_fma_f32 v[106:107], v[144:145], v[124:125], v[106:107] op_sel:[0,1,0] op_sel_hi:[1,1,1]
	v_add_f32_dpp v192, v192, v192 row_half_mirror row_mask:0xf bank_mask:0xf bound_ctrl:1
	v_add_f32_dpp v193, v193, v193 row_half_mirror row_mask:0xf bank_mask:0xf bound_ctrl:1
	v_add_f32_dpp v194, v194, v194 row_half_mirror row_mask:0xf bank_mask:0xf bound_ctrl:1
	v_add_f32_dpp v195, v195, v195 row_half_mirror row_mask:0xf bank_mask:0xf bound_ctrl:1
	v_pk_fma_f32 v[108:109], v[144:145], v[126:127], v[108:109] op_sel:[0,0,0] op_sel_hi:[1,0,1]
	s_mov_b64 exec, s[10:11]
	ds_write_b64 v45, v[192:193] offset:5888
	s_mov_b64 exec, s[0:1]
	v_pk_fma_f32 v[110:111], v[144:145], v[126:127], v[110:111] op_sel:[0,1,0] op_sel_hi:[1,1,1]
	s_nop 0
	v_pk_fma_f32 v[96:97], v[194:195], v[128:129], v[96:97] op_sel:[0,0,0] op_sel_hi:[1,0,1]
	v_pk_fma_f32 v[98:99], v[194:195], v[128:129], v[98:99] op_sel:[0,1,0] op_sel_hi:[1,1,1]
	v_pk_fma_f32 v[100:101], v[194:195], v[130:131], v[100:101] op_sel:[0,0,0] op_sel_hi:[1,0,1]
	v_pk_fma_f32 v[102:103], v[194:195], v[130:131], v[102:103] op_sel:[0,1,0] op_sel_hi:[1,1,1]
	v_pk_fma_f32 v[104:105], v[194:195], v[132:133], v[104:105] op_sel:[0,0,0] op_sel_hi:[1,0,1]
	v_pk_fma_f32 v[106:107], v[194:195], v[132:133], v[106:107] op_sel:[0,1,0] op_sel_hi:[1,1,1]
	v_pk_fma_f32 v[108:109], v[194:195], v[134:135], v[108:109] op_sel:[0,0,0] op_sel_hi:[1,0,1]
	v_pk_fma_f32 v[110:111], v[194:195], v[134:135], v[110:111] op_sel:[0,1,0] op_sel_hi:[1,1,1]
	v_pk_mul_f32 v[184:185], v[96:97], v[136:137] op_sel:[0,0] op_sel_hi:[1,0]
	v_pk_mul_f32 v[188:189], v[96:97], v[156:157] op_sel:[0,0] op_sel_hi:[1,0]
	v_pk_mul_f32 v[186:187], v[98:99], v[136:137] op_sel:[0,1] op_sel_hi:[1,1]
	v_pk_mul_f32 v[190:191], v[98:99], v[156:157] op_sel:[0,1] op_sel_hi:[1,1]
	v_pk_fma_f32 v[184:185], v[100:101], v[138:139], v[184:185] op_sel:[0,0,0] op_sel_hi:[1,0,1]
	v_pk_fma_f32 v[188:189], v[100:101], v[158:159], v[188:189] op_sel:[0,0,0] op_sel_hi:[1,0,1]
	v_pk_fma_f32 v[186:187], v[102:103], v[138:139], v[186:187] op_sel:[0,1,0] op_sel_hi:[1,1,1]
	v_pk_fma_f32 v[190:191], v[102:103], v[158:159], v[190:191] op_sel:[0,1,0] op_sel_hi:[1,1,1]
	v_pk_fma_f32 v[184:185], v[104:105], v[140:141], v[184:185] op_sel:[0,0,0] op_sel_hi:[1,0,1]
	v_pk_fma_f32 v[188:189], v[104:105], v[160:161], v[188:189] op_sel:[0,0,0] op_sel_hi:[1,0,1]
	v_pk_fma_f32 v[186:187], v[106:107], v[140:141], v[186:187] op_sel:[0,1,0] op_sel_hi:[1,1,1]
	v_pk_fma_f32 v[190:191], v[106:107], v[160:161], v[190:191] op_sel:[0,1,0] op_sel_hi:[1,1,1]
	v_pk_fma_f32 v[184:185], v[108:109], v[142:143], v[184:185] op_sel:[0,0,0] op_sel_hi:[1,0,1]
	v_pk_fma_f32 v[188:189], v[108:109], v[162:163], v[188:189] op_sel:[0,0,0] op_sel_hi:[1,0,1]
	v_pk_fma_f32 v[186:187], v[110:111], v[142:143], v[186:187] op_sel:[0,1,0] op_sel_hi:[1,1,1]
	v_pk_fma_f32 v[190:191], v[110:111], v[162:163], v[190:191] op_sel:[0,1,0] op_sel_hi:[1,1,1]
	v_pk_add_f32 v[192:193], v[184:185], v[186:187]
	v_pk_add_f32 v[194:195], v[188:189], v[190:191]
	ds_read_b128 v[120:123], v44 offset:40192
	ds_read_b128 v[124:127], v44 offset:40208
	ds_read_b128 v[128:131], v44 offset:40704
	ds_read_b128 v[132:135], v44 offset:40720
	ds_read_b128 v[136:139], v44 offset:40960
	ds_read_b128 v[140:143], v44 offset:40976
	ds_read_b64 v[144:145], v46 offset:39936
	ds_read_b128 v[156:159], v44 offset:41984
	ds_read_b128 v[160:163], v44 offset:42000
	s_waitcnt lgkmcnt(10)
; #define LAS __attribute__((address_space(3)))
; __device__ __forceinline__ float red8(float x) { x += dpp_mov<0xB1>(x); x += dpp_mov<0x4E>(x); x += dpp_mov<0x141>(x); return x; }
; __device__ __forceinline__ void scan_phase(const KP& P, LAS unsigned char* lds, const int tid, const int bx, const int G) {
;     ...
;             for (int s = 0; s < 32; ++s) {
;                 const LAS float* p = cb + s * 384;
;                 const f32x4 w0 = *(const LAS f32x4*)(p), w1 = *(const LAS f32x4*)(p + 4);
;                 const f32x4 k0 = *(const LAS f32x4*)(p + 64), k1 = *(const LAS f32x4*)(p + 68);
;                 const f32x4 a0 = *(const LAS f32x4*)(p + 128), a1 = *(const LAS f32x4*)(p + 132);
;                 const f32x4 b0 = *(const LAS f32x4*)(p + 192), b1 = *(const LAS f32x4*)(p + 196);
;                 const f32x4 r0 = *(const LAS f32x4*)(p + 256), r1 = *(const LAS f32x4*)(p + 260);
;                 const float vv = buf[(c & 1) * 12288 + s * 384 + 320 + v];
;                 f32x2 sa2 = S[0] * (f32x2){a0.x, a0.y};
;                 sa2 += S[1] * (f32x2){a0.z, a0.w}; sa2 += S[2] * (f32x2){a1.x, a1.y}; sa2 += S[3] * (f32x2){a1.z, a1.w};
;                 const float sa = red8(sa2.x + sa2.y);
;                 const f32x2 sav = {sa, sa}, vv2 = {vv, vv};
;                 S[0] = S[0] * (f32x2){w0.x, w0.y} + sav * (f32x2){b0.x, b0.y} + vv2 * (f32x2){k0.x, k0.y};
;                 S[1] = S[1] * (f32x2){w0.z, w0.w} + sav * (f32x2){b0.z, b0.w} + vv2 * (f32x2){k0.z, k0.w};
;                 S[2] = S[2] * (f32x2){w1.x, w1.y} + sav * (f32x2){b1.x, b1.y} + vv2 * (f32x2){k1.x, k1.y};
;                 S[3] = S[3] * (f32x2){w1.z, w1.w} + sav * (f32x2){b1.z, b1.w} + vv2 * (f32x2){k1.z, k1.w};
;                 f32x2 y2 = S[0] * (f32x2){r0.x, r0.y};
;                 y2 += S[1] * (f32x2){r0.z, r0.w}; y2 += S[2] * (f32x2){r1.x, r1.y}; y2 += S[3] * (f32x2){r1.z, r1.w};
;                 const float y = red8(y2.x + y2.y);
;                 if (kc == 0) ybuf[s * 64 + v] = y;
	v_add_f32_dpp v192, v192, v192 quad_perm:[1,0,3,2] row_mask:0xf bank_mask:0xf bound_ctrl:1
	v_add_f32_dpp v193, v193, v193 quad_perm:[1,0,3,2] row_mask:0xf bank_mask:0xf bound_ctrl:1
	v_add_f32_dpp v194, v194, v194 quad_perm:[1,0,3,2] row_mask:0xf bank_mask:0xf bound_ctrl:1
	v_add_f32_dpp v195, v195, v195 quad_perm:[1,0,3,2] row_mask:0xf bank_mask:0xf bound_ctrl:1
	v_pk_fma_f32 v[96:97], v[146:147], v[70:71], v[96:97] op_sel:[0,0,0] op_sel_hi:[1,0,1]
	v_pk_fma_f32 v[98:99], v[146:147], v[70:71], v[98:99] op_sel:[0,1,0] op_sel_hi:[1,1,1]
	v_pk_fma_f32 v[100:101], v[146:147], v[72:73], v[100:101] op_sel:[0,0,0] op_sel_hi:[1,0,1]
	v_add_f32_dpp v192, v192, v192 quad_perm:[2,3,0,1] row_mask:0xf bank_mask:0xf bound_ctrl:1
	v_add_f32_dpp v193, v193, v193 quad_perm:[2,3,0,1] row_mask:0xf bank_mask:0xf bound_ctrl:1
	v_add_f32_dpp v194, v194, v194 quad_perm:[2,3,0,1] row_mask:0xf bank_mask:0xf bound_ctrl:1
	v_add_f32_dpp v195, v195, v195 quad_perm:[2,3,0,1] row_mask:0xf bank_mask:0xf bound_ctrl:1
	v_pk_fma_f32 v[102:103], v[146:147], v[72:73], v[102:103] op_sel:[0,1,0] op_sel_hi:[1,1,1]
	v_pk_fma_f32 v[104:105], v[146:147], v[74:75], v[104:105] op_sel:[0,0,0] op_sel_hi:[1,0,1]
	v_pk_fma_f32 v[106:107], v[146:147], v[74:75], v[106:107] op_sel:[0,1,0] op_sel_hi:[1,1,1]
	v_add_f32_dpp v192, v192, v192 row_half_mirror row_mask:0xf bank_mask:0xf bound_ctrl:1
	v_add_f32_dpp v193, v193, v193 row_half_mirror row_mask:0xf bank_mask:0xf bound_ctrl:1
	v_add_f32_dpp v194, v194, v194 row_half_mirror row_mask:0xf bank_mask:0xf bound_ctrl:1
	v_add_f32_dpp v195, v195, v195 row_half_mirror row_mask:0xf bank_mask:0xf bound_ctrl:1
	v_pk_fma_f32 v[108:109], v[146:147], v[76:77], v[108:109] op_sel:[0,0,0] op_sel_hi:[1,0,1]
	s_mov_b64 exec, s[10:11]
	ds_write_b64 v45, v[192:193] offset:6144
	s_mov_b64 exec, s[0:1]
	v_pk_fma_f32 v[110:111], v[146:147], v[76:77], v[110:111] op_sel:[0,1,0] op_sel_hi:[1,1,1]
	s_nop 0
	v_pk_fma_f32 v[96:97], v[194:195], v[78:79], v[96:97] op_sel:[0,0,0] op_sel_hi:[1,0,1]
	v_pk_fma_f32 v[98:99], v[194:195], v[78:79], v[98:99] op_sel:[0,1,0] op_sel_hi:[1,1,1]
	v_pk_fma_f32 v[100:101], v[194:195], v[80:81], v[100:101] op_sel:[0,0,0] op_sel_hi:[1,0,1]
	v_pk_fma_f32 v[102:103], v[194:195], v[80:81], v[102:103] op_sel:[0,1,0] op_sel_hi:[1,1,1]
	v_pk_fma_f32 v[104:105], v[194:195], v[82:83], v[104:105] op_sel:[0,0,0] op_sel_hi:[1,0,1]
	v_pk_fma_f32 v[106:107], v[194:195], v[82:83], v[106:107] op_sel:[0,1,0] op_sel_hi:[1,1,1]
	v_pk_fma_f32 v[108:109], v[194:195], v[84:85], v[108:109] op_sel:[0,0,0] op_sel_hi:[1,0,1]
	v_pk_fma_f32 v[110:111], v[194:195], v[84:85], v[110:111] op_sel:[0,1,0] op_sel_hi:[1,1,1]
	v_pk_mul_f32 v[184:185], v[96:97], v[86:87] op_sel:[0,0] op_sel_hi:[1,0]
	v_pk_mul_f32 v[188:189], v[96:97], v[148:149] op_sel:[0,0] op_sel_hi:[1,0]
	v_pk_mul_f32 v[186:187], v[98:99], v[86:87] op_sel:[0,1] op_sel_hi:[1,1]
	v_pk_mul_f32 v[190:191], v[98:99], v[148:149] op_sel:[0,1] op_sel_hi:[1,1]
	v_pk_fma_f32 v[184:185], v[100:101], v[88:89], v[184:185] op_sel:[0,0,0] op_sel_hi:[1,0,1]
	v_pk_fma_f32 v[188:189], v[100:101], v[150:151], v[188:189] op_sel:[0,0,0] op_sel_hi:[1,0,1]
	v_pk_fma_f32 v[186:187], v[102:103], v[88:89], v[186:187] op_sel:[0,1,0] op_sel_hi:[1,1,1]
	v_pk_fma_f32 v[190:191], v[102:103], v[150:151], v[190:191] op_sel:[0,1,0] op_sel_hi:[1,1,1]
	v_pk_fma_f32 v[184:185], v[104:105], v[90:91], v[184:185] op_sel:[0,0,0] op_sel_hi:[1,0,1]
	v_pk_fma_f32 v[188:189], v[104:105], v[152:153], v[188:189] op_sel:[0,0,0] op_sel_hi:[1,0,1]
	v_pk_fma_f32 v[186:187], v[106:107], v[90:91], v[186:187] op_sel:[0,1,0] op_sel_hi:[1,1,1]
	v_pk_fma_f32 v[190:191], v[106:107], v[152:153], v[190:191] op_sel:[0,1,0] op_sel_hi:[1,1,1]
	v_pk_fma_f32 v[184:185], v[108:109], v[92:93], v[184:185] op_sel:[0,0,0] op_sel_hi:[1,0,1]
	v_pk_fma_f32 v[188:189], v[108:109], v[154:155], v[188:189] op_sel:[0,0,0] op_sel_hi:[1,0,1]
	v_pk_fma_f32 v[186:187], v[110:111], v[92:93], v[186:187] op_sel:[0,1,0] op_sel_hi:[1,1,1]
	v_pk_fma_f32 v[190:191], v[110:111], v[154:155], v[190:191] op_sel:[0,1,0] op_sel_hi:[1,1,1]
	v_pk_add_f32 v[192:193], v[184:185], v[186:187]
	v_pk_add_f32 v[194:195], v[188:189], v[190:191]
	ds_read_b128 v[70:73], v44 offset:41728
	ds_read_b128 v[74:77], v44 offset:41744
	ds_read_b128 v[78:81], v44 offset:42240
	ds_read_b128 v[82:85], v44 offset:42256
	ds_read_b128 v[86:89], v44 offset:42496
	ds_read_b128 v[90:93], v44 offset:42512
	ds_read_b64 v[146:147], v46 offset:41472
	ds_read_b128 v[148:151], v44 offset:43520
	ds_read_b128 v[152:155], v44 offset:43536
	s_waitcnt lgkmcnt(10)
; #define LAS __attribute__((address_space(3)))
; __device__ __forceinline__ float red8(float x) { x += dpp_mov<0xB1>(x); x += dpp_mov<0x4E>(x); x += dpp_mov<0x141>(x); return x; }
; __device__ __forceinline__ void scan_phase(const KP& P, LAS unsigned char* lds, const int tid, const int bx, const int G) {
;     ...
;             for (int s = 0; s < 32; ++s) {
;                 const LAS float* p = cb + s * 384;
;                 const f32x4 w0 = *(const LAS f32x4*)(p), w1 = *(const LAS f32x4*)(p + 4);
;                 const f32x4 k0 = *(const LAS f32x4*)(p + 64), k1 = *(const LAS f32x4*)(p + 68);
;                 const f32x4 a0 = *(const LAS f32x4*)(p + 128), a1 = *(const LAS f32x4*)(p + 132);
;                 const f32x4 b0 = *(const LAS f32x4*)(p + 192), b1 = *(const LAS f32x4*)(p + 196);
;                 const f32x4 r0 = *(const LAS f32x4*)(p + 256), r1 = *(const LAS f32x4*)(p + 260);
;                 const float vv = buf[(c & 1) * 12288 + s * 384 + 320 + v];
;                 f32x2 sa2 = S[0] * (f32x2){a0.x, a0.y};
;                 sa2 += S[1] * (f32x2){a0.z, a0.w}; sa2 += S[2] * (f32x2){a1.x, a1.y}; sa2 += S[3] * (f32x2){a1.z, a1.w};
;                 const float sa = red8(sa2.x + sa2.y);
;                 const f32x2 sav = {sa, sa}, vv2 = {vv, vv};
;                 S[0] = S[0] * (f32x2){w0.x, w0.y} + sav * (f32x2){b0.x, b0.y} + vv2 * (f32x2){k0.x, k0.y};
;                 S[1] = S[1] * (f32x2){w0.z, w0.w} + sav * (f32x2){b0.z, b0.w} + vv2 * (f32x2){k0.z, k0.w};
;                 S[2] = S[2] * (f32x2){w1.x, w1.y} + sav * (f32x2){b1.x, b1.y} + vv2 * (f32x2){k1.x, k1.y};
;                 S[3] = S[3] * (f32x2){w1.z, w1.w} + sav * (f32x2){b1.z, b1.w} + vv2 * (f32x2){k1.z, k1.w};
;                 f32x2 y2 = S[0] * (f32x2){r0.x, r0.y};
;                 y2 += S[1] * (f32x2){r0.z, r0.w}; y2 += S[2] * (f32x2){r1.x, r1.y}; y2 += S[3] * (f32x2){r1.z, r1.w};
;                 const float y = red8(y2.x + y2.y);
;                 if (kc == 0) ybuf[s * 64 + v] = y;
	v_add_f32_dpp v192, v192, v192 quad_perm:[1,0,3,2] row_mask:0xf bank_mask:0xf bound_ctrl:1
	v_add_f32_dpp v193, v193, v193 quad_perm:[1,0,3,2] row_mask:0xf bank_mask:0xf bound_ctrl:1
	v_add_f32_dpp v194, v194, v194 quad_perm:[1,0,3,2] row_mask:0xf bank_mask:0xf bound_ctrl:1
	v_add_f32_dpp v195, v195, v195 quad_perm:[1,0,3,2] row_mask:0xf bank_mask:0xf bound_ctrl:1
	v_pk_fma_f32 v[96:97], v[144:145], v[120:121], v[96:97] op_sel:[0,0,0] op_sel_hi:[1,0,1]
	v_pk_fma_f32 v[98:99], v[144:145], v[120:121], v[98:99] op_sel:[0,1,0] op_sel_hi:[1,1,1]
	v_pk_fma_f32 v[100:101], v[144:145], v[122:123], v[100:101] op_sel:[0,0,0] op_sel_hi:[1,0,1]
	v_add_f32_dpp v192, v192, v192 quad_perm:[2,3,0,1] row_mask:0xf bank_mask:0xf bound_ctrl:1
	v_add_f32_dpp v193, v193, v193 quad_perm:[2,3,0,1] row_mask:0xf bank_mask:0xf bound_ctrl:1
	v_add_f32_dpp v194, v194, v194 quad_perm:[2,3,0,1] row_mask:0xf bank_mask:0xf bound_ctrl:1
	v_add_f32_dpp v195, v195, v195 quad_perm:[2,3,0,1] row_mask:0xf bank_mask:0xf bound_ctrl:1
	v_pk_fma_f32 v[102:103], v[144:145], v[122:123], v[102:103] op_sel:[0,1,0] op_sel_hi:[1,1,1]
	v_pk_fma_f32 v[104:105], v[144:145], v[124:125], v[104:105] op_sel:[0,0,0] op_sel_hi:[1,0,1]
	v_pk_fma_f32 v[106:107], v[144:145], v[124:125], v[106:107] op_sel:[0,1,0] op_sel_hi:[1,1,1]
	v_add_f32_dpp v192, v192, v192 row_half_mirror row_mask:0xf bank_mask:0xf bound_ctrl:1
	v_add_f32_dpp v193, v193, v193 row_half_mirror row_mask:0xf bank_mask:0xf bound_ctrl:1
	v_add_f32_dpp v194, v194, v194 row_half_mirror row_mask:0xf bank_mask:0xf bound_ctrl:1
	v_add_f32_dpp v195, v195, v195 row_half_mirror row_mask:0xf bank_mask:0xf bound_ctrl:1
	v_pk_fma_f32 v[108:109], v[144:145], v[126:127], v[108:109] op_sel:[0,0,0] op_sel_hi:[1,0,1]
	s_mov_b64 exec, s[10:11]
	ds_write_b64 v45, v[192:193] offset:6400
	s_mov_b64 exec, s[0:1]
	v_pk_fma_f32 v[110:111], v[144:145], v[126:127], v[110:111] op_sel:[0,1,0] op_sel_hi:[1,1,1]
	s_nop 0
	v_pk_fma_f32 v[96:97], v[194:195], v[128:129], v[96:97] op_sel:[0,0,0] op_sel_hi:[1,0,1]
	v_pk_fma_f32 v[98:99], v[194:195], v[128:129], v[98:99] op_sel:[0,1,0] op_sel_hi:[1,1,1]
	v_pk_fma_f32 v[100:101], v[194:195], v[130:131], v[100:101] op_sel:[0,0,0] op_sel_hi:[1,0,1]
	v_pk_fma_f32 v[102:103], v[194:195], v[130:131], v[102:103] op_sel:[0,1,0] op_sel_hi:[1,1,1]
	v_pk_fma_f32 v[104:105], v[194:195], v[132:133], v[104:105] op_sel:[0,0,0] op_sel_hi:[1,0,1]
	v_pk_fma_f32 v[106:107], v[194:195], v[132:133], v[106:107] op_sel:[0,1,0] op_sel_hi:[1,1,1]
	v_pk_fma_f32 v[108:109], v[194:195], v[134:135], v[108:109] op_sel:[0,0,0] op_sel_hi:[1,0,1]
	v_pk_fma_f32 v[110:111], v[194:195], v[134:135], v[110:111] op_sel:[0,1,0] op_sel_hi:[1,1,1]
	v_pk_mul_f32 v[184:185], v[96:97], v[136:137] op_sel:[0,0] op_sel_hi:[1,0]
	v_pk_mul_f32 v[188:189], v[96:97], v[156:157] op_sel:[0,0] op_sel_hi:[1,0]
	v_pk_mul_f32 v[186:187], v[98:99], v[136:137] op_sel:[0,1] op_sel_hi:[1,1]
	v_pk_mul_f32 v[190:191], v[98:99], v[156:157] op_sel:[0,1] op_sel_hi:[1,1]
	v_pk_fma_f32 v[184:185], v[100:101], v[138:139], v[184:185] op_sel:[0,0,0] op_sel_hi:[1,0,1]
	v_pk_fma_f32 v[188:189], v[100:101], v[158:159], v[188:189] op_sel:[0,0,0] op_sel_hi:[1,0,1]
	v_pk_fma_f32 v[186:187], v[102:103], v[138:139], v[186:187] op_sel:[0,1,0] op_sel_hi:[1,1,1]
	v_pk_fma_f32 v[190:191], v[102:103], v[158:159], v[190:191] op_sel:[0,1,0] op_sel_hi:[1,1,1]
	v_pk_fma_f32 v[184:185], v[104:105], v[140:141], v[184:185] op_sel:[0,0,0] op_sel_hi:[1,0,1]
	v_pk_fma_f32 v[188:189], v[104:105], v[160:161], v[188:189] op_sel:[0,0,0] op_sel_hi:[1,0,1]
	v_pk_fma_f32 v[186:187], v[106:107], v[140:141], v[186:187] op_sel:[0,1,0] op_sel_hi:[1,1,1]
	v_pk_fma_f32 v[190:191], v[106:107], v[160:161], v[190:191] op_sel:[0,1,0] op_sel_hi:[1,1,1]
	v_pk_fma_f32 v[184:185], v[108:109], v[142:143], v[184:185] op_sel:[0,0,0] op_sel_hi:[1,0,1]
	v_pk_fma_f32 v[188:189], v[108:109], v[162:163], v[188:189] op_sel:[0,0,0] op_sel_hi:[1,0,1]
	v_pk_fma_f32 v[186:187], v[110:111], v[142:143], v[186:187] op_sel:[0,1,0] op_sel_hi:[1,1,1]
	v_pk_fma_f32 v[190:191], v[110:111], v[162:163], v[190:191] op_sel:[0,1,0] op_sel_hi:[1,1,1]
	v_pk_add_f32 v[192:193], v[184:185], v[186:187]
	v_pk_add_f32 v[194:195], v[188:189], v[190:191]
	ds_read_b128 v[120:123], v44 offset:43264
	ds_read_b128 v[124:127], v44 offset:43280
	ds_read_b128 v[128:131], v44 offset:43776
	ds_read_b128 v[132:135], v44 offset:43792
	ds_read_b128 v[136:139], v44 offset:44032
	ds_read_b128 v[140:143], v44 offset:44048
	ds_read_b64 v[144:145], v46 offset:43008
	ds_read_b128 v[156:159], v44 offset:45056
	ds_read_b128 v[160:163], v44 offset:45072
	s_waitcnt lgkmcnt(10)
; #define LAS __attribute__((address_space(3)))
; __device__ __forceinline__ float red8(float x) { x += dpp_mov<0xB1>(x); x += dpp_mov<0x4E>(x); x += dpp_mov<0x141>(x); return x; }
; __device__ __forceinline__ void scan_phase(const KP& P, LAS unsigned char* lds, const int tid, const int bx, const int G) {
;     ...
;             for (int s = 0; s < 32; ++s) {
;                 const LAS float* p = cb + s * 384;
;                 const f32x4 w0 = *(const LAS f32x4*)(p), w1 = *(const LAS f32x4*)(p + 4);
;                 const f32x4 k0 = *(const LAS f32x4*)(p + 64), k1 = *(const LAS f32x4*)(p + 68);
;                 const f32x4 a0 = *(const LAS f32x4*)(p + 128), a1 = *(const LAS f32x4*)(p + 132);
;                 const f32x4 b0 = *(const LAS f32x4*)(p + 192), b1 = *(const LAS f32x4*)(p + 196);
;                 const f32x4 r0 = *(const LAS f32x4*)(p + 256), r1 = *(const LAS f32x4*)(p + 260);
;                 const float vv = buf[(c & 1) * 12288 + s * 384 + 320 + v];
;                 f32x2 sa2 = S[0] * (f32x2){a0.x, a0.y};
;                 sa2 += S[1] * (f32x2){a0.z, a0.w}; sa2 += S[2] * (f32x2){a1.x, a1.y}; sa2 += S[3] * (f32x2){a1.z, a1.w};
;                 const float sa = red8(sa2.x + sa2.y);
;                 const f32x2 sav = {sa, sa}, vv2 = {vv, vv};
;                 S[0] = S[0] * (f32x2){w0.x, w0.y} + sav * (f32x2){b0.x, b0.y} + vv2 * (f32x2){k0.x, k0.y};
;                 S[1] = S[1] * (f32x2){w0.z, w0.w} + sav * (f32x2){b0.z, b0.w} + vv2 * (f32x2){k0.z, k0.w};
;                 S[2] = S[2] * (f32x2){w1.x, w1.y} + sav * (f32x2){b1.x, b1.y} + vv2 * (f32x2){k1.x, k1.y};
;                 S[3] = S[3] * (f32x2){w1.z, w1.w} + sav * (f32x2){b1.z, b1.w} + vv2 * (f32x2){k1.z, k1.w};
;                 f32x2 y2 = S[0] * (f32x2){r0.x, r0.y};
;                 y2 += S[1] * (f32x2){r0.z, r0.w}; y2 += S[2] * (f32x2){r1.x, r1.y}; y2 += S[3] * (f32x2){r1.z, r1.w};
;                 const float y = red8(y2.x + y2.y);
;                 if (kc == 0) ybuf[s * 64 + v] = y;
	v_add_f32_dpp v192, v192, v192 quad_perm:[1,0,3,2] row_mask:0xf bank_mask:0xf bound_ctrl:1
	v_add_f32_dpp v193, v193, v193 quad_perm:[1,0,3,2] row_mask:0xf bank_mask:0xf bound_ctrl:1
	v_add_f32_dpp v194, v194, v194 quad_perm:[1,0,3,2] row_mask:0xf bank_mask:0xf bound_ctrl:1
	v_add_f32_dpp v195, v195, v195 quad_perm:[1,0,3,2] row_mask:0xf bank_mask:0xf bound_ctrl:1
	v_pk_fma_f32 v[96:97], v[146:147], v[70:71], v[96:97] op_sel:[0,0,0] op_sel_hi:[1,0,1]
	v_pk_fma_f32 v[98:99], v[146:147], v[70:71], v[98:99] op_sel:[0,1,0] op_sel_hi:[1,1,1]
	v_pk_fma_f32 v[100:101], v[146:147], v[72:73], v[100:101] op_sel:[0,0,0] op_sel_hi:[1,0,1]
	v_add_f32_dpp v192, v192, v192 quad_perm:[2,3,0,1] row_mask:0xf bank_mask:0xf bound_ctrl:1
	v_add_f32_dpp v193, v193, v193 quad_perm:[2,3,0,1] row_mask:0xf bank_mask:0xf bound_ctrl:1
	v_add_f32_dpp v194, v194, v194 quad_perm:[2,3,0,1] row_mask:0xf bank_mask:0xf bound_ctrl:1
	v_add_f32_dpp v195, v195, v195 quad_perm:[2,3,0,1] row_mask:0xf bank_mask:0xf bound_ctrl:1
	v_pk_fma_f32 v[102:103], v[146:147], v[72:73], v[102:103] op_sel:[0,1,0] op_sel_hi:[1,1,1]
	v_pk_fma_f32 v[104:105], v[146:147], v[74:75], v[104:105] op_sel:[0,0,0] op_sel_hi:[1,0,1]
	v_pk_fma_f32 v[106:107], v[146:147], v[74:75], v[106:107] op_sel:[0,1,0] op_sel_hi:[1,1,1]
	v_add_f32_dpp v192, v192, v192 row_half_mirror row_mask:0xf bank_mask:0xf bound_ctrl:1
	v_add_f32_dpp v193, v193, v193 row_half_mirror row_mask:0xf bank_mask:0xf bound_ctrl:1
	v_add_f32_dpp v194, v194, v194 row_half_mirror row_mask:0xf bank_mask:0xf bound_ctrl:1
	v_add_f32_dpp v195, v195, v195 row_half_mirror row_mask:0xf bank_mask:0xf bound_ctrl:1
	v_pk_fma_f32 v[108:109], v[146:147], v[76:77], v[108:109] op_sel:[0,0,0] op_sel_hi:[1,0,1]
	s_mov_b64 exec, s[10:11]
	ds_write_b64 v45, v[192:193] offset:6656
	s_mov_b64 exec, s[0:1]
	v_pk_fma_f32 v[110:111], v[146:147], v[76:77], v[110:111] op_sel:[0,1,0] op_sel_hi:[1,1,1]
	s_nop 0
	v_pk_fma_f32 v[96:97], v[194:195], v[78:79], v[96:97] op_sel:[0,0,0] op_sel_hi:[1,0,1]
	v_pk_fma_f32 v[98:99], v[194:195], v[78:79], v[98:99] op_sel:[0,1,0] op_sel_hi:[1,1,1]
	v_pk_fma_f32 v[100:101], v[194:195], v[80:81], v[100:101] op_sel:[0,0,0] op_sel_hi:[1,0,1]
	v_pk_fma_f32 v[102:103], v[194:195], v[80:81], v[102:103] op_sel:[0,1,0] op_sel_hi:[1,1,1]
	v_pk_fma_f32 v[104:105], v[194:195], v[82:83], v[104:105] op_sel:[0,0,0] op_sel_hi:[1,0,1]
	v_pk_fma_f32 v[106:107], v[194:195], v[82:83], v[106:107] op_sel:[0,1,0] op_sel_hi:[1,1,1]
	v_pk_fma_f32 v[108:109], v[194:195], v[84:85], v[108:109] op_sel:[0,0,0] op_sel_hi:[1,0,1]
	v_pk_fma_f32 v[110:111], v[194:195], v[84:85], v[110:111] op_sel:[0,1,0] op_sel_hi:[1,1,1]
	v_pk_mul_f32 v[184:185], v[96:97], v[86:87] op_sel:[0,0] op_sel_hi:[1,0]
	v_pk_mul_f32 v[188:189], v[96:97], v[148:149] op_sel:[0,0] op_sel_hi:[1,0]
	v_pk_mul_f32 v[186:187], v[98:99], v[86:87] op_sel:[0,1] op_sel_hi:[1,1]
	v_pk_mul_f32 v[190:191], v[98:99], v[148:149] op_sel:[0,1] op_sel_hi:[1,1]
	v_pk_fma_f32 v[184:185], v[100:101], v[88:89], v[184:185] op_sel:[0,0,0] op_sel_hi:[1,0,1]
	v_pk_fma_f32 v[188:189], v[100:101], v[150:151], v[188:189] op_sel:[0,0,0] op_sel_hi:[1,0,1]
	v_pk_fma_f32 v[186:187], v[102:103], v[88:89], v[186:187] op_sel:[0,1,0] op_sel_hi:[1,1,1]
	v_pk_fma_f32 v[190:191], v[102:103], v[150:151], v[190:191] op_sel:[0,1,0] op_sel_hi:[1,1,1]
	v_pk_fma_f32 v[184:185], v[104:105], v[90:91], v[184:185] op_sel:[0,0,0] op_sel_hi:[1,0,1]
	v_pk_fma_f32 v[188:189], v[104:105], v[152:153], v[188:189] op_sel:[0,0,0] op_sel_hi:[1,0,1]
	v_pk_fma_f32 v[186:187], v[106:107], v[90:91], v[186:187] op_sel:[0,1,0] op_sel_hi:[1,1,1]
	v_pk_fma_f32 v[190:191], v[106:107], v[152:153], v[190:191] op_sel:[0,1,0] op_sel_hi:[1,1,1]
	v_pk_fma_f32 v[184:185], v[108:109], v[92:93], v[184:185] op_sel:[0,0,0] op_sel_hi:[1,0,1]
	v_pk_fma_f32 v[188:189], v[108:109], v[154:155], v[188:189] op_sel:[0,0,0] op_sel_hi:[1,0,1]
	v_pk_fma_f32 v[186:187], v[110:111], v[92:93], v[186:187] op_sel:[0,1,0] op_sel_hi:[1,1,1]
	v_pk_fma_f32 v[190:191], v[110:111], v[154:155], v[190:191] op_sel:[0,1,0] op_sel_hi:[1,1,1]
	v_pk_add_f32 v[192:193], v[184:185], v[186:187]
	v_pk_add_f32 v[194:195], v[188:189], v[190:191]
	ds_read_b128 v[70:73], v44 offset:44800
	ds_read_b128 v[74:77], v44 offset:44816
	ds_read_b128 v[78:81], v44 offset:45312
	ds_read_b128 v[82:85], v44 offset:45328
	ds_read_b128 v[86:89], v44 offset:45568
	ds_read_b128 v[90:93], v44 offset:45584
	ds_read_b64 v[146:147], v46 offset:44544
	ds_read_b128 v[148:151], v44 offset:46592
	ds_read_b128 v[152:155], v44 offset:46608
	s_waitcnt lgkmcnt(10)
; #define LAS __attribute__((address_space(3)))
; __device__ __forceinline__ float red8(float x) { x += dpp_mov<0xB1>(x); x += dpp_mov<0x4E>(x); x += dpp_mov<0x141>(x); return x; }
; __device__ __forceinline__ void scan_phase(const KP& P, LAS unsigned char* lds, const int tid, const int bx, const int G) {
;     ...
;             for (int s = 0; s < 32; ++s) {
;                 const LAS float* p = cb + s * 384;
;                 const f32x4 w0 = *(const LAS f32x4*)(p), w1 = *(const LAS f32x4*)(p + 4);
;                 const f32x4 k0 = *(const LAS f32x4*)(p + 64), k1 = *(const LAS f32x4*)(p + 68);
;                 const f32x4 a0 = *(const LAS f32x4*)(p + 128), a1 = *(const LAS f32x4*)(p + 132);
;                 const f32x4 b0 = *(const LAS f32x4*)(p + 192), b1 = *(const LAS f32x4*)(p + 196);
;                 const f32x4 r0 = *(const LAS f32x4*)(p + 256), r1 = *(const LAS f32x4*)(p + 260);
;                 const float vv = buf[(c & 1) * 12288 + s * 384 + 320 + v];
;                 f32x2 sa2 = S[0] * (f32x2){a0.x, a0.y};
;                 sa2 += S[1] * (f32x2){a0.z, a0.w}; sa2 += S[2] * (f32x2){a1.x, a1.y}; sa2 += S[3] * (f32x2){a1.z, a1.w};
;                 const float sa = red8(sa2.x + sa2.y);
;                 const f32x2 sav = {sa, sa}, vv2 = {vv, vv};
;                 S[0] = S[0] * (f32x2){w0.x, w0.y} + sav * (f32x2){b0.x, b0.y} + vv2 * (f32x2){k0.x, k0.y};
;                 S[1] = S[1] * (f32x2){w0.z, w0.w} + sav * (f32x2){b0.z, b0.w} + vv2 * (f32x2){k0.z, k0.w};
;                 S[2] = S[2] * (f32x2){w1.x, w1.y} + sav * (f32x2){b1.x, b1.y} + vv2 * (f32x2){k1.x, k1.y};
;                 S[3] = S[3] * (f32x2){w1.z, w1.w} + sav * (f32x2){b1.z, b1.w} + vv2 * (f32x2){k1.z, k1.w};
;                 f32x2 y2 = S[0] * (f32x2){r0.x, r0.y};
;                 y2 += S[1] * (f32x2){r0.z, r0.w}; y2 += S[2] * (f32x2){r1.x, r1.y}; y2 += S[3] * (f32x2){r1.z, r1.w};
;                 const float y = red8(y2.x + y2.y);
;                 if (kc == 0) ybuf[s * 64 + v] = y;
	v_add_f32_dpp v192, v192, v192 quad_perm:[1,0,3,2] row_mask:0xf bank_mask:0xf bound_ctrl:1
	v_add_f32_dpp v193, v193, v193 quad_perm:[1,0,3,2] row_mask:0xf bank_mask:0xf bound_ctrl:1
	v_add_f32_dpp v194, v194, v194 quad_perm:[1,0,3,2] row_mask:0xf bank_mask:0xf bound_ctrl:1
	v_add_f32_dpp v195, v195, v195 quad_perm:[1,0,3,2] row_mask:0xf bank_mask:0xf bound_ctrl:1
	v_pk_fma_f32 v[96:97], v[144:145], v[120:121], v[96:97] op_sel:[0,0,0] op_sel_hi:[1,0,1]
	v_pk_fma_f32 v[98:99], v[144:145], v[120:121], v[98:99] op_sel:[0,1,0] op_sel_hi:[1,1,1]
	v_pk_fma_f32 v[100:101], v[144:145], v[122:123], v[100:101] op_sel:[0,0,0] op_sel_hi:[1,0,1]
	v_add_f32_dpp v192, v192, v192 quad_perm:[2,3,0,1] row_mask:0xf bank_mask:0xf bound_ctrl:1
	v_add_f32_dpp v193, v193, v193 quad_perm:[2,3,0,1] row_mask:0xf bank_mask:0xf bound_ctrl:1
	v_add_f32_dpp v194, v194, v194 quad_perm:[2,3,0,1] row_mask:0xf bank_mask:0xf bound_ctrl:1
	v_add_f32_dpp v195, v195, v195 quad_perm:[2,3,0,1] row_mask:0xf bank_mask:0xf bound_ctrl:1
	v_pk_fma_f32 v[102:103], v[144:145], v[122:123], v[102:103] op_sel:[0,1,0] op_sel_hi:[1,1,1]
	v_pk_fma_f32 v[104:105], v[144:145], v[124:125], v[104:105] op_sel:[0,0,0] op_sel_hi:[1,0,1]
	v_pk_fma_f32 v[106:107], v[144:145], v[124:125], v[106:107] op_sel:[0,1,0] op_sel_hi:[1,1,1]
	v_add_f32_dpp v192, v192, v192 row_half_mirror row_mask:0xf bank_mask:0xf bound_ctrl:1
	v_add_f32_dpp v193, v193, v193 row_half_mirror row_mask:0xf bank_mask:0xf bound_ctrl:1
	v_add_f32_dpp v194, v194, v194 row_half_mirror row_mask:0xf bank_mask:0xf bound_ctrl:1
	v_add_f32_dpp v195, v195, v195 row_half_mirror row_mask:0xf bank_mask:0xf bound_ctrl:1
	v_pk_fma_f32 v[108:109], v[144:145], v[126:127], v[108:109] op_sel:[0,0,0] op_sel_hi:[1,0,1]
	s_mov_b64 exec, s[10:11]
	ds_write_b64 v45, v[192:193] offset:6912
	s_mov_b64 exec, s[0:1]
	v_pk_fma_f32 v[110:111], v[144:145], v[126:127], v[110:111] op_sel:[0,1,0] op_sel_hi:[1,1,1]
	s_nop 0
	v_pk_fma_f32 v[96:97], v[194:195], v[128:129], v[96:97] op_sel:[0,0,0] op_sel_hi:[1,0,1]
	v_pk_fma_f32 v[98:99], v[194:195], v[128:129], v[98:99] op_sel:[0,1,0] op_sel_hi:[1,1,1]
	v_pk_fma_f32 v[100:101], v[194:195], v[130:131], v[100:101] op_sel:[0,0,0] op_sel_hi:[1,0,1]
	v_pk_fma_f32 v[102:103], v[194:195], v[130:131], v[102:103] op_sel:[0,1,0] op_sel_hi:[1,1,1]
	v_pk_fma_f32 v[104:105], v[194:195], v[132:133], v[104:105] op_sel:[0,0,0] op_sel_hi:[1,0,1]
	v_pk_fma_f32 v[106:107], v[194:195], v[132:133], v[106:107] op_sel:[0,1,0] op_sel_hi:[1,1,1]
	v_pk_fma_f32 v[108:109], v[194:195], v[134:135], v[108:109] op_sel:[0,0,0] op_sel_hi:[1,0,1]
	v_pk_fma_f32 v[110:111], v[194:195], v[134:135], v[110:111] op_sel:[0,1,0] op_sel_hi:[1,1,1]
	v_pk_mul_f32 v[184:185], v[96:97], v[136:137] op_sel:[0,0] op_sel_hi:[1,0]
	v_pk_mul_f32 v[188:189], v[96:97], v[156:157] op_sel:[0,0] op_sel_hi:[1,0]
	v_pk_mul_f32 v[186:187], v[98:99], v[136:137] op_sel:[0,1] op_sel_hi:[1,1]
	v_pk_mul_f32 v[190:191], v[98:99], v[156:157] op_sel:[0,1] op_sel_hi:[1,1]
	v_pk_fma_f32 v[184:185], v[100:101], v[138:139], v[184:185] op_sel:[0,0,0] op_sel_hi:[1,0,1]
	v_pk_fma_f32 v[188:189], v[100:101], v[158:159], v[188:189] op_sel:[0,0,0] op_sel_hi:[1,0,1]
	v_pk_fma_f32 v[186:187], v[102:103], v[138:139], v[186:187] op_sel:[0,1,0] op_sel_hi:[1,1,1]
	v_pk_fma_f32 v[190:191], v[102:103], v[158:159], v[190:191] op_sel:[0,1,0] op_sel_hi:[1,1,1]
	v_pk_fma_f32 v[184:185], v[104:105], v[140:141], v[184:185] op_sel:[0,0,0] op_sel_hi:[1,0,1]
	v_pk_fma_f32 v[188:189], v[104:105], v[160:161], v[188:189] op_sel:[0,0,0] op_sel_hi:[1,0,1]
	v_pk_fma_f32 v[186:187], v[106:107], v[140:141], v[186:187] op_sel:[0,1,0] op_sel_hi:[1,1,1]
	v_pk_fma_f32 v[190:191], v[106:107], v[160:161], v[190:191] op_sel:[0,1,0] op_sel_hi:[1,1,1]
	v_pk_fma_f32 v[184:185], v[108:109], v[142:143], v[184:185] op_sel:[0,0,0] op_sel_hi:[1,0,1]
	v_pk_fma_f32 v[188:189], v[108:109], v[162:163], v[188:189] op_sel:[0,0,0] op_sel_hi:[1,0,1]
	v_pk_fma_f32 v[186:187], v[110:111], v[142:143], v[186:187] op_sel:[0,1,0] op_sel_hi:[1,1,1]
	v_pk_fma_f32 v[190:191], v[110:111], v[162:163], v[190:191] op_sel:[0,1,0] op_sel_hi:[1,1,1]
	v_pk_add_f32 v[192:193], v[184:185], v[186:187]
	v_pk_add_f32 v[194:195], v[188:189], v[190:191]
	ds_read_b128 v[120:123], v44 offset:46336
	ds_read_b128 v[124:127], v44 offset:46352
	ds_read_b128 v[128:131], v44 offset:46848
	ds_read_b128 v[132:135], v44 offset:46864
	ds_read_b128 v[136:139], v44 offset:47104
	ds_read_b128 v[140:143], v44 offset:47120
	ds_read_b64 v[144:145], v46 offset:46080
	ds_read_b128 v[156:159], v44 offset:48128
	ds_read_b128 v[160:163], v44 offset:48144
	s_waitcnt lgkmcnt(10)
; #define LAS __attribute__((address_space(3)))
; __device__ __forceinline__ float red8(float x) { x += dpp_mov<0xB1>(x); x += dpp_mov<0x4E>(x); x += dpp_mov<0x141>(x); return x; }
; __device__ __forceinline__ void scan_phase(const KP& P, LAS unsigned char* lds, const int tid, const int bx, const int G) {
;     ...
;             for (int s = 0; s < 32; ++s) {
;                 const LAS float* p = cb + s * 384;
;                 const f32x4 w0 = *(const LAS f32x4*)(p), w1 = *(const LAS f32x4*)(p + 4);
;                 const f32x4 k0 = *(const LAS f32x4*)(p + 64), k1 = *(const LAS f32x4*)(p + 68);
;                 const f32x4 a0 = *(const LAS f32x4*)(p + 128), a1 = *(const LAS f32x4*)(p + 132);
;                 const f32x4 b0 = *(const LAS f32x4*)(p + 192), b1 = *(const LAS f32x4*)(p + 196);
;                 const f32x4 r0 = *(const LAS f32x4*)(p + 256), r1 = *(const LAS f32x4*)(p + 260);
;                 const float vv = buf[(c & 1) * 12288 + s * 384 + 320 + v];
;                 f32x2 sa2 = S[0] * (f32x2){a0.x, a0.y};
;                 sa2 += S[1] * (f32x2){a0.z, a0.w}; sa2 += S[2] * (f32x2){a1.x, a1.y}; sa2 += S[3] * (f32x2){a1.z, a1.w};
;                 const float sa = red8(sa2.x + sa2.y);
;                 const f32x2 sav = {sa, sa}, vv2 = {vv, vv};
;                 S[0] = S[0] * (f32x2){w0.x, w0.y} + sav * (f32x2){b0.x, b0.y} + vv2 * (f32x2){k0.x, k0.y};
;                 S[1] = S[1] * (f32x2){w0.z, w0.w} + sav * (f32x2){b0.z, b0.w} + vv2 * (f32x2){k0.z, k0.w};
;                 S[2] = S[2] * (f32x2){w1.x, w1.y} + sav * (f32x2){b1.x, b1.y} + vv2 * (f32x2){k1.x, k1.y};
;                 S[3] = S[3] * (f32x2){w1.z, w1.w} + sav * (f32x2){b1.z, b1.w} + vv2 * (f32x2){k1.z, k1.w};
;                 f32x2 y2 = S[0] * (f32x2){r0.x, r0.y};
;                 y2 += S[1] * (f32x2){r0.z, r0.w}; y2 += S[2] * (f32x2){r1.x, r1.y}; y2 += S[3] * (f32x2){r1.z, r1.w};
;                 const float y = red8(y2.x + y2.y);
;                 if (kc == 0) ybuf[s * 64 + v] = y;
	v_add_f32_dpp v192, v192, v192 quad_perm:[1,0,3,2] row_mask:0xf bank_mask:0xf bound_ctrl:1
	v_add_f32_dpp v193, v193, v193 quad_perm:[1,0,3,2] row_mask:0xf bank_mask:0xf bound_ctrl:1
	v_add_f32_dpp v194, v194, v194 quad_perm:[1,0,3,2] row_mask:0xf bank_mask:0xf bound_ctrl:1
	v_add_f32_dpp v195, v195, v195 quad_perm:[1,0,3,2] row_mask:0xf bank_mask:0xf bound_ctrl:1
	v_pk_fma_f32 v[96:97], v[146:147], v[70:71], v[96:97] op_sel:[0,0,0] op_sel_hi:[1,0,1]
	v_pk_fma_f32 v[98:99], v[146:147], v[70:71], v[98:99] op_sel:[0,1,0] op_sel_hi:[1,1,1]
	v_pk_fma_f32 v[100:101], v[146:147], v[72:73], v[100:101] op_sel:[0,0,0] op_sel_hi:[1,0,1]
	v_add_f32_dpp v192, v192, v192 quad_perm:[2,3,0,1] row_mask:0xf bank_mask:0xf bound_ctrl:1
	v_add_f32_dpp v193, v193, v193 quad_perm:[2,3,0,1] row_mask:0xf bank_mask:0xf bound_ctrl:1
	v_add_f32_dpp v194, v194, v194 quad_perm:[2,3,0,1] row_mask:0xf bank_mask:0xf bound_ctrl:1
	v_add_f32_dpp v195, v195, v195 quad_perm:[2,3,0,1] row_mask:0xf bank_mask:0xf bound_ctrl:1
	v_pk_fma_f32 v[102:103], v[146:147], v[72:73], v[102:103] op_sel:[0,1,0] op_sel_hi:[1,1,1]
	v_pk_fma_f32 v[104:105], v[146:147], v[74:75], v[104:105] op_sel:[0,0,0] op_sel_hi:[1,0,1]
	v_pk_fma_f32 v[106:107], v[146:147], v[74:75], v[106:107] op_sel:[0,1,0] op_sel_hi:[1,1,1]
	v_add_f32_dpp v192, v192, v192 row_half_mirror row_mask:0xf bank_mask:0xf bound_ctrl:1
	v_add_f32_dpp v193, v193, v193 row_half_mirror row_mask:0xf bank_mask:0xf bound_ctrl:1
	v_add_f32_dpp v194, v194, v194 row_half_mirror row_mask:0xf bank_mask:0xf bound_ctrl:1
	v_add_f32_dpp v195, v195, v195 row_half_mirror row_mask:0xf bank_mask:0xf bound_ctrl:1
	v_pk_fma_f32 v[108:109], v[146:147], v[76:77], v[108:109] op_sel:[0,0,0] op_sel_hi:[1,0,1]
	s_mov_b64 exec, s[10:11]
	ds_write_b64 v45, v[192:193] offset:7168
	s_mov_b64 exec, s[0:1]
	v_pk_fma_f32 v[110:111], v[146:147], v[76:77], v[110:111] op_sel:[0,1,0] op_sel_hi:[1,1,1]
	s_nop 0
	v_pk_fma_f32 v[96:97], v[194:195], v[78:79], v[96:97] op_sel:[0,0,0] op_sel_hi:[1,0,1]
	v_pk_fma_f32 v[98:99], v[194:195], v[78:79], v[98:99] op_sel:[0,1,0] op_sel_hi:[1,1,1]
	v_pk_fma_f32 v[100:101], v[194:195], v[80:81], v[100:101] op_sel:[0,0,0] op_sel_hi:[1,0,1]
	v_pk_fma_f32 v[102:103], v[194:195], v[80:81], v[102:103] op_sel:[0,1,0] op_sel_hi:[1,1,1]
	v_pk_fma_f32 v[104:105], v[194:195], v[82:83], v[104:105] op_sel:[0,0,0] op_sel_hi:[1,0,1]
	v_pk_fma_f32 v[106:107], v[194:195], v[82:83], v[106:107] op_sel:[0,1,0] op_sel_hi:[1,1,1]
	v_pk_fma_f32 v[108:109], v[194:195], v[84:85], v[108:109] op_sel:[0,0,0] op_sel_hi:[1,0,1]
	v_pk_fma_f32 v[110:111], v[194:195], v[84:85], v[110:111] op_sel:[0,1,0] op_sel_hi:[1,1,1]
	v_pk_mul_f32 v[184:185], v[96:97], v[86:87] op_sel:[0,0] op_sel_hi:[1,0]
	v_pk_mul_f32 v[188:189], v[96:97], v[148:149] op_sel:[0,0] op_sel_hi:[1,0]
	v_pk_mul_f32 v[186:187], v[98:99], v[86:87] op_sel:[0,1] op_sel_hi:[1,1]
	v_pk_mul_f32 v[190:191], v[98:99], v[148:149] op_sel:[0,1] op_sel_hi:[1,1]
	v_pk_fma_f32 v[184:185], v[100:101], v[88:89], v[184:185] op_sel:[0,0,0] op_sel_hi:[1,0,1]
	v_pk_fma_f32 v[188:189], v[100:101], v[150:151], v[188:189] op_sel:[0,0,0] op_sel_hi:[1,0,1]
	v_pk_fma_f32 v[186:187], v[102:103], v[88:89], v[186:187] op_sel:[0,1,0] op_sel_hi:[1,1,1]
	v_pk_fma_f32 v[190:191], v[102:103], v[150:151], v[190:191] op_sel:[0,1,0] op_sel_hi:[1,1,1]
	v_pk_fma_f32 v[184:185], v[104:105], v[90:91], v[184:185] op_sel:[0,0,0] op_sel_hi:[1,0,1]
	v_pk_fma_f32 v[188:189], v[104:105], v[152:153], v[188:189] op_sel:[0,0,0] op_sel_hi:[1,0,1]
	v_pk_fma_f32 v[186:187], v[106:107], v[90:91], v[186:187] op_sel:[0,1,0] op_sel_hi:[1,1,1]
	v_pk_fma_f32 v[190:191], v[106:107], v[152:153], v[190:191] op_sel:[0,1,0] op_sel_hi:[1,1,1]
	v_pk_fma_f32 v[184:185], v[108:109], v[92:93], v[184:185] op_sel:[0,0,0] op_sel_hi:[1,0,1]
	v_pk_fma_f32 v[188:189], v[108:109], v[154:155], v[188:189] op_sel:[0,0,0] op_sel_hi:[1,0,1]
	v_pk_fma_f32 v[186:187], v[110:111], v[92:93], v[186:187] op_sel:[0,1,0] op_sel_hi:[1,1,1]
	v_pk_fma_f32 v[190:191], v[110:111], v[154:155], v[190:191] op_sel:[0,1,0] op_sel_hi:[1,1,1]
	v_pk_add_f32 v[192:193], v[184:185], v[186:187]
	v_pk_add_f32 v[194:195], v[188:189], v[190:191]
	ds_read_b128 v[70:73], v44 offset:47872
	ds_read_b128 v[74:77], v44 offset:47888
	ds_read_b128 v[78:81], v44 offset:48384
	ds_read_b128 v[82:85], v44 offset:48400
	ds_read_b128 v[86:89], v44 offset:48640
	ds_read_b128 v[90:93], v44 offset:48656
	ds_read_b64 v[146:147], v46 offset:47616
	s_waitcnt lgkmcnt(8)
; #define LAS __attribute__((address_space(3)))
; __device__ __forceinline__ float red8(float x) { x += dpp_mov<0xB1>(x); x += dpp_mov<0x4E>(x); x += dpp_mov<0x141>(x); return x; }
; __device__ __forceinline__ void scan_phase(const KP& P, LAS unsigned char* lds, const int tid, const int bx, const int G) {
;     ...
;             for (int s = 0; s < 32; ++s) {
;                 const LAS float* p = cb + s * 384;
;                 const f32x4 w0 = *(const LAS f32x4*)(p), w1 = *(const LAS f32x4*)(p + 4);
;                 const f32x4 k0 = *(const LAS f32x4*)(p + 64), k1 = *(const LAS f32x4*)(p + 68);
;                 const f32x4 a0 = *(const LAS f32x4*)(p + 128), a1 = *(const LAS f32x4*)(p + 132);
;                 const f32x4 b0 = *(const LAS f32x4*)(p + 192), b1 = *(const LAS f32x4*)(p + 196);
;                 const f32x4 r0 = *(const LAS f32x4*)(p + 256), r1 = *(const LAS f32x4*)(p + 260);
;                 const float vv = buf[(c & 1) * 12288 + s * 384 + 320 + v];
;                 f32x2 sa2 = S[0] * (f32x2){a0.x, a0.y};
;                 sa2 += S[1] * (f32x2){a0.z, a0.w}; sa2 += S[2] * (f32x2){a1.x, a1.y}; sa2 += S[3] * (f32x2){a1.z, a1.w};
;                 const float sa = red8(sa2.x + sa2.y);
;                 const f32x2 sav = {sa, sa}, vv2 = {vv, vv};
;                 S[0] = S[0] * (f32x2){w0.x, w0.y} + sav * (f32x2){b0.x, b0.y} + vv2 * (f32x2){k0.x, k0.y};
;                 S[1] = S[1] * (f32x2){w0.z, w0.w} + sav * (f32x2){b0.z, b0.w} + vv2 * (f32x2){k0.z, k0.w};
;                 S[2] = S[2] * (f32x2){w1.x, w1.y} + sav * (f32x2){b1.x, b1.y} + vv2 * (f32x2){k1.x, k1.y};
;                 S[3] = S[3] * (f32x2){w1.z, w1.w} + sav * (f32x2){b1.z, b1.w} + vv2 * (f32x2){k1.z, k1.w};
;                 f32x2 y2 = S[0] * (f32x2){r0.x, r0.y};
;                 y2 += S[1] * (f32x2){r0.z, r0.w}; y2 += S[2] * (f32x2){r1.x, r1.y}; y2 += S[3] * (f32x2){r1.z, r1.w};
;                 const float y = red8(y2.x + y2.y);
;                 if (kc == 0) ybuf[s * 64 + v] = y;
	v_add_f32_dpp v192, v192, v192 quad_perm:[1,0,3,2] row_mask:0xf bank_mask:0xf bound_ctrl:1
	v_add_f32_dpp v193, v193, v193 quad_perm:[1,0,3,2] row_mask:0xf bank_mask:0xf bound_ctrl:1
	v_add_f32_dpp v194, v194, v194 quad_perm:[1,0,3,2] row_mask:0xf bank_mask:0xf bound_ctrl:1
	v_add_f32_dpp v195, v195, v195 quad_perm:[1,0,3,2] row_mask:0xf bank_mask:0xf bound_ctrl:1
	v_pk_fma_f32 v[96:97], v[144:145], v[120:121], v[96:97] op_sel:[0,0,0] op_sel_hi:[1,0,1]
	v_pk_fma_f32 v[98:99], v[144:145], v[120:121], v[98:99] op_sel:[0,1,0] op_sel_hi:[1,1,1]
	v_pk_fma_f32 v[100:101], v[144:145], v[122:123], v[100:101] op_sel:[0,0,0] op_sel_hi:[1,0,1]
	v_add_f32_dpp v192, v192, v192 quad_perm:[2,3,0,1] row_mask:0xf bank_mask:0xf bound_ctrl:1
	v_add_f32_dpp v193, v193, v193 quad_perm:[2,3,0,1] row_mask:0xf bank_mask:0xf bound_ctrl:1
	v_add_f32_dpp v194, v194, v194 quad_perm:[2,3,0,1] row_mask:0xf bank_mask:0xf bound_ctrl:1
	v_add_f32_dpp v195, v195, v195 quad_perm:[2,3,0,1] row_mask:0xf bank_mask:0xf bound_ctrl:1
	v_pk_fma_f32 v[102:103], v[144:145], v[122:123], v[102:103] op_sel:[0,1,0] op_sel_hi:[1,1,1]
	v_pk_fma_f32 v[104:105], v[144:145], v[124:125], v[104:105] op_sel:[0,0,0] op_sel_hi:[1,0,1]
	v_pk_fma_f32 v[106:107], v[144:145], v[124:125], v[106:107] op_sel:[0,1,0] op_sel_hi:[1,1,1]
	v_add_f32_dpp v192, v192, v192 row_half_mirror row_mask:0xf bank_mask:0xf bound_ctrl:1
	v_add_f32_dpp v193, v193, v193 row_half_mirror row_mask:0xf bank_mask:0xf bound_ctrl:1
	v_add_f32_dpp v194, v194, v194 row_half_mirror row_mask:0xf bank_mask:0xf bound_ctrl:1
	v_add_f32_dpp v195, v195, v195 row_half_mirror row_mask:0xf bank_mask:0xf bound_ctrl:1
	v_pk_fma_f32 v[108:109], v[144:145], v[126:127], v[108:109] op_sel:[0,0,0] op_sel_hi:[1,0,1]
	s_mov_b64 exec, s[10:11]
	ds_write_b64 v45, v[192:193] offset:7424
	s_mov_b64 exec, s[0:1]
	v_pk_fma_f32 v[110:111], v[144:145], v[126:127], v[110:111] op_sel:[0,1,0] op_sel_hi:[1,1,1]
	s_nop 0
	v_pk_fma_f32 v[96:97], v[194:195], v[128:129], v[96:97] op_sel:[0,0,0] op_sel_hi:[1,0,1]
	v_pk_fma_f32 v[98:99], v[194:195], v[128:129], v[98:99] op_sel:[0,1,0] op_sel_hi:[1,1,1]
	v_pk_fma_f32 v[100:101], v[194:195], v[130:131], v[100:101] op_sel:[0,0,0] op_sel_hi:[1,0,1]
	v_pk_fma_f32 v[102:103], v[194:195], v[130:131], v[102:103] op_sel:[0,1,0] op_sel_hi:[1,1,1]
	v_pk_fma_f32 v[104:105], v[194:195], v[132:133], v[104:105] op_sel:[0,0,0] op_sel_hi:[1,0,1]
	v_pk_fma_f32 v[106:107], v[194:195], v[132:133], v[106:107] op_sel:[0,1,0] op_sel_hi:[1,1,1]
	v_pk_fma_f32 v[108:109], v[194:195], v[134:135], v[108:109] op_sel:[0,0,0] op_sel_hi:[1,0,1]
	v_pk_fma_f32 v[110:111], v[194:195], v[134:135], v[110:111] op_sel:[0,1,0] op_sel_hi:[1,1,1]
	v_pk_mul_f32 v[184:185], v[96:97], v[136:137] op_sel:[0,0] op_sel_hi:[1,0]
	v_pk_mul_f32 v[188:189], v[96:97], v[156:157] op_sel:[0,0] op_sel_hi:[1,0]
	v_pk_mul_f32 v[186:187], v[98:99], v[136:137] op_sel:[0,1] op_sel_hi:[1,1]
	v_pk_mul_f32 v[190:191], v[98:99], v[156:157] op_sel:[0,1] op_sel_hi:[1,1]
	v_pk_fma_f32 v[184:185], v[100:101], v[138:139], v[184:185] op_sel:[0,0,0] op_sel_hi:[1,0,1]
	v_pk_fma_f32 v[188:189], v[100:101], v[158:159], v[188:189] op_sel:[0,0,0] op_sel_hi:[1,0,1]
	v_pk_fma_f32 v[186:187], v[102:103], v[138:139], v[186:187] op_sel:[0,1,0] op_sel_hi:[1,1,1]
	v_pk_fma_f32 v[190:191], v[102:103], v[158:159], v[190:191] op_sel:[0,1,0] op_sel_hi:[1,1,1]
	v_pk_fma_f32 v[184:185], v[104:105], v[140:141], v[184:185] op_sel:[0,0,0] op_sel_hi:[1,0,1]
	v_pk_fma_f32 v[188:189], v[104:105], v[160:161], v[188:189] op_sel:[0,0,0] op_sel_hi:[1,0,1]
	v_pk_fma_f32 v[186:187], v[106:107], v[140:141], v[186:187] op_sel:[0,1,0] op_sel_hi:[1,1,1]
	v_pk_fma_f32 v[190:191], v[106:107], v[160:161], v[190:191] op_sel:[0,1,0] op_sel_hi:[1,1,1]
	v_pk_fma_f32 v[184:185], v[108:109], v[142:143], v[184:185] op_sel:[0,0,0] op_sel_hi:[1,0,1]
	v_pk_fma_f32 v[188:189], v[108:109], v[162:163], v[188:189] op_sel:[0,0,0] op_sel_hi:[1,0,1]
	v_pk_fma_f32 v[186:187], v[110:111], v[142:143], v[186:187] op_sel:[0,1,0] op_sel_hi:[1,1,1]
	v_pk_fma_f32 v[190:191], v[110:111], v[162:163], v[190:191] op_sel:[0,1,0] op_sel_hi:[1,1,1]
	v_pk_add_f32 v[192:193], v[184:185], v[186:187]
	v_pk_add_f32 v[194:195], v[188:189], v[190:191]
	s_waitcnt lgkmcnt(1)
; #define LAS __attribute__((address_space(3)))
; __device__ __forceinline__ float red8(float x) { x += dpp_mov<0xB1>(x); x += dpp_mov<0x4E>(x); x += dpp_mov<0x141>(x); return x; }
; __device__ __forceinline__ void scan_phase(const KP& P, LAS unsigned char* lds, const int tid, const int bx, const int G) {
;     ...
;             for (int s = 0; s < 32; ++s) {
;                 const LAS float* p = cb + s * 384;
;                 const f32x4 w0 = *(const LAS f32x4*)(p), w1 = *(const LAS f32x4*)(p + 4);
;                 const f32x4 k0 = *(const LAS f32x4*)(p + 64), k1 = *(const LAS f32x4*)(p + 68);
;                 const f32x4 a0 = *(const LAS f32x4*)(p + 128), a1 = *(const LAS f32x4*)(p + 132);
;                 const f32x4 b0 = *(const LAS f32x4*)(p + 192), b1 = *(const LAS f32x4*)(p + 196);
;                 const f32x4 r0 = *(const LAS f32x4*)(p + 256), r1 = *(const LAS f32x4*)(p + 260);
;                 const float vv = buf[(c & 1) * 12288 + s * 384 + 320 + v];
;                 f32x2 sa2 = S[0] * (f32x2){a0.x, a0.y};
;                 sa2 += S[1] * (f32x2){a0.z, a0.w}; sa2 += S[2] * (f32x2){a1.x, a1.y}; sa2 += S[3] * (f32x2){a1.z, a1.w};
;                 const float sa = red8(sa2.x + sa2.y);
;                 const f32x2 sav = {sa, sa}, vv2 = {vv, vv};
;                 S[0] = S[0] * (f32x2){w0.x, w0.y} + sav * (f32x2){b0.x, b0.y} + vv2 * (f32x2){k0.x, k0.y};
;                 S[1] = S[1] * (f32x2){w0.z, w0.w} + sav * (f32x2){b0.z, b0.w} + vv2 * (f32x2){k0.z, k0.w};
;                 S[2] = S[2] * (f32x2){w1.x, w1.y} + sav * (f32x2){b1.x, b1.y} + vv2 * (f32x2){k1.x, k1.y};
;                 S[3] = S[3] * (f32x2){w1.z, w1.w} + sav * (f32x2){b1.z, b1.w} + vv2 * (f32x2){k1.z, k1.w};
;                 f32x2 y2 = S[0] * (f32x2){r0.x, r0.y};
;                 y2 += S[1] * (f32x2){r0.z, r0.w}; y2 += S[2] * (f32x2){r1.x, r1.y}; y2 += S[3] * (f32x2){r1.z, r1.w};
;                 const float y = red8(y2.x + y2.y);
;                 if (kc == 0) ybuf[s * 64 + v] = y;
;             }
	s_nop 1
	v_add_f32_dpp v192, v192, v192 quad_perm:[1,0,3,2] row_mask:0xf bank_mask:0xf bound_ctrl:1
	v_add_f32_dpp v193, v193, v193 quad_perm:[1,0,3,2] row_mask:0xf bank_mask:0xf bound_ctrl:1
	v_add_f32_dpp v194, v194, v194 quad_perm:[1,0,3,2] row_mask:0xf bank_mask:0xf bound_ctrl:1
	v_add_f32_dpp v195, v195, v195 quad_perm:[1,0,3,2] row_mask:0xf bank_mask:0xf bound_ctrl:1
	v_pk_fma_f32 v[96:97], v[146:147], v[70:71], v[96:97] op_sel:[0,0,0] op_sel_hi:[1,0,1]
	v_pk_fma_f32 v[98:99], v[146:147], v[70:71], v[98:99] op_sel:[0,1,0] op_sel_hi:[1,1,1]
	v_pk_fma_f32 v[100:101], v[146:147], v[72:73], v[100:101] op_sel:[0,0,0] op_sel_hi:[1,0,1]
	v_add_f32_dpp v192, v192, v192 quad_perm:[2,3,0,1] row_mask:0xf bank_mask:0xf bound_ctrl:1
	v_add_f32_dpp v193, v193, v193 quad_perm:[2,3,0,1] row_mask:0xf bank_mask:0xf bound_ctrl:1
	v_add_f32_dpp v194, v194, v194 quad_perm:[2,3,0,1] row_mask:0xf bank_mask:0xf bound_ctrl:1
	v_add_f32_dpp v195, v195, v195 quad_perm:[2,3,0,1] row_mask:0xf bank_mask:0xf bound_ctrl:1
	v_pk_fma_f32 v[102:103], v[146:147], v[72:73], v[102:103] op_sel:[0,1,0] op_sel_hi:[1,1,1]
	v_pk_fma_f32 v[104:105], v[146:147], v[74:75], v[104:105] op_sel:[0,0,0] op_sel_hi:[1,0,1]
	v_pk_fma_f32 v[106:107], v[146:147], v[74:75], v[106:107] op_sel:[0,1,0] op_sel_hi:[1,1,1]
	v_add_f32_dpp v192, v192, v192 row_half_mirror row_mask:0xf bank_mask:0xf bound_ctrl:1
	v_add_f32_dpp v193, v193, v193 row_half_mirror row_mask:0xf bank_mask:0xf bound_ctrl:1
	v_add_f32_dpp v194, v194, v194 row_half_mirror row_mask:0xf bank_mask:0xf bound_ctrl:1
	v_add_f32_dpp v195, v195, v195 row_half_mirror row_mask:0xf bank_mask:0xf bound_ctrl:1
	v_pk_fma_f32 v[108:109], v[146:147], v[76:77], v[108:109] op_sel:[0,0,0] op_sel_hi:[1,0,1]
	s_mov_b64 exec, s[10:11]
	ds_write_b64 v45, v[192:193] offset:7680
	s_mov_b64 exec, s[0:1]
	v_pk_fma_f32 v[110:111], v[146:147], v[76:77], v[110:111] op_sel:[0,1,0] op_sel_hi:[1,1,1]
	s_nop 0
	v_pk_fma_f32 v[96:97], v[194:195], v[78:79], v[96:97] op_sel:[0,0,0] op_sel_hi:[1,0,1]
	v_pk_fma_f32 v[98:99], v[194:195], v[78:79], v[98:99] op_sel:[0,1,0] op_sel_hi:[1,1,1]
	v_pk_fma_f32 v[100:101], v[194:195], v[80:81], v[100:101] op_sel:[0,0,0] op_sel_hi:[1,0,1]
	v_pk_fma_f32 v[102:103], v[194:195], v[80:81], v[102:103] op_sel:[0,1,0] op_sel_hi:[1,1,1]
	v_pk_fma_f32 v[104:105], v[194:195], v[82:83], v[104:105] op_sel:[0,0,0] op_sel_hi:[1,0,1]
	v_pk_fma_f32 v[106:107], v[194:195], v[82:83], v[106:107] op_sel:[0,1,0] op_sel_hi:[1,1,1]
	v_pk_fma_f32 v[108:109], v[194:195], v[84:85], v[108:109] op_sel:[0,0,0] op_sel_hi:[1,0,1]
	v_pk_fma_f32 v[110:111], v[194:195], v[84:85], v[110:111] op_sel:[0,1,0] op_sel_hi:[1,1,1]
	v_pk_mul_f32 v[184:185], v[96:97], v[86:87] op_sel:[0,0] op_sel_hi:[1,0]
	s_nop 0
	v_pk_mul_f32 v[186:187], v[98:99], v[86:87] op_sel:[0,1] op_sel_hi:[1,1]
	s_nop 0
	v_pk_fma_f32 v[184:185], v[100:101], v[88:89], v[184:185] op_sel:[0,0,0] op_sel_hi:[1,0,1]
	s_nop 0
	v_pk_fma_f32 v[186:187], v[102:103], v[88:89], v[186:187] op_sel:[0,1,0] op_sel_hi:[1,1,1]
	s_nop 0
	v_pk_fma_f32 v[184:185], v[104:105], v[90:91], v[184:185] op_sel:[0,0,0] op_sel_hi:[1,0,1]
	s_nop 0
	v_pk_fma_f32 v[186:187], v[106:107], v[90:91], v[186:187] op_sel:[0,1,0] op_sel_hi:[1,1,1]
	s_nop 0
	v_pk_fma_f32 v[184:185], v[108:109], v[92:93], v[184:185] op_sel:[0,0,0] op_sel_hi:[1,0,1]
	s_nop 0
	v_pk_fma_f32 v[186:187], v[110:111], v[92:93], v[186:187] op_sel:[0,1,0] op_sel_hi:[1,1,1]
	s_nop 0
	v_pk_add_f32 v[192:193], v[184:185], v[186:187]
	v_pk_mul_f32 v[96:97], v[96:97], v[112:113] op_sel:[0,0] op_sel_hi:[1,0]
	v_pk_mul_f32 v[98:99], v[98:99], v[112:113] op_sel:[0,1] op_sel_hi:[1,1]
	v_pk_mul_f32 v[100:101], v[100:101], v[114:115] op_sel:[0,0] op_sel_hi:[1,0]
	v_pk_mul_f32 v[102:103], v[102:103], v[114:115] op_sel:[0,1] op_sel_hi:[1,1]
	v_pk_mul_f32 v[104:105], v[104:105], v[116:117] op_sel:[0,0] op_sel_hi:[1,0]
	v_pk_mul_f32 v[106:107], v[106:107], v[116:117] op_sel:[0,1] op_sel_hi:[1,1]
	v_pk_mul_f32 v[108:109], v[108:109], v[118:119] op_sel:[0,0] op_sel_hi:[1,0]
	v_pk_mul_f32 v[110:111], v[110:111], v[118:119] op_sel:[0,1] op_sel_hi:[1,1]
	v_add_f32_dpp v192, v192, v192 quad_perm:[1,0,3,2] row_mask:0xf bank_mask:0xf bound_ctrl:1
	v_add_f32_dpp v193, v193, v193 quad_perm:[1,0,3,2] row_mask:0xf bank_mask:0xf bound_ctrl:1
	s_nop 1
	v_add_f32_dpp v192, v192, v192 quad_perm:[2,3,0,1] row_mask:0xf bank_mask:0xf bound_ctrl:1
	v_add_f32_dpp v193, v193, v193 quad_perm:[2,3,0,1] row_mask:0xf bank_mask:0xf bound_ctrl:1
	s_nop 1
	v_add_f32_dpp v192, v192, v192 row_half_mirror row_mask:0xf bank_mask:0xf bound_ctrl:1
	v_add_f32_dpp v193, v193, v193 row_half_mirror row_mask:0xf bank_mask:0xf bound_ctrl:1
	s_nop 1
	s_mov_b64 exec, s[10:11]
	ds_write_b64 v45, v[192:193] offset:7936
	s_mov_b64 exec, s[0:1]
